# in-proj GEMM k-loops (both operand orders) also on the 8-phase schedule: every GEMM phase now uses it
# speedup vs baseline: 1.0331x; 1.0072x over previous
; template <bool SWAP>
; DI void gemm_mainloop(f32x16 (&acc)[4][2], const u16* __restrict__ A, int lda, int rlo, int rhi,
;                       const u16* __restrict__ B, int ldb, int K, char* lds, const u16* zero_line) {
;     ...
;   const int gch = (lc ^ ((lr >> 1) & 7)) * 8;
;   const u16* ap = A + (ptrdiff_t)lr * lda + gch;
;   const u16* bp = B + (ptrdiff_t)lr * ldb + gch;
;   const int nk = K >> 6;
;   typedef __attribute__((address_space(3))) unsigned lds_u32;
;   auto glds = [&](int kt, int st) {
;     char* as_ = lds + st * 65536 + tid * 16;
; #pragma unroll
;     for (int i = 0; i < 4; ++i) {
;       const int rr = lr + 64 * i;
;       const u16* srca = (rr >= rlo && rr < rhi) ? (ap + (ptrdiff_t)(64 * i) * lda + kt * 64) : (zero_line + lc * 8);
;       __builtin_amdgcn_global_load_lds((const unsigned*)srca, (lds_u32*)(as_ + i * 8192), 16, 0, 0);
;       __builtin_amdgcn_global_load_lds((const unsigned*)(bp + (ptrdiff_t)(64 * i) * ldb + kt * 64), (lds_u32*)(as_ + 32768 + i * 8192), 16, 0, 0);
;     }
;   };
;   const int sw = (r >> 1) & 7;
;   const int arow_off = (wm * 128 + r) * 128;
;   const int brow_off = 32768 + (wn * 64 + r) * 128;
;   __syncthreads();
;   glds(0, 0);
; template <int EPI>
; DI void phase_gemm(const Params& p, const GemmArgs& ga, char* lds) {
;     ...
;   for (int it = 0; it * (int)gridDim.x < total; ++it) {
;     const int lt = logical_index(it);
;     if (lt >= total) continue;
;     int mt, nt;
;     tile_mn(lt, Mt, ga.Nt, mt, nt);
;     int bb, tokbase, S, pos0, rlo = 0, rhi = 256;
;     if (EPI == EPI_UP) {
;       bb = 0; tokbase = 0; S = NTOK;
;       pos0 = 254 * mt - 1;
;       rlo = (mt == 0) ? 1 : 0;
;       rhi = NTOK - pos0; if (rhi > 256) rhi = 256;
;     } else {
;       seq_of_token(mt * 256, bb, tokbase, S);
;       pos0 = mt * 256 - tokbase;
;     }
;     const u16* A = ga.A + (ptrdiff_t)(tokbase + pos0) * ga.lda;
;     const u16* B = ga.Bt + (size_t)(nt * 256) * ga.K;
;     f32x16 acc[4][2];
;     bool swap;
;     if (EPI == EPI_M) swap = true;
;     else if (EPI == EPI_UP) swap = true;
;     else if (EPI == EPI_QKV1) swap = (nt < 8);
;     else swap = !(nt == 4 || nt == 5);
;     if (swap) gemm_mainloop<true>(acc, A, ga.lda, rlo, rhi, B, ga.K, ga.K, lds, (const u16*)(p.ws + OFF_ZERO));
;     else gemm_mainloop<false>(acc, A, ga.lda, rlo, rhi, B, ga.K, ga.K, lds, (const u16*)(p.ws + OFF_ZERO));
.LBB0_196:
	s_add_i32 s6, s6, s27
	s_cmpk_gt_i32 s6, 0x8ff
	s_cbranch_scc1 .LBB0_195
	s_mul_hi_i32 s7, s6, 0x2aaaaaab
	s_lshr_b32 s8, s7, 31
	s_ashr_i32 s7, s7, 4
	s_add_i32 s8, s7, s8
	s_mul_i32 s7, s8, 0xffffffa0
	s_add_i32 s9, s7, s6
	s_ashr_i32 s7, s9, 31
	s_lshr_b32 s7, s7, 29
	s_lshl_b32 s6, s8, 3
	s_add_i32 s10, s9, s7
	s_add_i32 s6, s9, s6
	s_and_b32 s31, s10, -8
	s_sub_i32 s30, s6, s31
	s_lshl_b32 s12, s30, 8
	s_ashr_i32 s13, s12, 31
	s_lshl_b64 s[6:7], s[12:13], 11
	s_add_u32 s20, s90, s6
	s_addc_u32 s21, s91, s7
	s_lshl_b32 s6, s10, 5
	s_and_b32 s14, s6, 0xffffff00
	s_ashr_i32 s15, s14, 31
	s_lshl_b64 s[18:19], s[14:15], 11
	v_readlane_b32 s6, v253, 43
	v_readlane_b32 s7, v253, 44
	s_add_u32 s22, s6, s18
	s_addc_u32 s23, s7, s19
	s_cmp_gt_i32 s9, 63
	s_cselect_b64 s[16:17], -1, 0
	s_mov_b64 s[6:7], -1
	s_and_b64 vcc, exec, s[16:17]
	s_mul_i32 s13, s8, 0x58
	s_cbranch_vccz .LBB0_203
	v_mov_b32_e32 v12, v204
	s_mov_b64 s[10:11], 0x20000
	v_ashrrev_i32_e32 v2, 3, v12
	v_lshrrev_b32_e32 v14, 1, v2
	v_xor_b32_e32 v0, v14, v12
	v_ashrrev_i32_e32 v3, 31, v2
	v_lshlrev_b64 v[4:5], 11, v[2:3]
	v_lshlrev_b32_e32 v0, 4, v0
	v_and_b32_e32 v10, 31, v12
	v_lshl_add_u64 v[6:7], s[20:21], 0, v[4:5]
	v_and_b32_e32 v0, 0x70, v0
	v_lshl_add_u64 v[8:9], s[22:23], 0, v[4:5]
	v_lshrrev_b32_e32 v15, 1, v12
	v_lshl_add_u64 v[6:7], v[6:7], 0, v[0:1]
	v_lshl_add_u64 v[8:9], v[8:9], 0, v[0:1]
	v_and_or_b32 v0, v15, s51, v10
	v_lshlrev_b32_e32 v169, 7, v0
	v_lshlrev_b32_e32 v0, 7, v12
	v_lshlrev_b32_e32 v171, 4, v12
	v_and_b32_e32 v170, 0x6f80, v0
	v_and_b32_e32 v0, 0x70, v171
	v_add_u32_e32 v172, 0x8000, v171
	v_lshl_add_u64 v[156:157], s[80:81], 0, v[0:1]
	v_cmp_gt_u32_e32 vcc, s50, v2
	v_readfirstlane_b32 s6, v171
	s_mov_b32 m0, s6
	v_cndmask_b32_e32 v11, v157, v7, vcc
	v_cndmask_b32_e32 v10, v156, v6, vcc
	v_readfirstlane_b32 s6, v172
	v_add_u32_e32 v0, 64, v2
	v_add_u32_e32 v173, 0x2000, v171
	s_barrier
	s_mov_b32 m0, s6
	v_lshl_add_u64 v[10:11], v[6:7], 0, s[10:11]
	v_cmp_gt_u32_e64 s[6:7], s50, v0
	v_readfirstlane_b32 s8, v173
	v_add_u32_e32 v174, 0xa000, v171
	v_cndmask_b32_e64 v11, v157, v11, s[6:7]
	v_cndmask_b32_e64 v10, v156, v10, s[6:7]
	s_mov_b32 m0, s8
	v_readfirstlane_b32 s8, v174
	v_lshl_add_u64 v[10:11], v[8:9], 0, s[10:11]
	s_mov_b32 m0, s8
	v_add_u32_e32 v0, 0x80, v2
	s_mov_b64 s[24:25], 0x40000
	v_add_u32_e32 v175, 0x4000, v171
	v_lshl_add_u64 v[10:11], v[6:7], 0, s[24:25]
	v_cmp_gt_u32_e64 s[8:9], s50, v0
	v_readfirstlane_b32 s10, v175
	v_add_u32_e32 v176, 0xc000, v171
	v_cndmask_b32_e64 v11, v157, v11, s[8:9]
	v_cndmask_b32_e64 v10, v156, v10, s[8:9]
	s_mov_b32 m0, s10
	v_readfirstlane_b32 s10, v176
	v_add_u32_e32 v0, 0xc0, v2
	s_mov_b64 s[34:35], 0x60000
	v_add_u32_e32 v177, 0x6000, v171
	v_lshl_add_u64 v[10:11], v[8:9], 0, s[24:25]
	s_mov_b32 m0, s10
	v_lshl_add_u64 v[2:3], v[6:7], 0, s[34:35]
	v_cmp_gt_u32_e64 s[10:11], s50, v0
	v_readfirstlane_b32 s24, v177
	v_add_u32_e32 v178, 0xe000, v171
	v_cndmask_b32_e64 v3, v157, v3, s[10:11]
	v_cndmask_b32_e64 v2, v156, v2, s[10:11]
	s_mov_b32 m0, s24
	v_readfirstlane_b32 s24, v178
	v_lshl_add_u64 v[2:3], v[8:9], 0, s[34:35]
	s_mov_b32 m0, s24
	v_bfe_u32 v13, v12, 5, 1
	v_bfe_u32 v16, v12, 1, 3
	v_bitop3_b32 v0, v15, v13, 7 bitop3:0x6c
	s_sub_i32 s24, s28, s31
	v_lshlrev_b32_e32 v179, 4, v0
	v_bitop3_b32 v0, v13, v16, 2 bitop3:0x36
	s_sub_i32 s24, s24, s13
	v_lshlrev_b32_e32 v180, 4, v0
	v_bitop3_b32 v0, v13, v16, 4 bitop3:0x36
	s_lshl_b32 s24, s24, 8
	v_lshlrev_b32_e32 v181, 4, v0
	v_bitop3_b32 v0, v13, v16, 6 bitop3:0x36
	s_ashr_i32 s25, s24, 31
	v_lshlrev_b32_e32 v182, 4, v0
	s_lshl_b64 s[24:25], s[24:25], 11
	v_bitop3_b32 v0, v14, 7, v12 bitop3:0x48
	v_lshl_add_u64 v[2:3], v[4:5], 0, s[24:25]
	v_lshlrev_b32_e32 v0, 4, v0
	v_or_b32_e32 v2, v2, v0
	v_lshl_add_u64 v[158:159], s[70:71], 0, v[2:3]
	v_lshl_add_u64 v[2:3], v[4:5], 0, s[18:19]
	s_waitcnt vmcnt(0)
	v_lshl_add_u64 v[2:3], v[2:3], 0, v[0:1]
	v_lshl_add_u64 v[160:161], s[70:71], 0, v[2:3]
	v_mov_b32_e32 v130, 0
	v_mov_b32_e32 v2, 0
	s_mov_b32 s15, 1
	v_add_u32_e32 v183, 0x10000, v171
	v_add_u32_e32 v185, 0x18000, v171
	v_add_u32_e32 v186, 0x12000, v171
	v_add_u32_e32 v187, 0x1a000, v171
	v_add_u32_e32 v188, 0x14000, v171
	v_add_u32_e32 v189, 0x1c000, v171
	v_add_u32_e32 v190, 0x16000, v171
	v_add_u32_e32 v191, 0x1e000, v171
	v_add_u32_e32 v192, 0x10000, v169
	v_or_b32_e32 v193, 0x10000, v170
	s_mov_b64 s[24:25], 0
	v_mov_b32_e32 v3, v2
	v_mov_b32_e32 v4, v2
	v_mov_b32_e32 v5, v2
	v_mov_b32_e32 v6, v2
	v_mov_b32_e32 v7, v2
	v_mov_b32_e32 v8, v2
	v_mov_b32_e32 v9, v2
	v_mov_b32_e32 v10, v2
	v_mov_b32_e32 v11, v2
	v_mov_b32_e32 v12, v2
	v_mov_b32_e32 v13, v2
	v_mov_b32_e32 v14, v2
	v_mov_b32_e32 v15, v2
	v_mov_b32_e32 v16, v2
	v_mov_b32_e32 v17, v2
	v_mov_b32_e32 v18, v2
	v_mov_b32_e32 v19, v2
	v_mov_b32_e32 v20, v2
	v_mov_b32_e32 v21, v2
	v_mov_b32_e32 v22, v2
	v_mov_b32_e32 v23, v2
	v_mov_b32_e32 v24, v2
	v_mov_b32_e32 v25, v2
	v_mov_b32_e32 v26, v2
	v_mov_b32_e32 v27, v2
	v_mov_b32_e32 v28, v2
	v_mov_b32_e32 v29, v2
	v_mov_b32_e32 v30, v2
	v_mov_b32_e32 v31, v2
	v_mov_b32_e32 v32, v2
	v_mov_b32_e32 v33, v2
	v_mov_b32_e32 v34, v2
	v_mov_b32_e32 v35, v2
	v_mov_b32_e32 v36, v2
	v_mov_b32_e32 v37, v2
	v_mov_b32_e32 v38, v2
	v_mov_b32_e32 v39, v2
	v_mov_b32_e32 v40, v2
	v_mov_b32_e32 v41, v2
	v_mov_b32_e32 v42, v2
	v_mov_b32_e32 v43, v2
	v_mov_b32_e32 v44, v2
	v_mov_b32_e32 v45, v2
	v_mov_b32_e32 v46, v2
	v_mov_b32_e32 v47, v2
	v_mov_b32_e32 v48, v2
	v_mov_b32_e32 v49, v2
	v_mov_b32_e32 v50, v2
	v_mov_b32_e32 v51, v2
	v_mov_b32_e32 v52, v2
	v_mov_b32_e32 v53, v2
	v_mov_b32_e32 v54, v2
	v_mov_b32_e32 v55, v2
	v_mov_b32_e32 v56, v2
; DI int opaque_tid() { int t = threadIdx.x; asm volatile("" : "+v"(t)); return t; }
; template <bool SWAP>
; DI void gemm_mainloop(f32x16 (&acc)[4][2], const u16* __restrict__ A, int lda, int rlo, int rhi,
;                       const u16* __restrict__ B, int ldb, int K, char* lds, const u16* zero_line) {
;   const int tid = opaque_tid(), lane = tid & 63, w = tid >> 6;
;   const int wm = w >> 2, wn = w & 3;
;   const int h = lane >> 5, r = lane & 31;
;   const int lr = tid >> 3, lc = tid & 7;
; #pragma unroll
;   for (int mi = 0; mi < 4; ++mi)
; #pragma unroll
;     for (int ni = 0; ni < 2; ++ni)
; #pragma unroll
;       for (int i = 0; i < 16; ++i) acc[mi][ni][i] = 0.f;
;   const int gch = (lc ^ ((lr >> 1) & 7)) * 8;
;   const u16* ap = A + (ptrdiff_t)lr * lda + gch;
;   const u16* bp = B + (ptrdiff_t)lr * ldb + gch;
;   const int nk = K >> 6;
;   typedef __attribute__((address_space(3))) unsigned lds_u32;
;   auto glds = [&](int kt, int st) {
;     char* as_ = lds + st * 65536 + tid * 16;
; #pragma unroll
;     for (int i = 0; i < 4; ++i) {
;       const int rr = lr + 64 * i;
;       const u16* srca = (rr >= rlo && rr < rhi) ? (ap + (ptrdiff_t)(64 * i) * lda + kt * 64) : (zero_line + lc * 8);
;       __builtin_amdgcn_global_load_lds((const unsigned*)srca, (lds_u32*)(as_ + i * 8192), 16, 0, 0);
;       __builtin_amdgcn_global_load_lds((const unsigned*)(bp + (ptrdiff_t)(64 * i) * ldb + kt * 64), (lds_u32*)(as_ + 32768 + i * 8192), 16, 0, 0);
;     }
;   };
;   const int sw = (r >> 1) & 7;
;   const int arow_off = (wm * 128 + r) * 128;
;   const int brow_off = 32768 + (wn * 64 + r) * 128;
;   __syncthreads();
;   glds(0, 0);
;   asm volatile("s_waitcnt vmcnt(0)" ::: "memory");
;   __syncthreads();
	v_mov_b32_e32 v57, v2
	v_mov_b32_e32 v58, v2
	v_mov_b32_e32 v59, v2
	v_mov_b32_e32 v60, v2
	v_mov_b32_e32 v61, v2
	v_mov_b32_e32 v62, v2
	v_mov_b32_e32 v63, v2
	v_mov_b32_e32 v64, v2
	v_mov_b32_e32 v65, v2
	v_mov_b32_e32 v66, v2
	v_mov_b32_e32 v67, v2
	v_mov_b32_e32 v68, v2
	v_mov_b32_e32 v69, v2
	v_mov_b32_e32 v70, v2
	v_mov_b32_e32 v71, v2
	v_mov_b32_e32 v72, v2
	v_mov_b32_e32 v73, v2
	v_mov_b32_e32 v74, v2
	v_mov_b32_e32 v75, v2
	v_mov_b32_e32 v76, v2
	v_mov_b32_e32 v77, v2
	v_mov_b32_e32 v78, v2
	v_mov_b32_e32 v79, v2
	v_mov_b32_e32 v80, v2
	v_mov_b32_e32 v81, v2
	v_mov_b32_e32 v82, v2
	v_mov_b32_e32 v83, v2
	v_mov_b32_e32 v84, v2
	v_mov_b32_e32 v85, v2
	v_mov_b32_e32 v86, v2
	v_mov_b32_e32 v87, v2
	v_mov_b32_e32 v88, v2
	v_mov_b32_e32 v89, v2
	v_mov_b32_e32 v90, v2
	v_mov_b32_e32 v91, v2
	v_mov_b32_e32 v92, v2
	v_mov_b32_e32 v93, v2
	v_mov_b32_e32 v94, v2
	v_mov_b32_e32 v95, v2
	v_mov_b32_e32 v96, v2
	v_mov_b32_e32 v97, v2
	v_mov_b32_e32 v98, v2
	v_mov_b32_e32 v99, v2
	v_mov_b32_e32 v100, v2
	v_mov_b32_e32 v101, v2
	v_mov_b32_e32 v102, v2
	v_mov_b32_e32 v103, v2
	v_mov_b32_e32 v104, v2
	v_mov_b32_e32 v105, v2
	v_mov_b32_e32 v106, v2
	v_mov_b32_e32 v107, v2
	v_mov_b32_e32 v108, v2
	v_mov_b32_e32 v109, v2
	v_mov_b32_e32 v110, v2
	v_mov_b32_e32 v111, v2
	v_mov_b32_e32 v112, v2
	v_mov_b32_e32 v113, v2
	v_mov_b32_e32 v114, v2
	v_mov_b32_e32 v115, v2
	v_mov_b32_e32 v116, v2
	v_mov_b32_e32 v117, v2
	v_mov_b32_e32 v118, v2
	v_mov_b32_e32 v119, v2
	v_mov_b32_e32 v120, v2
	v_mov_b32_e32 v121, v2
	v_mov_b32_e32 v122, v2
	v_mov_b32_e32 v123, v2
	v_mov_b32_e32 v124, v2
	v_mov_b32_e32 v125, v2
	v_mov_b32_e32 v126, v2
	v_mov_b32_e32 v127, v2
	v_mov_b32_e32 v128, v2
	v_mov_b32_e32 v129, v2
	v_mov_b32_e32 v131, v130
	v_mov_b32_e32 v132, v130
	v_mov_b32_e32 v133, v130
	v_mov_b32_e32 v134, v130
	v_mov_b32_e32 v135, v130
	v_mov_b32_e32 v136, v130
	v_mov_b32_e32 v137, v130
	v_mov_b32_e32 v138, v130
	v_mov_b32_e32 v139, v130
	v_mov_b32_e32 v140, v130
	v_mov_b32_e32 v141, v130
	v_mov_b32_e32 v146, v130
	v_mov_b32_e32 v147, v130
	v_mov_b32_e32 v148, v130
	v_mov_b32_e32 v149, v130
	v_mov_b32_e32 v142, v130
	v_mov_b32_e32 v143, v130
	v_mov_b32_e32 v144, v130
	v_mov_b32_e32 v145, v130
	v_mov_b32_e32 v150, v130
	v_mov_b32_e32 v151, v130
	v_mov_b32_e32 v152, v130
	v_mov_b32_e32 v153, v130
	s_waitcnt vmcnt(0) lgkmcnt(0)
	s_barrier
	s_ashr_i32 s7, s12, 31
	s_mov_b32 s6, s12
	s_lshl_b64 s[6:7], s[6:7], 11
	s_add_u32 s6, s90, s6
	s_addc_u32 s7, s91, s7
	s_ashr_i32 s9, s14, 31
	s_mov_b32 s8, s14
	s_lshl_b64 s[8:9], s[8:9], 11
	v_readlane_b32 s10, v253, 43
	v_readlane_b32 s11, v253, 44
	s_add_u32 s8, s10, s8
	s_addc_u32 s9, s11, s9
	v_and_b32_e32 v130, 63, v204
	v_lshrrev_b32_e32 v131, 6, v204
	v_lshrrev_b32_e32 v132, 3, v204
	v_lshrrev_b32_e32 v0, 4, v130
	v_lshl_add_u32 v0, v131, 2, v0
	v_xor_b32_e32 v0, v0, v130
	v_and_b32_e32 v0, 7, v0
	v_lshlrev_b32_e32 v133, 4, v0
	v_lshl_add_u32 v232, v132, 11, v133
	v_add_u32_e32 v233, 0x20000, v232
	v_add_u32_e32 v234, 0x40000, v232
	v_add_u32_e32 v235, 0x60000, v232
	v_and_b32_e32 v0, 31, v132
	v_lshrrev_b32_e32 v130, 5, v132
	v_lshl_add_u32 v0, v130, 6, v0
	v_lshl_add_u32 v236, v0, 11, v133
	v_add_u32_e32 v237, 0x10000, v236
	v_add_u32_e32 v238, 0x40000, v236
	v_add_u32_e32 v239, 0x50000, v236
	v_and_b32_e32 v132, 31, v204
	v_lshrrev_b32_e32 v0, 2, v131
	v_lshl_add_u32 v0, v0, 6, v132
	v_lshlrev_b32_e32 v244, 7, v0
	v_and_b32_e32 v0, 3, v131
	v_lshl_add_u32 v0, v0, 5, v132
	v_lshlrev_b32_e32 v245, 7, v0
	v_bfe_u32 v0, v204, 5, 1
	v_bfe_u32 v130, v132, 1, 3
	v_or_b32_e32 v133, 0, v0
	v_xor_b32_e32 v133, v133, v130
	v_lshlrev_b32_e32 v240, 4, v133
	v_or_b32_e32 v133, 2, v0
	v_xor_b32_e32 v133, v133, v130
	v_lshlrev_b32_e32 v241, 4, v133
	v_or_b32_e32 v133, 4, v0
	v_xor_b32_e32 v133, v133, v130
	v_lshlrev_b32_e32 v242, 4, v133
	v_or_b32_e32 v133, 6, v0
	v_xor_b32_e32 v133, v133, v130
	v_lshlrev_b32_e32 v243, 4, v133
	v_lshlrev_b32_e32 v131, 10, v131
	s_nop 0
	v_readfirstlane_b32 s100, v131
	v_mov_b32_e32 v146, 0
	v_mov_b32_e32 v147, 0
	v_mov_b32_e32 v148, 0
	v_mov_b32_e32 v149, 0
	v_lshlrev_b32_e32 v130, 4, v204
	v_add_u32_e32 v132, 0x10000, v130
	s_mov_b64 exec, -1
	s_mov_b32 s11, 0
	s_mov_b32 s10, 0x10000
	s_waitcnt lgkmcnt(0)
	s_add_u32 m0, s100, 0x8000
	s_nop 0
	global_load_lds_dwordx4 v236, s[8:9]
	v_add_u32_e32 v236, 0x80, v236
	s_add_u32 m0, s100, 0xa000
	s_nop 0
	global_load_lds_dwordx4 v238, s[8:9]
	v_add_u32_e32 v238, 0x80, v238
	s_add_u32 m0, s100, 0x0
	s_nop 0
	global_load_lds_dwordx4 v232, s[6:7]
	v_add_u32_e32 v232, 0x80, v232
	s_add_u32 m0, s100, 0x2000
	s_nop 0
	global_load_lds_dwordx4 v234, s[6:7]
	v_add_u32_e32 v234, 0x80, v234
	s_add_u32 m0, s100, 0xc000
	s_nop 0
	global_load_lds_dwordx4 v237, s[8:9]
	v_add_u32_e32 v237, 0x80, v237
	s_add_u32 m0, s100, 0xe000
	s_nop 0
	global_load_lds_dwordx4 v239, s[8:9]
	v_add_u32_e32 v239, 0x80, v239
	s_add_u32 m0, s100, 0x4000
	s_nop 0
	global_load_lds_dwordx4 v233, s[6:7]
	v_add_u32_e32 v233, 0x80, v233
	s_add_u32 m0, s100, 0x6000
	s_nop 0
	global_load_lds_dwordx4 v235, s[6:7]
	v_add_u32_e32 v235, 0x80, v235
	s_cmp_eq_u32 s101, 1
	s_cbranch_scc0 .Lg8_qa_p0
	s_barrier
.Lg8_qa_p0:
	s_waitcnt vmcnt(4)
	s_barrier
	s_add_u32 m0, s100, 0x18000
	s_nop 0
	global_load_lds_dwordx4 v236, s[8:9]
	v_add_u32_e32 v236, 0x80, v236
	s_add_u32 m0, s100, 0x1a000
	s_nop 0
	global_load_lds_dwordx4 v238, s[8:9]
	v_add_u32_e32 v238, 0x80, v238
	s_add_u32 m0, s100, 0x10000
	s_nop 0
	global_load_lds_dwordx4 v232, s[6:7]
	v_add_u32_e32 v232, 0x80, v232
	s_add_u32 m0, s100, 0x12000
	s_nop 0
	global_load_lds_dwordx4 v234, s[6:7]
	v_add_u32_e32 v234, 0x80, v234
	s_add_u32 m0, s100, 0x1c000
	s_nop 0
	global_load_lds_dwordx4 v237, s[8:9]
	v_add_u32_e32 v237, 0x80, v237
	s_add_u32 m0, s100, 0x1e000
	s_nop 0
	global_load_lds_dwordx4 v239, s[8:9]
	v_add_u32_e32 v239, 0x80, v239
	s_waitcnt vmcnt(6)
	s_barrier
; #define MFMA(a, b, c) __builtin_amdgcn_mfma_f32_32x32x16_bf16((a), (b), (c), 0, 0, 0)
; template <bool SWAP>
; DI void gemm_mainloop(f32x16 (&acc)[4][2], const u16* __restrict__ A, int lda, int rlo, int rhi,
;                       const u16* __restrict__ B, int ldb, int K, char* lds, const u16* zero_line) {
;     ...
;   auto ldfrag = [&](const char* st, int ks, int buf) {
;     const int co = ((2 * ks + h) ^ sw) << 4;
; #pragma unroll
;     for (int mi = 0; mi < 4; ++mi) fa[buf][mi] = *(const bf16x8*)(st + arow_off + mi * 4096 + co);
; #pragma unroll
;     for (int ni = 0; ni < 2; ++ni) fb[buf][ni] = *(const bf16x8*)(st + brow_off + ni * 4096 + co);
;   };
;   auto mma = [&](int buf) {
; #pragma unroll
;     for (int mi = 0; mi < 4; ++mi)
; #pragma unroll
;       for (int ni = 0; ni < 2; ++ni)
;         acc[mi][ni] = SWAP ? MFMA(fb[buf][ni], fa[buf][mi], acc[mi][ni]) : MFMA(fa[buf][mi], fb[buf][ni], acc[mi][ni]);
;   };
;   auto pat_rd = [&]() {
; #pragma unroll
;     for (int g = 0; g < 6; ++g) {
;       __builtin_amdgcn_sched_group_barrier(0x100, 1, 0);
;       __builtin_amdgcn_sched_group_barrier(0x008, 1, 0);
;     }
;     __builtin_amdgcn_sched_group_barrier(0x008, 2, 0);
;   };
; #pragma unroll 2
;   for (int kt = 0; kt < nk; ++kt) {
;     const char* st = lds + (kt & 1) * 65536;
;     ldfrag(st, 0, 0);
;     mma(1);
;     pat_rd();
;     if (kt + 1 < nk) glds(kt + 1, (kt + 1) & 1);
;     ldfrag(st, 1, 1);
;     mma(0);
;     pat_rd();
;     ldfrag(st, 2, 0);
;     mma(1);
;     pat_rd();
;     ldfrag(st, 3, 1);
;     mma(0);
;     pat_rd();
;     asm volatile("s_waitcnt vmcnt(0)" ::: "memory");
;     __syncthreads();
;   }
.Lg8_qa:
	v_add3_u32 v246, v245, v240, 0
	v_add3_u32 v247, v245, v241, 0
	v_add3_u32 v248, v245, v242, 0
	v_add3_u32 v249, v245, v243, 0
	ds_read_b128 v[170:173], v246 offset:32768
	ds_read_b128 v[174:177], v247 offset:32768
	ds_read_b128 v[178:181], v248 offset:32768
	ds_read_b128 v[186:189], v249 offset:32768
	v_add3_u32 v246, v244, v240, 0
	v_add3_u32 v247, v244, v241, 0
	v_add3_u32 v248, v244, v242, 0
	v_add3_u32 v249, v244, v243, 0
	ds_read_b128 v[130:133], v246
	ds_read_b128 v[134:137], v247
	ds_read_b128 v[138:141], v248
	ds_read_b128 v[142:145], v249
	ds_read_b128 v[146:149], v246 offset:4096
	ds_read_b128 v[150:153], v247 offset:4096
	ds_read_b128 v[156:159], v248 offset:4096
	ds_read_b128 v[160:163], v249 offset:4096
	s_add_u32 m0, s100, 0x14000
	s_nop 0
	global_load_lds_dwordx4 v233, s[6:7]
	v_add_u32_e32 v233, 0x80, v233
	s_add_u32 m0, s100, 0x16000
	s_nop 0
	global_load_lds_dwordx4 v235, s[6:7]
	v_add_u32_e32 v235, 0x80, v235
	s_waitcnt lgkmcnt(8)
	s_barrier
	s_waitcnt lgkmcnt(0)
	v_mfma_f32_32x32x16_bf16 v[114:129], v[130:133], v[170:173], v[114:129]
	v_mfma_f32_32x32x16_bf16 v[82:97], v[146:149], v[170:173], v[82:97]
	v_mfma_f32_32x32x16_bf16 v[114:129], v[134:137], v[174:177], v[114:129]
	v_mfma_f32_32x32x16_bf16 v[82:97], v[150:153], v[174:177], v[82:97]
	v_mfma_f32_32x32x16_bf16 v[114:129], v[138:141], v[178:181], v[114:129]
	v_mfma_f32_32x32x16_bf16 v[82:97], v[156:159], v[178:181], v[82:97]
	v_mfma_f32_32x32x16_bf16 v[114:129], v[142:145], v[186:189], v[114:129]
	v_mfma_f32_32x32x16_bf16 v[82:97], v[160:163], v[186:189], v[82:97]
	s_barrier
	v_add3_u32 v246, v245, v240, 0
	v_add3_u32 v247, v245, v241, 0
	v_add3_u32 v248, v245, v242, 0
	v_add3_u32 v249, v245, v243, 0
	ds_read_b128 v[190:193], v246 offset:49152
	ds_read_b128 v[194:197], v247 offset:49152
	ds_read_b128 v[198:201], v248 offset:49152
	ds_read_b128 v[228:231], v249 offset:49152
	s_add_u32 m0, s100, 0x8000
	s_nop 0
	global_load_lds_dwordx4 v236, s[8:9]
	v_add_u32_e32 v236, 0x80, v236
	s_add_u32 m0, s100, 0xa000
	s_nop 0
	global_load_lds_dwordx4 v238, s[8:9]
	v_add_u32_e32 v238, 0x80, v238
	s_barrier
	s_waitcnt lgkmcnt(0)
	v_mfma_f32_32x32x16_bf16 v[98:113], v[130:133], v[190:193], v[98:113]
	v_mfma_f32_32x32x16_bf16 v[66:81], v[146:149], v[190:193], v[66:81]
	v_mfma_f32_32x32x16_bf16 v[98:113], v[134:137], v[194:197], v[98:113]
	v_mfma_f32_32x32x16_bf16 v[66:81], v[150:153], v[194:197], v[66:81]
	v_mfma_f32_32x32x16_bf16 v[98:113], v[138:141], v[198:201], v[98:113]
	v_mfma_f32_32x32x16_bf16 v[66:81], v[156:159], v[198:201], v[66:81]
	v_mfma_f32_32x32x16_bf16 v[98:113], v[142:145], v[228:231], v[98:113]
	v_mfma_f32_32x32x16_bf16 v[66:81], v[160:163], v[228:231], v[66:81]
	s_barrier
	v_add3_u32 v246, v244, v240, 0
	v_add3_u32 v247, v244, v241, 0
	v_add3_u32 v248, v244, v242, 0
	v_add3_u32 v249, v244, v243, 0
	ds_read_b128 v[130:133], v246 offset:16384
	ds_read_b128 v[134:137], v247 offset:16384
	ds_read_b128 v[138:141], v248 offset:16384
	ds_read_b128 v[142:145], v249 offset:16384
	ds_read_b128 v[146:149], v246 offset:20480
	ds_read_b128 v[150:153], v247 offset:20480
	ds_read_b128 v[156:159], v248 offset:20480
	ds_read_b128 v[160:163], v249 offset:20480
	s_add_u32 m0, s100, 0x0
	s_nop 0
	global_load_lds_dwordx4 v232, s[6:7]
	v_add_u32_e32 v232, 0x80, v232
	s_add_u32 m0, s100, 0x2000
	s_nop 0
	global_load_lds_dwordx4 v234, s[6:7]
	v_add_u32_e32 v234, 0x80, v234
	s_barrier
	s_waitcnt lgkmcnt(0)
	v_mfma_f32_32x32x16_bf16 v[50:65], v[130:133], v[170:173], v[50:65]
	v_mfma_f32_32x32x16_bf16 v[18:33], v[146:149], v[170:173], v[18:33]
	v_mfma_f32_32x32x16_bf16 v[50:65], v[134:137], v[174:177], v[50:65]
	v_mfma_f32_32x32x16_bf16 v[18:33], v[150:153], v[174:177], v[18:33]
	v_mfma_f32_32x32x16_bf16 v[50:65], v[138:141], v[178:181], v[50:65]
	v_mfma_f32_32x32x16_bf16 v[18:33], v[156:159], v[178:181], v[18:33]
	v_mfma_f32_32x32x16_bf16 v[50:65], v[142:145], v[186:189], v[50:65]
	v_mfma_f32_32x32x16_bf16 v[18:33], v[160:163], v[186:189], v[18:33]
	s_barrier
	s_add_u32 m0, s100, 0xc000
	s_nop 0
	global_load_lds_dwordx4 v237, s[8:9]
	v_add_u32_e32 v237, 0x80, v237
	s_add_u32 m0, s100, 0xe000
	s_nop 0
	global_load_lds_dwordx4 v239, s[8:9]
	v_add_u32_e32 v239, 0x80, v239
	s_waitcnt vmcnt(6)
	s_barrier
	v_mfma_f32_32x32x16_bf16 v[34:49], v[130:133], v[190:193], v[34:49]
	v_mfma_f32_32x32x16_bf16 v[2:17], v[146:149], v[190:193], v[2:17]
	v_mfma_f32_32x32x16_bf16 v[34:49], v[134:137], v[194:197], v[34:49]
	v_mfma_f32_32x32x16_bf16 v[2:17], v[150:153], v[194:197], v[2:17]
	v_mfma_f32_32x32x16_bf16 v[34:49], v[138:141], v[198:201], v[34:49]
	v_mfma_f32_32x32x16_bf16 v[2:17], v[156:159], v[198:201], v[2:17]
	v_mfma_f32_32x32x16_bf16 v[34:49], v[142:145], v[228:231], v[34:49]
	v_mfma_f32_32x32x16_bf16 v[2:17], v[160:163], v[228:231], v[2:17]
	s_barrier
	v_add3_u32 v246, v245, v240, s10
	v_add3_u32 v247, v245, v241, s10
	v_add3_u32 v248, v245, v242, s10
	v_add3_u32 v249, v245, v243, s10
	ds_read_b128 v[170:173], v246 offset:32768
	ds_read_b128 v[174:177], v247 offset:32768
	ds_read_b128 v[178:181], v248 offset:32768
	ds_read_b128 v[186:189], v249 offset:32768
	v_add3_u32 v246, v244, v240, s10
	v_add3_u32 v247, v244, v241, s10
	v_add3_u32 v248, v244, v242, s10
	v_add3_u32 v249, v244, v243, s10
	ds_read_b128 v[130:133], v246
	ds_read_b128 v[134:137], v247
	ds_read_b128 v[138:141], v248
	ds_read_b128 v[142:145], v249
	ds_read_b128 v[146:149], v246 offset:4096
	ds_read_b128 v[150:153], v247 offset:4096
	ds_read_b128 v[156:159], v248 offset:4096
	ds_read_b128 v[160:163], v249 offset:4096
	s_add_u32 m0, s100, 0x4000
	s_nop 0
	global_load_lds_dwordx4 v233, s[6:7]
	v_add_u32_e32 v233, 0x80, v233
	s_add_u32 m0, s100, 0x6000
	s_nop 0
	global_load_lds_dwordx4 v235, s[6:7]
	v_add_u32_e32 v235, 0x80, v235
	s_waitcnt lgkmcnt(8)
	s_barrier
; #define MFMA(a, b, c) __builtin_amdgcn_mfma_f32_32x32x16_bf16((a), (b), (c), 0, 0, 0)
; template <bool SWAP>
; DI void gemm_mainloop(f32x16 (&acc)[4][2], const u16* __restrict__ A, int lda, int rlo, int rhi,
;                       const u16* __restrict__ B, int ldb, int K, char* lds, const u16* zero_line) {
;     ...
;   auto ldfrag = [&](const char* st, int ks, int buf) {
;     const int co = ((2 * ks + h) ^ sw) << 4;
; #pragma unroll
;     for (int mi = 0; mi < 4; ++mi) fa[buf][mi] = *(const bf16x8*)(st + arow_off + mi * 4096 + co);
; #pragma unroll
;     for (int ni = 0; ni < 2; ++ni) fb[buf][ni] = *(const bf16x8*)(st + brow_off + ni * 4096 + co);
;   };
;   auto mma = [&](int buf) {
; #pragma unroll
;     for (int mi = 0; mi < 4; ++mi)
; #pragma unroll
;       for (int ni = 0; ni < 2; ++ni)
;         acc[mi][ni] = SWAP ? MFMA(fb[buf][ni], fa[buf][mi], acc[mi][ni]) : MFMA(fa[buf][mi], fb[buf][ni], acc[mi][ni]);
;   };
;   auto pat_rd = [&]() {
; #pragma unroll
;     for (int g = 0; g < 6; ++g) {
;       __builtin_amdgcn_sched_group_barrier(0x100, 1, 0);
;       __builtin_amdgcn_sched_group_barrier(0x008, 1, 0);
;     }
;     __builtin_amdgcn_sched_group_barrier(0x008, 2, 0);
;   };
; #pragma unroll 2
;   for (int kt = 0; kt < nk; ++kt) {
;     const char* st = lds + (kt & 1) * 65536;
;     ldfrag(st, 0, 0);
;     mma(1);
;     pat_rd();
;     if (kt + 1 < nk) glds(kt + 1, (kt + 1) & 1);
;     ldfrag(st, 1, 1);
;     mma(0);
;     pat_rd();
;     ldfrag(st, 2, 0);
;     mma(1);
;     pat_rd();
;     ldfrag(st, 3, 1);
;     mma(0);
;     pat_rd();
;     asm volatile("s_waitcnt vmcnt(0)" ::: "memory");
;     __syncthreads();
;   }
;   mma(1);
	s_waitcnt lgkmcnt(0)
	v_mfma_f32_32x32x16_bf16 v[114:129], v[130:133], v[170:173], v[114:129]
	v_mfma_f32_32x32x16_bf16 v[82:97], v[146:149], v[170:173], v[82:97]
	v_mfma_f32_32x32x16_bf16 v[114:129], v[134:137], v[174:177], v[114:129]
	v_mfma_f32_32x32x16_bf16 v[82:97], v[150:153], v[174:177], v[82:97]
	v_mfma_f32_32x32x16_bf16 v[114:129], v[138:141], v[178:181], v[114:129]
	v_mfma_f32_32x32x16_bf16 v[82:97], v[156:159], v[178:181], v[82:97]
	v_mfma_f32_32x32x16_bf16 v[114:129], v[142:145], v[186:189], v[114:129]
	v_mfma_f32_32x32x16_bf16 v[82:97], v[160:163], v[186:189], v[82:97]
	s_barrier
	v_add3_u32 v246, v245, v240, s10
	v_add3_u32 v247, v245, v241, s10
	v_add3_u32 v248, v245, v242, s10
	v_add3_u32 v249, v245, v243, s10
	ds_read_b128 v[190:193], v246 offset:49152
	ds_read_b128 v[194:197], v247 offset:49152
	ds_read_b128 v[198:201], v248 offset:49152
	ds_read_b128 v[228:231], v249 offset:49152
	s_add_u32 m0, s100, 0x18000
	s_nop 0
	global_load_lds_dwordx4 v236, s[8:9]
	v_add_u32_e32 v236, 0x80, v236
	s_add_u32 m0, s100, 0x1a000
	s_nop 0
	global_load_lds_dwordx4 v238, s[8:9]
	v_add_u32_e32 v238, 0x80, v238
	s_barrier
	s_waitcnt lgkmcnt(0)
	v_mfma_f32_32x32x16_bf16 v[98:113], v[130:133], v[190:193], v[98:113]
	v_mfma_f32_32x32x16_bf16 v[66:81], v[146:149], v[190:193], v[66:81]
	v_mfma_f32_32x32x16_bf16 v[98:113], v[134:137], v[194:197], v[98:113]
	v_mfma_f32_32x32x16_bf16 v[66:81], v[150:153], v[194:197], v[66:81]
	v_mfma_f32_32x32x16_bf16 v[98:113], v[138:141], v[198:201], v[98:113]
	v_mfma_f32_32x32x16_bf16 v[66:81], v[156:159], v[198:201], v[66:81]
	v_mfma_f32_32x32x16_bf16 v[98:113], v[142:145], v[228:231], v[98:113]
	v_mfma_f32_32x32x16_bf16 v[66:81], v[160:163], v[228:231], v[66:81]
	s_barrier
	v_add3_u32 v246, v244, v240, s10
	v_add3_u32 v247, v244, v241, s10
	v_add3_u32 v248, v244, v242, s10
	v_add3_u32 v249, v244, v243, s10
	ds_read_b128 v[130:133], v246 offset:16384
	ds_read_b128 v[134:137], v247 offset:16384
	ds_read_b128 v[138:141], v248 offset:16384
	ds_read_b128 v[142:145], v249 offset:16384
	ds_read_b128 v[146:149], v246 offset:20480
	ds_read_b128 v[150:153], v247 offset:20480
	ds_read_b128 v[156:159], v248 offset:20480
	ds_read_b128 v[160:163], v249 offset:20480
	s_add_u32 m0, s100, 0x10000
	s_nop 0
	global_load_lds_dwordx4 v232, s[6:7]
	v_add_u32_e32 v232, 0x80, v232
	s_add_u32 m0, s100, 0x12000
	s_nop 0
	global_load_lds_dwordx4 v234, s[6:7]
	v_add_u32_e32 v234, 0x80, v234
	s_barrier
	s_waitcnt lgkmcnt(0)
	v_mfma_f32_32x32x16_bf16 v[50:65], v[130:133], v[170:173], v[50:65]
	v_mfma_f32_32x32x16_bf16 v[18:33], v[146:149], v[170:173], v[18:33]
	v_mfma_f32_32x32x16_bf16 v[50:65], v[134:137], v[174:177], v[50:65]
	v_mfma_f32_32x32x16_bf16 v[18:33], v[150:153], v[174:177], v[18:33]
	v_mfma_f32_32x32x16_bf16 v[50:65], v[138:141], v[178:181], v[50:65]
	v_mfma_f32_32x32x16_bf16 v[18:33], v[156:159], v[178:181], v[18:33]
	v_mfma_f32_32x32x16_bf16 v[50:65], v[142:145], v[186:189], v[50:65]
	v_mfma_f32_32x32x16_bf16 v[18:33], v[160:163], v[186:189], v[18:33]
	s_barrier
	s_add_u32 m0, s100, 0x1c000
	s_nop 0
	global_load_lds_dwordx4 v237, s[8:9]
	v_add_u32_e32 v237, 0x80, v237
	s_add_u32 m0, s100, 0x1e000
	s_nop 0
	global_load_lds_dwordx4 v239, s[8:9]
	v_add_u32_e32 v239, 0x80, v239
	s_waitcnt vmcnt(6)
	s_barrier
	v_mfma_f32_32x32x16_bf16 v[34:49], v[130:133], v[190:193], v[34:49]
	v_mfma_f32_32x32x16_bf16 v[2:17], v[146:149], v[190:193], v[2:17]
	v_mfma_f32_32x32x16_bf16 v[34:49], v[134:137], v[194:197], v[34:49]
	v_mfma_f32_32x32x16_bf16 v[2:17], v[150:153], v[194:197], v[2:17]
	v_mfma_f32_32x32x16_bf16 v[34:49], v[138:141], v[198:201], v[34:49]
	v_mfma_f32_32x32x16_bf16 v[2:17], v[156:159], v[198:201], v[2:17]
	v_mfma_f32_32x32x16_bf16 v[34:49], v[142:145], v[228:231], v[34:49]
	v_mfma_f32_32x32x16_bf16 v[2:17], v[160:163], v[228:231], v[2:17]
	s_barrier
	s_add_i32 s11, s11, 2
	s_cmp_lt_u32 s11, 14
	s_cbranch_scc1 .Lg8_qa
	v_add3_u32 v246, v245, v240, 0
	v_add3_u32 v247, v245, v241, 0
	v_add3_u32 v248, v245, v242, 0
	v_add3_u32 v249, v245, v243, 0
	ds_read_b128 v[170:173], v246 offset:32768
	ds_read_b128 v[174:177], v247 offset:32768
	ds_read_b128 v[178:181], v248 offset:32768
	ds_read_b128 v[186:189], v249 offset:32768
	v_add3_u32 v246, v244, v240, 0
	v_add3_u32 v247, v244, v241, 0
	v_add3_u32 v248, v244, v242, 0
	v_add3_u32 v249, v244, v243, 0
	ds_read_b128 v[130:133], v246
	ds_read_b128 v[134:137], v247
	ds_read_b128 v[138:141], v248
	ds_read_b128 v[142:145], v249
	ds_read_b128 v[146:149], v246 offset:4096
	ds_read_b128 v[150:153], v247 offset:4096
	ds_read_b128 v[156:159], v248 offset:4096
	ds_read_b128 v[160:163], v249 offset:4096
	s_add_u32 m0, s100, 0x14000
	s_nop 0
	global_load_lds_dwordx4 v233, s[6:7]
	v_add_u32_e32 v233, 0x80, v233
	s_add_u32 m0, s100, 0x16000
	s_nop 0
	global_load_lds_dwordx4 v235, s[6:7]
	v_add_u32_e32 v235, 0x80, v235
	s_barrier
	s_waitcnt lgkmcnt(0)
	v_mfma_f32_32x32x16_bf16 v[114:129], v[130:133], v[170:173], v[114:129]
	v_mfma_f32_32x32x16_bf16 v[82:97], v[146:149], v[170:173], v[82:97]
	v_mfma_f32_32x32x16_bf16 v[114:129], v[134:137], v[174:177], v[114:129]
	v_mfma_f32_32x32x16_bf16 v[82:97], v[150:153], v[174:177], v[82:97]
	v_mfma_f32_32x32x16_bf16 v[114:129], v[138:141], v[178:181], v[114:129]
	v_mfma_f32_32x32x16_bf16 v[82:97], v[156:159], v[178:181], v[82:97]
	v_mfma_f32_32x32x16_bf16 v[114:129], v[142:145], v[186:189], v[114:129]
	v_mfma_f32_32x32x16_bf16 v[82:97], v[160:163], v[186:189], v[82:97]
	s_barrier
	v_add3_u32 v246, v245, v240, 0
	v_add3_u32 v247, v245, v241, 0
	v_add3_u32 v248, v245, v242, 0
	v_add3_u32 v249, v245, v243, 0
	ds_read_b128 v[190:193], v246 offset:49152
	ds_read_b128 v[194:197], v247 offset:49152
	ds_read_b128 v[198:201], v248 offset:49152
	ds_read_b128 v[228:231], v249 offset:49152
	s_barrier
; #define MFMA(a, b, c) __builtin_amdgcn_mfma_f32_32x32x16_bf16((a), (b), (c), 0, 0, 0)
; template <bool SWAP>
; DI void gemm_mainloop(f32x16 (&acc)[4][2], const u16* __restrict__ A, int lda, int rlo, int rhi,
;                       const u16* __restrict__ B, int ldb, int K, char* lds, const u16* zero_line) {
;     ...
;   auto ldfrag = [&](const char* st, int ks, int buf) {
;     const int co = ((2 * ks + h) ^ sw) << 4;
; #pragma unroll
;     for (int mi = 0; mi < 4; ++mi) fa[buf][mi] = *(const bf16x8*)(st + arow_off + mi * 4096 + co);
; #pragma unroll
;     for (int ni = 0; ni < 2; ++ni) fb[buf][ni] = *(const bf16x8*)(st + brow_off + ni * 4096 + co);
;   };
;   auto mma = [&](int buf) {
; #pragma unroll
;     for (int mi = 0; mi < 4; ++mi)
; #pragma unroll
;       for (int ni = 0; ni < 2; ++ni)
;         acc[mi][ni] = SWAP ? MFMA(fb[buf][ni], fa[buf][mi], acc[mi][ni]) : MFMA(fa[buf][mi], fb[buf][ni], acc[mi][ni]);
;   };
;   auto pat_rd = [&]() {
; #pragma unroll
;     for (int g = 0; g < 6; ++g) {
;       __builtin_amdgcn_sched_group_barrier(0x100, 1, 0);
;       __builtin_amdgcn_sched_group_barrier(0x008, 1, 0);
;     }
;     __builtin_amdgcn_sched_group_barrier(0x008, 2, 0);
;   };
; #pragma unroll 2
;   for (int kt = 0; kt < nk; ++kt) {
;     const char* st = lds + (kt & 1) * 65536;
;     ldfrag(st, 0, 0);
;     mma(1);
;     pat_rd();
;     if (kt + 1 < nk) glds(kt + 1, (kt + 1) & 1);
;     ldfrag(st, 1, 1);
;     mma(0);
;     pat_rd();
;     ldfrag(st, 2, 0);
;     mma(1);
;     pat_rd();
;     ldfrag(st, 3, 1);
;     mma(0);
;     pat_rd();
;     asm volatile("s_waitcnt vmcnt(0)" ::: "memory");
;     __syncthreads();
;   }
;   mma(1);
	s_waitcnt lgkmcnt(0)
	v_mfma_f32_32x32x16_bf16 v[98:113], v[130:133], v[190:193], v[98:113]
	v_mfma_f32_32x32x16_bf16 v[66:81], v[146:149], v[190:193], v[66:81]
	v_mfma_f32_32x32x16_bf16 v[98:113], v[134:137], v[194:197], v[98:113]
	v_mfma_f32_32x32x16_bf16 v[66:81], v[150:153], v[194:197], v[66:81]
	v_mfma_f32_32x32x16_bf16 v[98:113], v[138:141], v[198:201], v[98:113]
	v_mfma_f32_32x32x16_bf16 v[66:81], v[156:159], v[198:201], v[66:81]
	v_mfma_f32_32x32x16_bf16 v[98:113], v[142:145], v[228:231], v[98:113]
	v_mfma_f32_32x32x16_bf16 v[66:81], v[160:163], v[228:231], v[66:81]
	s_barrier
	v_add3_u32 v246, v244, v240, 0
	v_add3_u32 v247, v244, v241, 0
	v_add3_u32 v248, v244, v242, 0
	v_add3_u32 v249, v244, v243, 0
	ds_read_b128 v[130:133], v246 offset:16384
	ds_read_b128 v[134:137], v247 offset:16384
	ds_read_b128 v[138:141], v248 offset:16384
	ds_read_b128 v[142:145], v249 offset:16384
	ds_read_b128 v[146:149], v246 offset:20480
	ds_read_b128 v[150:153], v247 offset:20480
	ds_read_b128 v[156:159], v248 offset:20480
	ds_read_b128 v[160:163], v249 offset:20480
	s_waitcnt vmcnt(4)
	s_barrier
	s_waitcnt lgkmcnt(0)
	v_mfma_f32_32x32x16_bf16 v[50:65], v[130:133], v[170:173], v[50:65]
	v_mfma_f32_32x32x16_bf16 v[18:33], v[146:149], v[170:173], v[18:33]
	v_mfma_f32_32x32x16_bf16 v[50:65], v[134:137], v[174:177], v[50:65]
	v_mfma_f32_32x32x16_bf16 v[18:33], v[150:153], v[174:177], v[18:33]
	v_mfma_f32_32x32x16_bf16 v[50:65], v[138:141], v[178:181], v[50:65]
	v_mfma_f32_32x32x16_bf16 v[18:33], v[156:159], v[178:181], v[18:33]
	v_mfma_f32_32x32x16_bf16 v[50:65], v[142:145], v[186:189], v[50:65]
	v_mfma_f32_32x32x16_bf16 v[18:33], v[160:163], v[186:189], v[18:33]
	v_mfma_f32_32x32x16_bf16 v[34:49], v[130:133], v[190:193], v[34:49]
	v_mfma_f32_32x32x16_bf16 v[2:17], v[146:149], v[190:193], v[2:17]
	v_mfma_f32_32x32x16_bf16 v[34:49], v[134:137], v[194:197], v[34:49]
	v_mfma_f32_32x32x16_bf16 v[2:17], v[150:153], v[194:197], v[2:17]
	v_mfma_f32_32x32x16_bf16 v[34:49], v[138:141], v[198:201], v[34:49]
	v_mfma_f32_32x32x16_bf16 v[2:17], v[156:159], v[198:201], v[2:17]
	v_mfma_f32_32x32x16_bf16 v[34:49], v[142:145], v[228:231], v[34:49]
	v_mfma_f32_32x32x16_bf16 v[2:17], v[160:163], v[228:231], v[2:17]
	s_barrier
	v_add3_u32 v246, v245, v240, s10
	v_add3_u32 v247, v245, v241, s10
	v_add3_u32 v248, v245, v242, s10
	v_add3_u32 v249, v245, v243, s10
	ds_read_b128 v[170:173], v246 offset:32768
	ds_read_b128 v[174:177], v247 offset:32768
	ds_read_b128 v[178:181], v248 offset:32768
	ds_read_b128 v[186:189], v249 offset:32768
	v_add3_u32 v246, v244, v240, s10
	v_add3_u32 v247, v244, v241, s10
	v_add3_u32 v248, v244, v242, s10
	v_add3_u32 v249, v244, v243, s10
	ds_read_b128 v[130:133], v246
	ds_read_b128 v[134:137], v247
	ds_read_b128 v[138:141], v248
	ds_read_b128 v[142:145], v249
	ds_read_b128 v[146:149], v246 offset:4096
	ds_read_b128 v[150:153], v247 offset:4096
	ds_read_b128 v[156:159], v248 offset:4096
	ds_read_b128 v[160:163], v249 offset:4096
	s_waitcnt vmcnt(2)
	s_barrier
	s_waitcnt lgkmcnt(0)
	v_mfma_f32_32x32x16_bf16 v[114:129], v[130:133], v[170:173], v[114:129]
	v_mfma_f32_32x32x16_bf16 v[82:97], v[146:149], v[170:173], v[82:97]
	v_mfma_f32_32x32x16_bf16 v[114:129], v[134:137], v[174:177], v[114:129]
	v_mfma_f32_32x32x16_bf16 v[82:97], v[150:153], v[174:177], v[82:97]
	v_mfma_f32_32x32x16_bf16 v[114:129], v[138:141], v[178:181], v[114:129]
	v_mfma_f32_32x32x16_bf16 v[82:97], v[156:159], v[178:181], v[82:97]
	v_mfma_f32_32x32x16_bf16 v[114:129], v[142:145], v[186:189], v[114:129]
	v_mfma_f32_32x32x16_bf16 v[82:97], v[160:163], v[186:189], v[82:97]
	s_barrier
	v_add3_u32 v246, v245, v240, s10
	v_add3_u32 v247, v245, v241, s10
	v_add3_u32 v248, v245, v242, s10
	v_add3_u32 v249, v245, v243, s10
	ds_read_b128 v[190:193], v246 offset:49152
	ds_read_b128 v[194:197], v247 offset:49152
	ds_read_b128 v[198:201], v248 offset:49152
	ds_read_b128 v[228:231], v249 offset:49152
	s_waitcnt vmcnt(0)
	s_barrier
	s_waitcnt lgkmcnt(0)
	v_mfma_f32_32x32x16_bf16 v[98:113], v[130:133], v[190:193], v[98:113]
	v_mfma_f32_32x32x16_bf16 v[66:81], v[146:149], v[190:193], v[66:81]
	v_mfma_f32_32x32x16_bf16 v[98:113], v[134:137], v[194:197], v[98:113]
	v_mfma_f32_32x32x16_bf16 v[66:81], v[150:153], v[194:197], v[66:81]
	v_mfma_f32_32x32x16_bf16 v[98:113], v[138:141], v[198:201], v[98:113]
	v_mfma_f32_32x32x16_bf16 v[66:81], v[156:159], v[198:201], v[66:81]
	v_mfma_f32_32x32x16_bf16 v[98:113], v[142:145], v[228:231], v[98:113]
	v_mfma_f32_32x32x16_bf16 v[66:81], v[160:163], v[228:231], v[66:81]
	s_barrier
	v_add3_u32 v246, v244, v240, s10
	v_add3_u32 v247, v244, v241, s10
	v_add3_u32 v248, v244, v242, s10
	v_add3_u32 v249, v244, v243, s10
	ds_read_b128 v[130:133], v246 offset:16384
	ds_read_b128 v[134:137], v247 offset:16384
	ds_read_b128 v[138:141], v248 offset:16384
	ds_read_b128 v[142:145], v249 offset:16384
	ds_read_b128 v[146:149], v246 offset:20480
	ds_read_b128 v[150:153], v247 offset:20480
	ds_read_b128 v[156:159], v248 offset:20480
	ds_read_b128 v[160:163], v249 offset:20480
	s_barrier
	s_waitcnt lgkmcnt(0)
	v_mfma_f32_32x32x16_bf16 v[50:65], v[130:133], v[170:173], v[50:65]
	v_mfma_f32_32x32x16_bf16 v[18:33], v[146:149], v[170:173], v[18:33]
	v_mfma_f32_32x32x16_bf16 v[50:65], v[134:137], v[174:177], v[50:65]
	v_mfma_f32_32x32x16_bf16 v[18:33], v[150:153], v[174:177], v[18:33]
	v_mfma_f32_32x32x16_bf16 v[50:65], v[138:141], v[178:181], v[50:65]
	v_mfma_f32_32x32x16_bf16 v[18:33], v[156:159], v[178:181], v[18:33]
	v_mfma_f32_32x32x16_bf16 v[50:65], v[142:145], v[186:189], v[50:65]
	v_mfma_f32_32x32x16_bf16 v[18:33], v[160:163], v[186:189], v[18:33]
	v_mfma_f32_32x32x16_bf16 v[34:49], v[130:133], v[190:193], v[34:49]
	v_mfma_f32_32x32x16_bf16 v[2:17], v[146:149], v[190:193], v[2:17]
	v_mfma_f32_32x32x16_bf16 v[34:49], v[134:137], v[194:197], v[34:49]
	v_mfma_f32_32x32x16_bf16 v[2:17], v[150:153], v[194:197], v[2:17]
	v_mfma_f32_32x32x16_bf16 v[34:49], v[138:141], v[198:201], v[34:49]
	v_mfma_f32_32x32x16_bf16 v[2:17], v[156:159], v[198:201], v[2:17]
	v_mfma_f32_32x32x16_bf16 v[34:49], v[142:145], v[228:231], v[34:49]
	v_mfma_f32_32x32x16_bf16 v[2:17], v[160:163], v[228:231], v[2:17]
	s_barrier
	s_cmp_eq_u32 s101, 0
	s_cbranch_scc0 .Lg8_qa_p1
	s_barrier
; DI int opaque_tid() { int t = threadIdx.x; asm volatile("" : "+v"(t)); return t; }
; template <bool SWAP>
; DI void gemm_mainloop(f32x16 (&acc)[4][2], const u16* __restrict__ A, int lda, int rlo, int rhi,
;                       const u16* __restrict__ B, int ldb, int K, char* lds, const u16* zero_line) {
;   const int tid = opaque_tid(), lane = tid & 63, w = tid >> 6;
;   const int wm = w >> 2, wn = w & 3;
;   const int h = lane >> 5, r = lane & 31;
;   const int lr = tid >> 3, lc = tid & 7;
; #pragma unroll
;   for (int mi = 0; mi < 4; ++mi)
; #pragma unroll
;     for (int ni = 0; ni < 2; ++ni)
; #pragma unroll
;       for (int i = 0; i < 16; ++i) acc[mi][ni][i] = 0.f;
;   const int gch = (lc ^ ((lr >> 1) & 7)) * 8;
;   const u16* ap = A + (ptrdiff_t)lr * lda + gch;
;   const u16* bp = B + (ptrdiff_t)lr * ldb + gch;
;   const int nk = K >> 6;
;   typedef __attribute__((address_space(3))) unsigned lds_u32;
;   auto glds = [&](int kt, int st) {
;     char* as_ = lds + st * 65536 + tid * 16;
; #pragma unroll
;     for (int i = 0; i < 4; ++i) {
;       const int rr = lr + 64 * i;
;       const u16* srca = (rr >= rlo && rr < rhi) ? (ap + (ptrdiff_t)(64 * i) * lda + kt * 64) : (zero_line + lc * 8);
;       __builtin_amdgcn_global_load_lds((const unsigned*)srca, (lds_u32*)(as_ + i * 8192), 16, 0, 0);
;       __builtin_amdgcn_global_load_lds((const unsigned*)(bp + (ptrdiff_t)(64 * i) * ldb + kt * 64), (lds_u32*)(as_ + 32768 + i * 8192), 16, 0, 0);
;     }
;   };
;   const int sw = (r >> 1) & 7;
;   const int arow_off = (wm * 128 + r) * 128;
;   const int brow_off = 32768 + (wn * 64 + r) * 128;
;   __syncthreads();
;   glds(0, 0);
;   asm volatile("s_waitcnt vmcnt(0)" ::: "memory");
;   __syncthreads();
.Lg8_qa_p1:
	s_nop 7
	s_nop 7
.LBB0_202:
	s_mov_b64 s[6:7], 0
.LBB0_203:
	s_and_b64 vcc, exec, s[6:7]
	s_cbranch_vccz .LBB0_209
	s_nop 9
	v_mov_b32_e32 v12, v204
	s_mov_b64 s[10:11], 0x20000
	v_ashrrev_i32_e32 v2, 3, v12
	v_lshrrev_b32_e32 v14, 1, v2
	v_xor_b32_e32 v0, v14, v12
	v_ashrrev_i32_e32 v3, 31, v2
	v_lshlrev_b64 v[4:5], 11, v[2:3]
	v_lshlrev_b32_e32 v0, 4, v0
	v_and_b32_e32 v10, 31, v12
	v_lshl_add_u64 v[6:7], s[20:21], 0, v[4:5]
	v_and_b32_e32 v0, 0x70, v0
	v_lshl_add_u64 v[8:9], s[22:23], 0, v[4:5]
	v_lshrrev_b32_e32 v15, 1, v12
	v_lshl_add_u64 v[6:7], v[6:7], 0, v[0:1]
	v_lshl_add_u64 v[8:9], v[8:9], 0, v[0:1]
	v_and_or_b32 v0, v15, s51, v10
	v_lshlrev_b32_e32 v169, 7, v0
	v_lshlrev_b32_e32 v0, 7, v12
	v_lshlrev_b32_e32 v171, 4, v12
	v_and_b32_e32 v170, 0x6f80, v0
	v_and_b32_e32 v0, 0x70, v171
	v_add_u32_e32 v172, 0x8000, v171
	v_lshl_add_u64 v[156:157], s[80:81], 0, v[0:1]
	v_cmp_gt_u32_e32 vcc, s50, v2
	v_readfirstlane_b32 s6, v171
	s_mov_b32 m0, s6
	v_cndmask_b32_e32 v11, v157, v7, vcc
	v_cndmask_b32_e32 v10, v156, v6, vcc
	v_readfirstlane_b32 s6, v172
	v_add_u32_e32 v0, 64, v2
	v_add_u32_e32 v173, 0x2000, v171
	s_barrier
	s_mov_b32 m0, s6
	v_lshl_add_u64 v[10:11], v[6:7], 0, s[10:11]
	v_cmp_gt_u32_e64 s[6:7], s50, v0
	v_readfirstlane_b32 s8, v173
	v_add_u32_e32 v174, 0xa000, v171
	v_cndmask_b32_e64 v11, v157, v11, s[6:7]
	v_cndmask_b32_e64 v10, v156, v10, s[6:7]
	s_mov_b32 m0, s8
	v_readfirstlane_b32 s8, v174
	v_lshl_add_u64 v[10:11], v[8:9], 0, s[10:11]
	s_mov_b32 m0, s8
	v_add_u32_e32 v0, 0x80, v2
	s_mov_b64 s[20:21], 0x40000
	v_add_u32_e32 v175, 0x4000, v171
	v_lshl_add_u64 v[10:11], v[6:7], 0, s[20:21]
	v_cmp_gt_u32_e64 s[8:9], s50, v0
	v_readfirstlane_b32 s10, v175
	v_add_u32_e32 v176, 0xc000, v171
	v_cndmask_b32_e64 v11, v157, v11, s[8:9]
	v_cndmask_b32_e64 v10, v156, v10, s[8:9]
	s_mov_b32 m0, s10
	v_readfirstlane_b32 s10, v176
	v_add_u32_e32 v0, 0xc0, v2
	s_mov_b64 s[22:23], 0x60000
	v_add_u32_e32 v177, 0x6000, v171
	v_lshl_add_u64 v[10:11], v[8:9], 0, s[20:21]
	s_mov_b32 m0, s10
	v_lshl_add_u64 v[2:3], v[6:7], 0, s[22:23]
	v_cmp_gt_u32_e64 s[10:11], s50, v0
	v_readfirstlane_b32 s20, v177
	v_add_u32_e32 v178, 0xe000, v171
	v_cndmask_b32_e64 v3, v157, v3, s[10:11]
	v_cndmask_b32_e64 v2, v156, v2, s[10:11]
	s_mov_b32 m0, s20
	v_readfirstlane_b32 s20, v178
	v_lshl_add_u64 v[2:3], v[8:9], 0, s[22:23]
	s_mov_b32 m0, s20
	v_bfe_u32 v13, v12, 5, 1
	v_bfe_u32 v16, v12, 1, 3
	v_bitop3_b32 v0, v15, v13, 7 bitop3:0x6c
	s_sub_i32 s20, s28, s31
	v_lshlrev_b32_e32 v179, 4, v0
	v_bitop3_b32 v0, v13, v16, 2 bitop3:0x36
	s_sub_i32 s13, s20, s13
	v_lshlrev_b32_e32 v180, 4, v0
	v_bitop3_b32 v0, v13, v16, 4 bitop3:0x36
	s_lshl_b32 s20, s13, 8
	v_lshlrev_b32_e32 v181, 4, v0
	v_bitop3_b32 v0, v13, v16, 6 bitop3:0x36
	s_ashr_i32 s21, s20, 31
	v_lshlrev_b32_e32 v182, 4, v0
	s_lshl_b64 s[20:21], s[20:21], 11
	v_bitop3_b32 v0, v14, 7, v12 bitop3:0x48
	v_lshl_add_u64 v[2:3], v[4:5], 0, s[20:21]
	v_lshlrev_b32_e32 v0, 4, v0
	v_or_b32_e32 v2, v2, v0
	v_lshl_add_u64 v[158:159], s[70:71], 0, v[2:3]
	v_lshl_add_u64 v[2:3], v[4:5], 0, s[18:19]
	s_waitcnt vmcnt(0)
; DI int opaque_tid() { int t = threadIdx.x; asm volatile("" : "+v"(t)); return t; }
; template <bool SWAP>
; DI void gemm_mainloop(f32x16 (&acc)[4][2], const u16* __restrict__ A, int lda, int rlo, int rhi,
;                       const u16* __restrict__ B, int ldb, int K, char* lds, const u16* zero_line) {
;   const int tid = opaque_tid(), lane = tid & 63, w = tid >> 6;
;   const int wm = w >> 2, wn = w & 3;
;   const int h = lane >> 5, r = lane & 31;
;   const int lr = tid >> 3, lc = tid & 7;
; #pragma unroll
;   for (int mi = 0; mi < 4; ++mi)
; #pragma unroll
;     for (int ni = 0; ni < 2; ++ni)
; #pragma unroll
;       for (int i = 0; i < 16; ++i) acc[mi][ni][i] = 0.f;
;   const int gch = (lc ^ ((lr >> 1) & 7)) * 8;
;   const u16* ap = A + (ptrdiff_t)lr * lda + gch;
;   const u16* bp = B + (ptrdiff_t)lr * ldb + gch;
;   const int nk = K >> 6;
;   typedef __attribute__((address_space(3))) unsigned lds_u32;
;   auto glds = [&](int kt, int st) {
;     char* as_ = lds + st * 65536 + tid * 16;
; #pragma unroll
;     for (int i = 0; i < 4; ++i) {
;       const int rr = lr + 64 * i;
;       const u16* srca = (rr >= rlo && rr < rhi) ? (ap + (ptrdiff_t)(64 * i) * lda + kt * 64) : (zero_line + lc * 8);
;       __builtin_amdgcn_global_load_lds((const unsigned*)srca, (lds_u32*)(as_ + i * 8192), 16, 0, 0);
;       __builtin_amdgcn_global_load_lds((const unsigned*)(bp + (ptrdiff_t)(64 * i) * ldb + kt * 64), (lds_u32*)(as_ + 32768 + i * 8192), 16, 0, 0);
;     }
;   };
;   const int sw = (r >> 1) & 7;
;   const int arow_off = (wm * 128 + r) * 128;
;   const int brow_off = 32768 + (wn * 64 + r) * 128;
;   __syncthreads();
;   glds(0, 0);
;   asm volatile("s_waitcnt vmcnt(0)" ::: "memory");
;   __syncthreads();
	v_lshl_add_u64 v[2:3], v[2:3], 0, v[0:1]
	v_lshl_add_u64 v[160:161], s[70:71], 0, v[2:3]
	v_mov_b32_e32 v130, 0
	v_mov_b32_e32 v2, 0
	s_mov_b32 s15, 1
	v_add_u32_e32 v183, 0x10000, v171
	v_add_u32_e32 v185, 0x18000, v171
	v_add_u32_e32 v186, 0x12000, v171
	v_add_u32_e32 v187, 0x1a000, v171
	v_add_u32_e32 v188, 0x14000, v171
	v_add_u32_e32 v189, 0x1c000, v171
	v_add_u32_e32 v190, 0x16000, v171
	v_add_u32_e32 v191, 0x1e000, v171
	v_add_u32_e32 v192, 0x10000, v169
	v_or_b32_e32 v193, 0x10000, v170
	s_mov_b64 s[18:19], 0
	v_mov_b32_e32 v3, v2
	v_mov_b32_e32 v4, v2
	v_mov_b32_e32 v5, v2
	v_mov_b32_e32 v6, v2
	v_mov_b32_e32 v7, v2
	v_mov_b32_e32 v8, v2
	v_mov_b32_e32 v9, v2
	v_mov_b32_e32 v10, v2
	v_mov_b32_e32 v11, v2
	v_mov_b32_e32 v12, v2
	v_mov_b32_e32 v13, v2
	v_mov_b32_e32 v14, v2
	v_mov_b32_e32 v15, v2
	v_mov_b32_e32 v16, v2
	v_mov_b32_e32 v17, v2
	v_mov_b32_e32 v18, v2
	v_mov_b32_e32 v19, v2
	v_mov_b32_e32 v20, v2
	v_mov_b32_e32 v21, v2
	v_mov_b32_e32 v22, v2
	v_mov_b32_e32 v23, v2
	v_mov_b32_e32 v24, v2
	v_mov_b32_e32 v25, v2
	v_mov_b32_e32 v26, v2
	v_mov_b32_e32 v27, v2
	v_mov_b32_e32 v28, v2
	v_mov_b32_e32 v29, v2
	v_mov_b32_e32 v30, v2
	v_mov_b32_e32 v31, v2
	v_mov_b32_e32 v32, v2
	v_mov_b32_e32 v33, v2
	v_mov_b32_e32 v34, v2
	v_mov_b32_e32 v35, v2
	v_mov_b32_e32 v36, v2
	v_mov_b32_e32 v37, v2
	v_mov_b32_e32 v38, v2
	v_mov_b32_e32 v39, v2
	v_mov_b32_e32 v40, v2
	v_mov_b32_e32 v41, v2
	v_mov_b32_e32 v42, v2
	v_mov_b32_e32 v43, v2
	v_mov_b32_e32 v44, v2
	v_mov_b32_e32 v45, v2
	v_mov_b32_e32 v46, v2
	v_mov_b32_e32 v47, v2
	v_mov_b32_e32 v48, v2
	v_mov_b32_e32 v49, v2
	v_mov_b32_e32 v50, v2
	v_mov_b32_e32 v51, v2
	v_mov_b32_e32 v52, v2
	v_mov_b32_e32 v53, v2
	v_mov_b32_e32 v54, v2
	v_mov_b32_e32 v55, v2
	v_mov_b32_e32 v56, v2
	v_mov_b32_e32 v57, v2
	v_mov_b32_e32 v58, v2
	v_mov_b32_e32 v59, v2
	v_mov_b32_e32 v60, v2
	v_mov_b32_e32 v61, v2
	v_mov_b32_e32 v62, v2
	v_mov_b32_e32 v63, v2
	v_mov_b32_e32 v64, v2
	v_mov_b32_e32 v65, v2
	v_mov_b32_e32 v66, v2
	v_mov_b32_e32 v67, v2
	v_mov_b32_e32 v68, v2
	v_mov_b32_e32 v69, v2
	v_mov_b32_e32 v70, v2
	v_mov_b32_e32 v71, v2
	v_mov_b32_e32 v72, v2
	v_mov_b32_e32 v73, v2
	v_mov_b32_e32 v74, v2
	v_mov_b32_e32 v75, v2
	v_mov_b32_e32 v76, v2
	v_mov_b32_e32 v77, v2
	v_mov_b32_e32 v78, v2
	v_mov_b32_e32 v79, v2
	v_mov_b32_e32 v80, v2
	v_mov_b32_e32 v81, v2
	v_mov_b32_e32 v82, v2
	v_mov_b32_e32 v83, v2
	v_mov_b32_e32 v84, v2
	v_mov_b32_e32 v85, v2
	v_mov_b32_e32 v86, v2
	v_mov_b32_e32 v87, v2
	v_mov_b32_e32 v88, v2
	v_mov_b32_e32 v89, v2
	v_mov_b32_e32 v90, v2
	v_mov_b32_e32 v91, v2
	v_mov_b32_e32 v92, v2
	v_mov_b32_e32 v93, v2
	v_mov_b32_e32 v94, v2
	v_mov_b32_e32 v95, v2
	v_mov_b32_e32 v96, v2
	v_mov_b32_e32 v97, v2
	v_mov_b32_e32 v98, v2
	v_mov_b32_e32 v99, v2
	v_mov_b32_e32 v100, v2
	v_mov_b32_e32 v101, v2
	v_mov_b32_e32 v102, v2
	v_mov_b32_e32 v103, v2
	v_mov_b32_e32 v104, v2
	v_mov_b32_e32 v105, v2
	v_mov_b32_e32 v106, v2
	v_mov_b32_e32 v107, v2
	v_mov_b32_e32 v108, v2
	v_mov_b32_e32 v109, v2
	v_mov_b32_e32 v110, v2
	v_mov_b32_e32 v111, v2
	v_mov_b32_e32 v112, v2
	v_mov_b32_e32 v113, v2
	v_mov_b32_e32 v114, v2
	v_mov_b32_e32 v115, v2
	v_mov_b32_e32 v116, v2
	v_mov_b32_e32 v117, v2
	v_mov_b32_e32 v118, v2
	v_mov_b32_e32 v119, v2
	v_mov_b32_e32 v120, v2
	v_mov_b32_e32 v121, v2
	v_mov_b32_e32 v122, v2
	v_mov_b32_e32 v123, v2
	v_mov_b32_e32 v124, v2
	v_mov_b32_e32 v125, v2
	v_mov_b32_e32 v126, v2
	v_mov_b32_e32 v127, v2
	v_mov_b32_e32 v128, v2
	v_mov_b32_e32 v129, v2
	v_mov_b32_e32 v131, v130
	v_mov_b32_e32 v132, v130
	v_mov_b32_e32 v133, v130
	v_mov_b32_e32 v134, v130
	v_mov_b32_e32 v135, v130
	v_mov_b32_e32 v136, v130
	v_mov_b32_e32 v137, v130
	v_mov_b32_e32 v138, v130
	v_mov_b32_e32 v139, v130
	v_mov_b32_e32 v140, v130
	v_mov_b32_e32 v141, v130
	v_mov_b32_e32 v146, v130
	v_mov_b32_e32 v147, v130
	v_mov_b32_e32 v148, v130
	v_mov_b32_e32 v149, v130
	v_mov_b32_e32 v142, v130
	v_mov_b32_e32 v143, v130
	v_mov_b32_e32 v144, v130
	v_mov_b32_e32 v145, v130
	v_mov_b32_e32 v150, v130
	v_mov_b32_e32 v151, v130
	v_mov_b32_e32 v152, v130
	v_mov_b32_e32 v153, v130
	s_waitcnt vmcnt(0) lgkmcnt(0)
	s_barrier
	s_ashr_i32 s7, s12, 31
	s_mov_b32 s6, s12
	s_lshl_b64 s[6:7], s[6:7], 11
	s_add_u32 s6, s90, s6
	s_addc_u32 s7, s91, s7
	s_ashr_i32 s9, s14, 31
	s_mov_b32 s8, s14
	s_lshl_b64 s[8:9], s[8:9], 11
	v_readlane_b32 s10, v253, 43
	v_readlane_b32 s11, v253, 44
	s_add_u32 s8, s10, s8
	s_addc_u32 s9, s11, s9
	v_and_b32_e32 v130, 63, v204
	v_lshrrev_b32_e32 v131, 6, v204
	v_lshrrev_b32_e32 v132, 3, v204
	v_lshrrev_b32_e32 v0, 4, v130
	v_lshl_add_u32 v0, v131, 2, v0
	v_xor_b32_e32 v0, v0, v130
	v_and_b32_e32 v0, 7, v0
	v_lshlrev_b32_e32 v133, 4, v0
	v_lshl_add_u32 v232, v132, 11, v133
	v_add_u32_e32 v233, 0x20000, v232
	v_add_u32_e32 v234, 0x40000, v232
	v_add_u32_e32 v235, 0x60000, v232
	v_and_b32_e32 v0, 31, v132
	v_lshrrev_b32_e32 v130, 5, v132
	v_lshl_add_u32 v0, v130, 6, v0
	v_lshl_add_u32 v236, v0, 11, v133
	v_add_u32_e32 v237, 0x10000, v236
	v_add_u32_e32 v238, 0x40000, v236
	v_add_u32_e32 v239, 0x50000, v236
	v_and_b32_e32 v132, 31, v204
	v_lshrrev_b32_e32 v0, 2, v131
	v_lshl_add_u32 v0, v0, 6, v132
	v_lshlrev_b32_e32 v244, 7, v0
	v_and_b32_e32 v0, 3, v131
	v_lshl_add_u32 v0, v0, 5, v132
	v_lshlrev_b32_e32 v245, 7, v0
	v_bfe_u32 v0, v204, 5, 1
	v_bfe_u32 v130, v132, 1, 3
	v_or_b32_e32 v133, 0, v0
	v_xor_b32_e32 v133, v133, v130
	v_lshlrev_b32_e32 v240, 4, v133
	v_or_b32_e32 v133, 2, v0
	v_xor_b32_e32 v133, v133, v130
	v_lshlrev_b32_e32 v241, 4, v133
	v_or_b32_e32 v133, 4, v0
	v_xor_b32_e32 v133, v133, v130
	v_lshlrev_b32_e32 v242, 4, v133
	v_or_b32_e32 v133, 6, v0
	v_xor_b32_e32 v133, v133, v130
	v_lshlrev_b32_e32 v243, 4, v133
	v_lshlrev_b32_e32 v131, 10, v131
	s_nop 0
	v_readfirstlane_b32 s100, v131
	v_mov_b32_e32 v146, 0
	v_mov_b32_e32 v147, 0
	v_mov_b32_e32 v148, 0
	v_mov_b32_e32 v149, 0
	v_lshlrev_b32_e32 v130, 4, v204
	v_add_u32_e32 v132, 0x10000, v130
	s_mov_b64 exec, -1
	s_mov_b32 s11, 0
	s_mov_b32 s10, 0x10000
	s_waitcnt lgkmcnt(0)
	s_add_u32 m0, s100, 0x8000
	s_nop 0
	global_load_lds_dwordx4 v236, s[8:9]
	v_add_u32_e32 v236, 0x80, v236
	s_add_u32 m0, s100, 0xa000
	s_nop 0
	global_load_lds_dwordx4 v238, s[8:9]
	v_add_u32_e32 v238, 0x80, v238
	s_add_u32 m0, s100, 0x0
	s_nop 0
	global_load_lds_dwordx4 v232, s[6:7]
	v_add_u32_e32 v232, 0x80, v232
	s_add_u32 m0, s100, 0x2000
	s_nop 0
	global_load_lds_dwordx4 v234, s[6:7]
	v_add_u32_e32 v234, 0x80, v234
	s_add_u32 m0, s100, 0xc000
	s_nop 0
	global_load_lds_dwordx4 v237, s[8:9]
	v_add_u32_e32 v237, 0x80, v237
	s_add_u32 m0, s100, 0xe000
	s_nop 0
	global_load_lds_dwordx4 v239, s[8:9]
	v_add_u32_e32 v239, 0x80, v239
	s_add_u32 m0, s100, 0x4000
	s_nop 0
	global_load_lds_dwordx4 v233, s[6:7]
	v_add_u32_e32 v233, 0x80, v233
	s_add_u32 m0, s100, 0x6000
	s_nop 0
	global_load_lds_dwordx4 v235, s[6:7]
	v_add_u32_e32 v235, 0x80, v235
	s_cmp_eq_u32 s101, 1
	s_cbranch_scc0 .Lg8_qb_p0
	s_barrier

; #define MFMA(a, b, c) __builtin_amdgcn_mfma_f32_32x32x16_bf16((a), (b), (c), 0, 0, 0)
; template <bool SWAP>
; DI void gemm_mainloop(f32x16 (&acc)[4][2], const u16* __restrict__ A, int lda, int rlo, int rhi,
;                       const u16* __restrict__ B, int ldb, int K, char* lds, const u16* zero_line) {
;     ...
;   auto ldfrag = [&](const char* st, int ks, int buf) {
;     const int co = ((2 * ks + h) ^ sw) << 4;
; #pragma unroll
;     for (int mi = 0; mi < 4; ++mi) fa[buf][mi] = *(const bf16x8*)(st + arow_off + mi * 4096 + co);
; #pragma unroll
;     for (int ni = 0; ni < 2; ++ni) fb[buf][ni] = *(const bf16x8*)(st + brow_off + ni * 4096 + co);
;   };
;   auto mma = [&](int buf) {
; #pragma unroll
;     for (int mi = 0; mi < 4; ++mi)
; #pragma unroll
;       for (int ni = 0; ni < 2; ++ni)
;         acc[mi][ni] = SWAP ? MFMA(fb[buf][ni], fa[buf][mi], acc[mi][ni]) : MFMA(fa[buf][mi], fb[buf][ni], acc[mi][ni]);
;   };
;   auto pat_rd = [&]() {
; #pragma unroll
;     for (int g = 0; g < 6; ++g) {
;       __builtin_amdgcn_sched_group_barrier(0x100, 1, 0);
;       __builtin_amdgcn_sched_group_barrier(0x008, 1, 0);
;     }
;     __builtin_amdgcn_sched_group_barrier(0x008, 2, 0);
;   };
; #pragma unroll 2
;   for (int kt = 0; kt < nk; ++kt) {
;     const char* st = lds + (kt & 1) * 65536;
;     ldfrag(st, 0, 0);
;     mma(1);
;     pat_rd();
;     if (kt + 1 < nk) glds(kt + 1, (kt + 1) & 1);
;     ldfrag(st, 1, 1);
;     mma(0);
;     pat_rd();
;     ldfrag(st, 2, 0);
;     mma(1);
;     pat_rd();
;     ldfrag(st, 3, 1);
;     mma(0);
;     pat_rd();
;     asm volatile("s_waitcnt vmcnt(0)" ::: "memory");
;     __syncthreads();
;   }
.Lg8_qb:
	v_add3_u32 v246, v245, v240, 0
	v_add3_u32 v247, v245, v241, 0
	v_add3_u32 v248, v245, v242, 0
	v_add3_u32 v249, v245, v243, 0
	ds_read_b128 v[170:173], v246 offset:32768
	ds_read_b128 v[174:177], v247 offset:32768
	ds_read_b128 v[178:181], v248 offset:32768
	ds_read_b128 v[186:189], v249 offset:32768
	v_add3_u32 v246, v244, v240, 0
	v_add3_u32 v247, v244, v241, 0
	v_add3_u32 v248, v244, v242, 0
	v_add3_u32 v249, v244, v243, 0
	ds_read_b128 v[130:133], v246
	ds_read_b128 v[134:137], v247
	ds_read_b128 v[138:141], v248
	ds_read_b128 v[142:145], v249
	ds_read_b128 v[146:149], v246 offset:4096
	ds_read_b128 v[150:153], v247 offset:4096
	ds_read_b128 v[156:159], v248 offset:4096
	ds_read_b128 v[160:163], v249 offset:4096
	s_add_u32 m0, s100, 0x14000
	s_nop 0
	global_load_lds_dwordx4 v233, s[6:7]
	v_add_u32_e32 v233, 0x80, v233
	s_add_u32 m0, s100, 0x16000
	s_nop 0
	global_load_lds_dwordx4 v235, s[6:7]
	v_add_u32_e32 v235, 0x80, v235
	s_waitcnt lgkmcnt(8)
	s_barrier
	s_waitcnt lgkmcnt(0)
	v_mfma_f32_32x32x16_bf16 v[114:129], v[170:173], v[130:133], v[114:129]
	v_mfma_f32_32x32x16_bf16 v[82:97], v[170:173], v[146:149], v[82:97]
	v_mfma_f32_32x32x16_bf16 v[114:129], v[174:177], v[134:137], v[114:129]
	v_mfma_f32_32x32x16_bf16 v[82:97], v[174:177], v[150:153], v[82:97]
	v_mfma_f32_32x32x16_bf16 v[114:129], v[178:181], v[138:141], v[114:129]
	v_mfma_f32_32x32x16_bf16 v[82:97], v[178:181], v[156:159], v[82:97]
	v_mfma_f32_32x32x16_bf16 v[114:129], v[186:189], v[142:145], v[114:129]
	v_mfma_f32_32x32x16_bf16 v[82:97], v[186:189], v[160:163], v[82:97]
	s_barrier
	v_add3_u32 v246, v245, v240, 0
	v_add3_u32 v247, v245, v241, 0
	v_add3_u32 v248, v245, v242, 0
	v_add3_u32 v249, v245, v243, 0
	ds_read_b128 v[190:193], v246 offset:49152
	ds_read_b128 v[194:197], v247 offset:49152
	ds_read_b128 v[198:201], v248 offset:49152
	ds_read_b128 v[228:231], v249 offset:49152
	s_add_u32 m0, s100, 0x8000
	s_nop 0
	global_load_lds_dwordx4 v236, s[8:9]
	v_add_u32_e32 v236, 0x80, v236
	s_add_u32 m0, s100, 0xa000
	s_nop 0
	global_load_lds_dwordx4 v238, s[8:9]
	v_add_u32_e32 v238, 0x80, v238
	s_barrier
	s_waitcnt lgkmcnt(0)
	v_mfma_f32_32x32x16_bf16 v[98:113], v[190:193], v[130:133], v[98:113]
	v_mfma_f32_32x32x16_bf16 v[66:81], v[190:193], v[146:149], v[66:81]
	v_mfma_f32_32x32x16_bf16 v[98:113], v[194:197], v[134:137], v[98:113]
	v_mfma_f32_32x32x16_bf16 v[66:81], v[194:197], v[150:153], v[66:81]
	v_mfma_f32_32x32x16_bf16 v[98:113], v[198:201], v[138:141], v[98:113]
	v_mfma_f32_32x32x16_bf16 v[66:81], v[198:201], v[156:159], v[66:81]
	v_mfma_f32_32x32x16_bf16 v[98:113], v[228:231], v[142:145], v[98:113]
	v_mfma_f32_32x32x16_bf16 v[66:81], v[228:231], v[160:163], v[66:81]
	s_barrier
	v_add3_u32 v246, v244, v240, 0
	v_add3_u32 v247, v244, v241, 0
	v_add3_u32 v248, v244, v242, 0
	v_add3_u32 v249, v244, v243, 0
	ds_read_b128 v[130:133], v246 offset:16384
	ds_read_b128 v[134:137], v247 offset:16384
	ds_read_b128 v[138:141], v248 offset:16384
	ds_read_b128 v[142:145], v249 offset:16384
	ds_read_b128 v[146:149], v246 offset:20480
	ds_read_b128 v[150:153], v247 offset:20480
	ds_read_b128 v[156:159], v248 offset:20480
	ds_read_b128 v[160:163], v249 offset:20480
	s_add_u32 m0, s100, 0x0
	s_nop 0
	global_load_lds_dwordx4 v232, s[6:7]
	v_add_u32_e32 v232, 0x80, v232
	s_add_u32 m0, s100, 0x2000
	s_nop 0
	global_load_lds_dwordx4 v234, s[6:7]
	v_add_u32_e32 v234, 0x80, v234
	s_barrier
	s_waitcnt lgkmcnt(0)
	v_mfma_f32_32x32x16_bf16 v[50:65], v[170:173], v[130:133], v[50:65]
	v_mfma_f32_32x32x16_bf16 v[18:33], v[170:173], v[146:149], v[18:33]
	v_mfma_f32_32x32x16_bf16 v[50:65], v[174:177], v[134:137], v[50:65]
	v_mfma_f32_32x32x16_bf16 v[18:33], v[174:177], v[150:153], v[18:33]
	v_mfma_f32_32x32x16_bf16 v[50:65], v[178:181], v[138:141], v[50:65]
	v_mfma_f32_32x32x16_bf16 v[18:33], v[178:181], v[156:159], v[18:33]
	v_mfma_f32_32x32x16_bf16 v[50:65], v[186:189], v[142:145], v[50:65]
	v_mfma_f32_32x32x16_bf16 v[18:33], v[186:189], v[160:163], v[18:33]
	s_barrier
	s_add_u32 m0, s100, 0xc000
	s_nop 0
	global_load_lds_dwordx4 v237, s[8:9]
	v_add_u32_e32 v237, 0x80, v237
	s_add_u32 m0, s100, 0xe000
	s_nop 0
	global_load_lds_dwordx4 v239, s[8:9]
	v_add_u32_e32 v239, 0x80, v239
	s_waitcnt vmcnt(6)
	s_barrier
	v_mfma_f32_32x32x16_bf16 v[34:49], v[190:193], v[130:133], v[34:49]
	v_mfma_f32_32x32x16_bf16 v[2:17], v[190:193], v[146:149], v[2:17]
	v_mfma_f32_32x32x16_bf16 v[34:49], v[194:197], v[134:137], v[34:49]
	v_mfma_f32_32x32x16_bf16 v[2:17], v[194:197], v[150:153], v[2:17]
	v_mfma_f32_32x32x16_bf16 v[34:49], v[198:201], v[138:141], v[34:49]
	v_mfma_f32_32x32x16_bf16 v[2:17], v[198:201], v[156:159], v[2:17]
	v_mfma_f32_32x32x16_bf16 v[34:49], v[228:231], v[142:145], v[34:49]
	v_mfma_f32_32x32x16_bf16 v[2:17], v[228:231], v[160:163], v[2:17]
	s_barrier
	v_add3_u32 v246, v245, v240, s10
	v_add3_u32 v247, v245, v241, s10
	v_add3_u32 v248, v245, v242, s10
	v_add3_u32 v249, v245, v243, s10
	ds_read_b128 v[170:173], v246 offset:32768
	ds_read_b128 v[174:177], v247 offset:32768
	ds_read_b128 v[178:181], v248 offset:32768
	ds_read_b128 v[186:189], v249 offset:32768
	v_add3_u32 v246, v244, v240, s10
	v_add3_u32 v247, v244, v241, s10
	v_add3_u32 v248, v244, v242, s10
	v_add3_u32 v249, v244, v243, s10
	ds_read_b128 v[130:133], v246
	ds_read_b128 v[134:137], v247
	ds_read_b128 v[138:141], v248
	ds_read_b128 v[142:145], v249
	ds_read_b128 v[146:149], v246 offset:4096
	ds_read_b128 v[150:153], v247 offset:4096
	ds_read_b128 v[156:159], v248 offset:4096
	ds_read_b128 v[160:163], v249 offset:4096
	s_add_u32 m0, s100, 0x4000
	s_nop 0
	global_load_lds_dwordx4 v233, s[6:7]
	v_add_u32_e32 v233, 0x80, v233
	s_add_u32 m0, s100, 0x6000
	s_nop 0
	global_load_lds_dwordx4 v235, s[6:7]
	v_add_u32_e32 v235, 0x80, v235
	s_waitcnt lgkmcnt(8)
	s_barrier
; #define MFMA(a, b, c) __builtin_amdgcn_mfma_f32_32x32x16_bf16((a), (b), (c), 0, 0, 0)
; template <bool SWAP>
; DI void gemm_mainloop(f32x16 (&acc)[4][2], const u16* __restrict__ A, int lda, int rlo, int rhi,
;                       const u16* __restrict__ B, int ldb, int K, char* lds, const u16* zero_line) {
;     ...
;   auto ldfrag = [&](const char* st, int ks, int buf) {
;     const int co = ((2 * ks + h) ^ sw) << 4;
; #pragma unroll
;     for (int mi = 0; mi < 4; ++mi) fa[buf][mi] = *(const bf16x8*)(st + arow_off + mi * 4096 + co);
; #pragma unroll
;     for (int ni = 0; ni < 2; ++ni) fb[buf][ni] = *(const bf16x8*)(st + brow_off + ni * 4096 + co);
;   };
;   auto mma = [&](int buf) {
; #pragma unroll
;     for (int mi = 0; mi < 4; ++mi)
; #pragma unroll
;       for (int ni = 0; ni < 2; ++ni)
;         acc[mi][ni] = SWAP ? MFMA(fb[buf][ni], fa[buf][mi], acc[mi][ni]) : MFMA(fa[buf][mi], fb[buf][ni], acc[mi][ni]);
;   };
;   auto pat_rd = [&]() {
; #pragma unroll
;     for (int g = 0; g < 6; ++g) {
;       __builtin_amdgcn_sched_group_barrier(0x100, 1, 0);
;       __builtin_amdgcn_sched_group_barrier(0x008, 1, 0);
;     }
;     __builtin_amdgcn_sched_group_barrier(0x008, 2, 0);
;   };
; #pragma unroll 2
;   for (int kt = 0; kt < nk; ++kt) {
;     const char* st = lds + (kt & 1) * 65536;
;     ldfrag(st, 0, 0);
;     mma(1);
;     pat_rd();
;     if (kt + 1 < nk) glds(kt + 1, (kt + 1) & 1);
;     ldfrag(st, 1, 1);
;     mma(0);
;     pat_rd();
;     ldfrag(st, 2, 0);
;     mma(1);
;     pat_rd();
;     ldfrag(st, 3, 1);
;     mma(0);
;     pat_rd();
;     asm volatile("s_waitcnt vmcnt(0)" ::: "memory");
;     __syncthreads();
;   }
;   mma(1);
	s_waitcnt lgkmcnt(0)
	v_mfma_f32_32x32x16_bf16 v[114:129], v[170:173], v[130:133], v[114:129]
	v_mfma_f32_32x32x16_bf16 v[82:97], v[170:173], v[146:149], v[82:97]
	v_mfma_f32_32x32x16_bf16 v[114:129], v[174:177], v[134:137], v[114:129]
	v_mfma_f32_32x32x16_bf16 v[82:97], v[174:177], v[150:153], v[82:97]
	v_mfma_f32_32x32x16_bf16 v[114:129], v[178:181], v[138:141], v[114:129]
	v_mfma_f32_32x32x16_bf16 v[82:97], v[178:181], v[156:159], v[82:97]
	v_mfma_f32_32x32x16_bf16 v[114:129], v[186:189], v[142:145], v[114:129]
	v_mfma_f32_32x32x16_bf16 v[82:97], v[186:189], v[160:163], v[82:97]
	s_barrier
	v_add3_u32 v246, v245, v240, s10
	v_add3_u32 v247, v245, v241, s10
	v_add3_u32 v248, v245, v242, s10
	v_add3_u32 v249, v245, v243, s10
	ds_read_b128 v[190:193], v246 offset:49152
	ds_read_b128 v[194:197], v247 offset:49152
	ds_read_b128 v[198:201], v248 offset:49152
	ds_read_b128 v[228:231], v249 offset:49152
	s_add_u32 m0, s100, 0x18000
	s_nop 0
	global_load_lds_dwordx4 v236, s[8:9]
	v_add_u32_e32 v236, 0x80, v236
	s_add_u32 m0, s100, 0x1a000
	s_nop 0
	global_load_lds_dwordx4 v238, s[8:9]
	v_add_u32_e32 v238, 0x80, v238
	s_barrier
	s_waitcnt lgkmcnt(0)
	v_mfma_f32_32x32x16_bf16 v[98:113], v[190:193], v[130:133], v[98:113]
	v_mfma_f32_32x32x16_bf16 v[66:81], v[190:193], v[146:149], v[66:81]
	v_mfma_f32_32x32x16_bf16 v[98:113], v[194:197], v[134:137], v[98:113]
	v_mfma_f32_32x32x16_bf16 v[66:81], v[194:197], v[150:153], v[66:81]
	v_mfma_f32_32x32x16_bf16 v[98:113], v[198:201], v[138:141], v[98:113]
	v_mfma_f32_32x32x16_bf16 v[66:81], v[198:201], v[156:159], v[66:81]
	v_mfma_f32_32x32x16_bf16 v[98:113], v[228:231], v[142:145], v[98:113]
	v_mfma_f32_32x32x16_bf16 v[66:81], v[228:231], v[160:163], v[66:81]
	s_barrier
	v_add3_u32 v246, v244, v240, s10
	v_add3_u32 v247, v244, v241, s10
	v_add3_u32 v248, v244, v242, s10
	v_add3_u32 v249, v244, v243, s10
	ds_read_b128 v[130:133], v246 offset:16384
	ds_read_b128 v[134:137], v247 offset:16384
	ds_read_b128 v[138:141], v248 offset:16384
	ds_read_b128 v[142:145], v249 offset:16384
	ds_read_b128 v[146:149], v246 offset:20480
	ds_read_b128 v[150:153], v247 offset:20480
	ds_read_b128 v[156:159], v248 offset:20480
	ds_read_b128 v[160:163], v249 offset:20480
	s_add_u32 m0, s100, 0x10000
	s_nop 0
	global_load_lds_dwordx4 v232, s[6:7]
	v_add_u32_e32 v232, 0x80, v232
	s_add_u32 m0, s100, 0x12000
	s_nop 0
	global_load_lds_dwordx4 v234, s[6:7]
	v_add_u32_e32 v234, 0x80, v234
	s_barrier
	s_waitcnt lgkmcnt(0)
	v_mfma_f32_32x32x16_bf16 v[50:65], v[170:173], v[130:133], v[50:65]
	v_mfma_f32_32x32x16_bf16 v[18:33], v[170:173], v[146:149], v[18:33]
	v_mfma_f32_32x32x16_bf16 v[50:65], v[174:177], v[134:137], v[50:65]
	v_mfma_f32_32x32x16_bf16 v[18:33], v[174:177], v[150:153], v[18:33]
	v_mfma_f32_32x32x16_bf16 v[50:65], v[178:181], v[138:141], v[50:65]
	v_mfma_f32_32x32x16_bf16 v[18:33], v[178:181], v[156:159], v[18:33]
	v_mfma_f32_32x32x16_bf16 v[50:65], v[186:189], v[142:145], v[50:65]
	v_mfma_f32_32x32x16_bf16 v[18:33], v[186:189], v[160:163], v[18:33]
	s_barrier
	s_add_u32 m0, s100, 0x1c000
	s_nop 0
	global_load_lds_dwordx4 v237, s[8:9]
	v_add_u32_e32 v237, 0x80, v237
	s_add_u32 m0, s100, 0x1e000
	s_nop 0
	global_load_lds_dwordx4 v239, s[8:9]
	v_add_u32_e32 v239, 0x80, v239
	s_waitcnt vmcnt(6)
	s_barrier
	v_mfma_f32_32x32x16_bf16 v[34:49], v[190:193], v[130:133], v[34:49]
	v_mfma_f32_32x32x16_bf16 v[2:17], v[190:193], v[146:149], v[2:17]
	v_mfma_f32_32x32x16_bf16 v[34:49], v[194:197], v[134:137], v[34:49]
	v_mfma_f32_32x32x16_bf16 v[2:17], v[194:197], v[150:153], v[2:17]
	v_mfma_f32_32x32x16_bf16 v[34:49], v[198:201], v[138:141], v[34:49]
	v_mfma_f32_32x32x16_bf16 v[2:17], v[198:201], v[156:159], v[2:17]
	v_mfma_f32_32x32x16_bf16 v[34:49], v[228:231], v[142:145], v[34:49]
	v_mfma_f32_32x32x16_bf16 v[2:17], v[228:231], v[160:163], v[2:17]
	s_barrier
	s_add_i32 s11, s11, 2
	s_cmp_lt_u32 s11, 14
	s_cbranch_scc1 .Lg8_qb
	v_add3_u32 v246, v245, v240, 0
	v_add3_u32 v247, v245, v241, 0
	v_add3_u32 v248, v245, v242, 0
	v_add3_u32 v249, v245, v243, 0
	ds_read_b128 v[170:173], v246 offset:32768
	ds_read_b128 v[174:177], v247 offset:32768
	ds_read_b128 v[178:181], v248 offset:32768
	ds_read_b128 v[186:189], v249 offset:32768
	v_add3_u32 v246, v244, v240, 0
	v_add3_u32 v247, v244, v241, 0
	v_add3_u32 v248, v244, v242, 0
	v_add3_u32 v249, v244, v243, 0
	ds_read_b128 v[130:133], v246
	ds_read_b128 v[134:137], v247
	ds_read_b128 v[138:141], v248
	ds_read_b128 v[142:145], v249
	ds_read_b128 v[146:149], v246 offset:4096
	ds_read_b128 v[150:153], v247 offset:4096
	ds_read_b128 v[156:159], v248 offset:4096
	ds_read_b128 v[160:163], v249 offset:4096
	s_add_u32 m0, s100, 0x14000
	s_nop 0
	global_load_lds_dwordx4 v233, s[6:7]
	v_add_u32_e32 v233, 0x80, v233
	s_add_u32 m0, s100, 0x16000
	s_nop 0
	global_load_lds_dwordx4 v235, s[6:7]
	v_add_u32_e32 v235, 0x80, v235
	s_barrier
	s_waitcnt lgkmcnt(0)
	v_mfma_f32_32x32x16_bf16 v[114:129], v[170:173], v[130:133], v[114:129]
	v_mfma_f32_32x32x16_bf16 v[82:97], v[170:173], v[146:149], v[82:97]
	v_mfma_f32_32x32x16_bf16 v[114:129], v[174:177], v[134:137], v[114:129]
	v_mfma_f32_32x32x16_bf16 v[82:97], v[174:177], v[150:153], v[82:97]
	v_mfma_f32_32x32x16_bf16 v[114:129], v[178:181], v[138:141], v[114:129]
	v_mfma_f32_32x32x16_bf16 v[82:97], v[178:181], v[156:159], v[82:97]
	v_mfma_f32_32x32x16_bf16 v[114:129], v[186:189], v[142:145], v[114:129]
	v_mfma_f32_32x32x16_bf16 v[82:97], v[186:189], v[160:163], v[82:97]
	s_barrier
	v_add3_u32 v246, v245, v240, 0
	v_add3_u32 v247, v245, v241, 0
	v_add3_u32 v248, v245, v242, 0
	v_add3_u32 v249, v245, v243, 0
	ds_read_b128 v[190:193], v246 offset:49152
	ds_read_b128 v[194:197], v247 offset:49152
	ds_read_b128 v[198:201], v248 offset:49152
	ds_read_b128 v[228:231], v249 offset:49152
	s_barrier
; #define MFMA(a, b, c) __builtin_amdgcn_mfma_f32_32x32x16_bf16((a), (b), (c), 0, 0, 0)
; template <bool SWAP>
; DI void gemm_mainloop(f32x16 (&acc)[4][2], const u16* __restrict__ A, int lda, int rlo, int rhi,
;                       const u16* __restrict__ B, int ldb, int K, char* lds, const u16* zero_line) {
;     ...
;   auto ldfrag = [&](const char* st, int ks, int buf) {
;     const int co = ((2 * ks + h) ^ sw) << 4;
; #pragma unroll
;     for (int mi = 0; mi < 4; ++mi) fa[buf][mi] = *(const bf16x8*)(st + arow_off + mi * 4096 + co);
; #pragma unroll
;     for (int ni = 0; ni < 2; ++ni) fb[buf][ni] = *(const bf16x8*)(st + brow_off + ni * 4096 + co);
;   };
;   auto mma = [&](int buf) {
; #pragma unroll
;     for (int mi = 0; mi < 4; ++mi)
; #pragma unroll
;       for (int ni = 0; ni < 2; ++ni)
;         acc[mi][ni] = SWAP ? MFMA(fb[buf][ni], fa[buf][mi], acc[mi][ni]) : MFMA(fa[buf][mi], fb[buf][ni], acc[mi][ni]);
;   };
;   auto pat_rd = [&]() {
; #pragma unroll
;     for (int g = 0; g < 6; ++g) {
;       __builtin_amdgcn_sched_group_barrier(0x100, 1, 0);
;       __builtin_amdgcn_sched_group_barrier(0x008, 1, 0);
;     }
;     __builtin_amdgcn_sched_group_barrier(0x008, 2, 0);
;   };
; #pragma unroll 2
;   for (int kt = 0; kt < nk; ++kt) {
;     const char* st = lds + (kt & 1) * 65536;
;     ldfrag(st, 0, 0);
;     mma(1);
;     pat_rd();
;     if (kt + 1 < nk) glds(kt + 1, (kt + 1) & 1);
;     ldfrag(st, 1, 1);
;     mma(0);
;     pat_rd();
;     ldfrag(st, 2, 0);
;     mma(1);
;     pat_rd();
;     ldfrag(st, 3, 1);
;     mma(0);
;     pat_rd();
;     asm volatile("s_waitcnt vmcnt(0)" ::: "memory");
;     __syncthreads();
;   }
;   mma(1);
	s_waitcnt lgkmcnt(0)
	v_mfma_f32_32x32x16_bf16 v[98:113], v[190:193], v[130:133], v[98:113]
	v_mfma_f32_32x32x16_bf16 v[66:81], v[190:193], v[146:149], v[66:81]
	v_mfma_f32_32x32x16_bf16 v[98:113], v[194:197], v[134:137], v[98:113]
	v_mfma_f32_32x32x16_bf16 v[66:81], v[194:197], v[150:153], v[66:81]
	v_mfma_f32_32x32x16_bf16 v[98:113], v[198:201], v[138:141], v[98:113]
	v_mfma_f32_32x32x16_bf16 v[66:81], v[198:201], v[156:159], v[66:81]
	v_mfma_f32_32x32x16_bf16 v[98:113], v[228:231], v[142:145], v[98:113]
	v_mfma_f32_32x32x16_bf16 v[66:81], v[228:231], v[160:163], v[66:81]
	s_barrier
	v_add3_u32 v246, v244, v240, 0
	v_add3_u32 v247, v244, v241, 0
	v_add3_u32 v248, v244, v242, 0
	v_add3_u32 v249, v244, v243, 0
	ds_read_b128 v[130:133], v246 offset:16384
	ds_read_b128 v[134:137], v247 offset:16384
	ds_read_b128 v[138:141], v248 offset:16384
	ds_read_b128 v[142:145], v249 offset:16384
	ds_read_b128 v[146:149], v246 offset:20480
	ds_read_b128 v[150:153], v247 offset:20480
	ds_read_b128 v[156:159], v248 offset:20480
	ds_read_b128 v[160:163], v249 offset:20480
	s_waitcnt vmcnt(4)
	s_barrier
	s_waitcnt lgkmcnt(0)
	v_mfma_f32_32x32x16_bf16 v[50:65], v[170:173], v[130:133], v[50:65]
	v_mfma_f32_32x32x16_bf16 v[18:33], v[170:173], v[146:149], v[18:33]
	v_mfma_f32_32x32x16_bf16 v[50:65], v[174:177], v[134:137], v[50:65]
	v_mfma_f32_32x32x16_bf16 v[18:33], v[174:177], v[150:153], v[18:33]
	v_mfma_f32_32x32x16_bf16 v[50:65], v[178:181], v[138:141], v[50:65]
	v_mfma_f32_32x32x16_bf16 v[18:33], v[178:181], v[156:159], v[18:33]
	v_mfma_f32_32x32x16_bf16 v[50:65], v[186:189], v[142:145], v[50:65]
	v_mfma_f32_32x32x16_bf16 v[18:33], v[186:189], v[160:163], v[18:33]
	v_mfma_f32_32x32x16_bf16 v[34:49], v[190:193], v[130:133], v[34:49]
	v_mfma_f32_32x32x16_bf16 v[2:17], v[190:193], v[146:149], v[2:17]
	v_mfma_f32_32x32x16_bf16 v[34:49], v[194:197], v[134:137], v[34:49]
	v_mfma_f32_32x32x16_bf16 v[2:17], v[194:197], v[150:153], v[2:17]
	v_mfma_f32_32x32x16_bf16 v[34:49], v[198:201], v[138:141], v[34:49]
	v_mfma_f32_32x32x16_bf16 v[2:17], v[198:201], v[156:159], v[2:17]
	v_mfma_f32_32x32x16_bf16 v[34:49], v[228:231], v[142:145], v[34:49]
	v_mfma_f32_32x32x16_bf16 v[2:17], v[228:231], v[160:163], v[2:17]
	s_barrier
	v_add3_u32 v246, v245, v240, s10
	v_add3_u32 v247, v245, v241, s10
	v_add3_u32 v248, v245, v242, s10
	v_add3_u32 v249, v245, v243, s10
	ds_read_b128 v[170:173], v246 offset:32768
	ds_read_b128 v[174:177], v247 offset:32768
	ds_read_b128 v[178:181], v248 offset:32768
	ds_read_b128 v[186:189], v249 offset:32768
	v_add3_u32 v246, v244, v240, s10
	v_add3_u32 v247, v244, v241, s10
	v_add3_u32 v248, v244, v242, s10
	v_add3_u32 v249, v244, v243, s10
	ds_read_b128 v[130:133], v246
	ds_read_b128 v[134:137], v247
	ds_read_b128 v[138:141], v248
	ds_read_b128 v[142:145], v249
	ds_read_b128 v[146:149], v246 offset:4096
	ds_read_b128 v[150:153], v247 offset:4096
	ds_read_b128 v[156:159], v248 offset:4096
	ds_read_b128 v[160:163], v249 offset:4096
	s_waitcnt vmcnt(2)
	s_barrier
	s_waitcnt lgkmcnt(0)
	v_mfma_f32_32x32x16_bf16 v[114:129], v[170:173], v[130:133], v[114:129]
	v_mfma_f32_32x32x16_bf16 v[82:97], v[170:173], v[146:149], v[82:97]
	v_mfma_f32_32x32x16_bf16 v[114:129], v[174:177], v[134:137], v[114:129]
	v_mfma_f32_32x32x16_bf16 v[82:97], v[174:177], v[150:153], v[82:97]
	v_mfma_f32_32x32x16_bf16 v[114:129], v[178:181], v[138:141], v[114:129]
	v_mfma_f32_32x32x16_bf16 v[82:97], v[178:181], v[156:159], v[82:97]
	v_mfma_f32_32x32x16_bf16 v[114:129], v[186:189], v[142:145], v[114:129]
	v_mfma_f32_32x32x16_bf16 v[82:97], v[186:189], v[160:163], v[82:97]
	s_barrier
	v_add3_u32 v246, v245, v240, s10
	v_add3_u32 v247, v245, v241, s10
	v_add3_u32 v248, v245, v242, s10
	v_add3_u32 v249, v245, v243, s10
	ds_read_b128 v[190:193], v246 offset:49152
	ds_read_b128 v[194:197], v247 offset:49152
	ds_read_b128 v[198:201], v248 offset:49152
	ds_read_b128 v[228:231], v249 offset:49152
	s_waitcnt vmcnt(0)
	s_barrier
	s_waitcnt lgkmcnt(0)
	v_mfma_f32_32x32x16_bf16 v[98:113], v[190:193], v[130:133], v[98:113]
	v_mfma_f32_32x32x16_bf16 v[66:81], v[190:193], v[146:149], v[66:81]
	v_mfma_f32_32x32x16_bf16 v[98:113], v[194:197], v[134:137], v[98:113]
	v_mfma_f32_32x32x16_bf16 v[66:81], v[194:197], v[150:153], v[66:81]
	v_mfma_f32_32x32x16_bf16 v[98:113], v[198:201], v[138:141], v[98:113]
	v_mfma_f32_32x32x16_bf16 v[66:81], v[198:201], v[156:159], v[66:81]
	v_mfma_f32_32x32x16_bf16 v[98:113], v[228:231], v[142:145], v[98:113]
	v_mfma_f32_32x32x16_bf16 v[66:81], v[228:231], v[160:163], v[66:81]
	s_barrier
	v_add3_u32 v246, v244, v240, s10
	v_add3_u32 v247, v244, v241, s10
	v_add3_u32 v248, v244, v242, s10
	v_add3_u32 v249, v244, v243, s10
	ds_read_b128 v[130:133], v246 offset:16384
	ds_read_b128 v[134:137], v247 offset:16384
	ds_read_b128 v[138:141], v248 offset:16384
	ds_read_b128 v[142:145], v249 offset:16384
	ds_read_b128 v[146:149], v246 offset:20480
	ds_read_b128 v[150:153], v247 offset:20480
	ds_read_b128 v[156:159], v248 offset:20480
	ds_read_b128 v[160:163], v249 offset:20480
	s_barrier
	s_waitcnt lgkmcnt(0)
	v_mfma_f32_32x32x16_bf16 v[50:65], v[170:173], v[130:133], v[50:65]
	v_mfma_f32_32x32x16_bf16 v[18:33], v[170:173], v[146:149], v[18:33]
	v_mfma_f32_32x32x16_bf16 v[50:65], v[174:177], v[134:137], v[50:65]
	v_mfma_f32_32x32x16_bf16 v[18:33], v[174:177], v[150:153], v[18:33]
	v_mfma_f32_32x32x16_bf16 v[50:65], v[178:181], v[138:141], v[50:65]
	v_mfma_f32_32x32x16_bf16 v[18:33], v[178:181], v[156:159], v[18:33]
	v_mfma_f32_32x32x16_bf16 v[50:65], v[186:189], v[142:145], v[50:65]
	v_mfma_f32_32x32x16_bf16 v[18:33], v[186:189], v[160:163], v[18:33]
	v_mfma_f32_32x32x16_bf16 v[34:49], v[190:193], v[130:133], v[34:49]
	v_mfma_f32_32x32x16_bf16 v[2:17], v[190:193], v[146:149], v[2:17]
	v_mfma_f32_32x32x16_bf16 v[34:49], v[194:197], v[134:137], v[34:49]
	v_mfma_f32_32x32x16_bf16 v[2:17], v[194:197], v[150:153], v[2:17]
	v_mfma_f32_32x32x16_bf16 v[34:49], v[198:201], v[138:141], v[34:49]
	v_mfma_f32_32x32x16_bf16 v[2:17], v[198:201], v[156:159], v[2:17]
	v_mfma_f32_32x32x16_bf16 v[34:49], v[228:231], v[142:145], v[34:49]
	v_mfma_f32_32x32x16_bf16 v[2:17], v[228:231], v[160:163], v[2:17]
	s_barrier
	s_cmp_eq_u32 s101, 0
	s_cbranch_scc0 .Lg8_qb_p1
	s_barrier

; template <int EPI>
; DI void phase_gemm(const Params& p, const GemmArgs& ga, char* lds) {
;     ...
;       } else {
; #pragma unroll
;         for (int ni = 0; ni < 2; ++ni) {
;           const int vrow = n0w - 2048 + ni * 32 + r;
;           u16* vb = VT + (size_t)1024 * tokbase + (size_t)vrow * S;
; #pragma unroll
;           for (int mi = 0; mi < 4; ++mi)
; #pragma unroll
;             for (int jp = 0; jp < 2; ++jp) {
;               const int pos = pos0 + wm * 128 + mi * 32 + 16 * jp + 8 * h;
;               u32x2 X = {pk_bf16(acc[mi][ni][8 * jp], acc[mi][ni][8 * jp + 1]), pk_bf16(acc[mi][ni][8 * jp + 2], acc[mi][ni][8 * jp + 3])};
;               u32x2 Y = {pk_bf16(acc[mi][ni][8 * jp + 4], acc[mi][ni][8 * jp + 5]), pk_bf16(acc[mi][ni][8 * jp + 6], acc[mi][ni][8 * jp + 7])};
;               half_swap(X, Y);
;               u32x4 v = {X.x, X.y, Y.x, Y.y};
;               *(u32x4*)(vb + pos) = v;
;             }
;         }
;       }
.LBB0_208:
.LBB0_209:
	v_or_b32_e32 v132, s14, v155
	s_andn2_b64 vcc, exec, s[16:17]
	s_mov_b64 s[6:7], -1
	s_cbranch_vccnz .LBB0_211
	s_cmpk_lt_i32 s30, 0x80
	s_movk_i32 s6, 0xc000
	s_cselect_b32 s6, s6, 0x7ffff800
	s_cselect_b32 s8, 14, 11
	s_and_b32 s6, s6, s12
	s_ashr_i32 s7, s6, 31
	v_add_u32_e32 v0, s12, v167
	v_add_u32_e32 v130, v132, v166
	v_subrev_u32_e32 v0, s6, v0
	s_lshl_b64 s[6:7], s[6:7], 11
	v_readlane_b32 s9, v253, 41
	v_or_b32_e32 v138, v0, v154
	v_ashrrev_i32_e32 v131, 31, v130
	s_add_u32 s6, s9, s6
	v_readlane_b32 s9, v253, 42
	s_addc_u32 s7, s9, s7
	v_lshlrev_b64 v[134:135], s8, v[130:131]
	v_ashrrev_i32_e32 v139, 31, v138
	v_lshl_add_u64 v[140:141], v[134:135], 1, s[6:7]
	v_cvt_pk_bf16_f32 v134, v114, v115
	v_cvt_pk_bf16_f32 v135, v116, v117
	v_cvt_pk_bf16_f32 v136, v118, v119
	v_cvt_pk_bf16_f32 v137, v120, v121
	v_lshlrev_b64 v[138:139], 1, v[138:139]
	v_permlane32_swap_b32_e32 v134, v136
	v_permlane32_swap_b32_e32 v135, v137
	v_lshl_add_u64 v[140:141], v[140:141], 0, v[138:139]
	global_store_dwordx4 v[140:141], v[134:137], off
	v_or_b32_e32 v130, 32, v130
	v_ashrrev_i32_e32 v131, 31, v130
	v_cvt_pk_bf16_f32 v134, v122, v123
	v_cvt_pk_bf16_f32 v135, v124, v125
	v_cvt_pk_bf16_f32 v136, v126, v127
	v_cvt_pk_bf16_f32 v137, v128, v129
	s_nop 0
	v_permlane32_swap_b32_e32 v134, v136
	v_permlane32_swap_b32_e32 v135, v137
	global_store_dwordx4 v[140:141], v[134:137], off offset:32
	v_lshlrev_b64 v[130:131], s8, v[130:131]
	v_lshl_add_u64 v[130:131], v[130:131], 1, s[6:7]
	v_cvt_pk_bf16_f32 v134, v82, v83
	v_cvt_pk_bf16_f32 v135, v84, v85
	v_cvt_pk_bf16_f32 v136, v86, v87
	v_cvt_pk_bf16_f32 v137, v88, v89
	s_nop 0
	v_permlane32_swap_b32_e32 v134, v136
	v_permlane32_swap_b32_e32 v135, v137
	global_store_dwordx4 v[140:141], v[134:137], off offset:64
	v_lshl_add_u64 v[130:131], v[130:131], 0, v[138:139]
	s_mov_b64 s[6:7], 0
	v_cvt_pk_bf16_f32 v134, v90, v91
	v_cvt_pk_bf16_f32 v135, v92, v93
	v_cvt_pk_bf16_f32 v136, v94, v95
	v_cvt_pk_bf16_f32 v137, v96, v97
	s_nop 0
	v_permlane32_swap_b32_e32 v134, v136
	v_permlane32_swap_b32_e32 v135, v137
	global_store_dwordx4 v[140:141], v[134:137], off offset:96
	s_nop 1
	v_cvt_pk_bf16_f32 v134, v50, v51
	v_cvt_pk_bf16_f32 v135, v52, v53
	v_cvt_pk_bf16_f32 v136, v54, v55
	v_cvt_pk_bf16_f32 v137, v56, v57
	s_nop 0
	v_permlane32_swap_b32_e32 v134, v136
	v_permlane32_swap_b32_e32 v135, v137
	global_store_dwordx4 v[140:141], v[134:137], off offset:128
	s_nop 1
	v_cvt_pk_bf16_f32 v134, v58, v59
	v_cvt_pk_bf16_f32 v135, v60, v61
	v_cvt_pk_bf16_f32 v136, v62, v63
	v_cvt_pk_bf16_f32 v137, v64, v65
	s_nop 0
	v_permlane32_swap_b32_e32 v134, v136
	v_permlane32_swap_b32_e32 v135, v137
	global_store_dwordx4 v[140:141], v[134:137], off offset:160
	s_nop 1
	v_cvt_pk_bf16_f32 v134, v18, v19
	v_cvt_pk_bf16_f32 v135, v20, v21
	v_cvt_pk_bf16_f32 v136, v22, v23
	v_cvt_pk_bf16_f32 v137, v24, v25
	s_nop 0
	v_permlane32_swap_b32_e32 v134, v136
	v_permlane32_swap_b32_e32 v135, v137
	global_store_dwordx4 v[140:141], v[134:137], off offset:192
	s_nop 1
	v_cvt_pk_bf16_f32 v134, v26, v27
	v_cvt_pk_bf16_f32 v135, v28, v29
	v_cvt_pk_bf16_f32 v136, v30, v31
	v_cvt_pk_bf16_f32 v137, v32, v33
	s_nop 0
	v_permlane32_swap_b32_e32 v134, v136
	v_permlane32_swap_b32_e32 v135, v137
	global_store_dwordx4 v[140:141], v[134:137], off offset:224
	s_nop 1
	v_cvt_pk_bf16_f32 v134, v98, v99
	v_cvt_pk_bf16_f32 v135, v100, v101
	v_cvt_pk_bf16_f32 v136, v102, v103
	v_cvt_pk_bf16_f32 v137, v104, v105
	s_nop 0
	v_permlane32_swap_b32_e32 v134, v136
	v_permlane32_swap_b32_e32 v135, v137
	global_store_dwordx4 v[130:131], v[134:137], off
	s_nop 1
	v_cvt_pk_bf16_f32 v134, v106, v107
	v_cvt_pk_bf16_f32 v135, v108, v109
	v_cvt_pk_bf16_f32 v136, v110, v111
	v_cvt_pk_bf16_f32 v137, v112, v113
	s_nop 0
	v_permlane32_swap_b32_e32 v134, v136
	v_permlane32_swap_b32_e32 v135, v137
	global_store_dwordx4 v[130:131], v[134:137], off offset:32
	s_nop 1
	v_cvt_pk_bf16_f32 v134, v66, v67
	v_cvt_pk_bf16_f32 v135, v68, v69
	v_cvt_pk_bf16_f32 v136, v70, v71
	v_cvt_pk_bf16_f32 v137, v72, v73
	s_nop 0
	v_permlane32_swap_b32_e32 v134, v136
	v_permlane32_swap_b32_e32 v135, v137
	global_store_dwordx4 v[130:131], v[134:137], off offset:64
	s_nop 1
	v_cvt_pk_bf16_f32 v134, v74, v75
	v_cvt_pk_bf16_f32 v135, v76, v77
	v_cvt_pk_bf16_f32 v136, v78, v79
	v_cvt_pk_bf16_f32 v137, v80, v81
	s_nop 0
	v_permlane32_swap_b32_e32 v134, v136
	v_permlane32_swap_b32_e32 v135, v137
	global_store_dwordx4 v[130:131], v[134:137], off offset:96
	s_nop 1
	v_cvt_pk_bf16_f32 v134, v34, v35
	v_cvt_pk_bf16_f32 v135, v36, v37
	v_cvt_pk_bf16_f32 v136, v38, v39
	v_cvt_pk_bf16_f32 v137, v40, v41
	s_nop 0
	v_permlane32_swap_b32_e32 v134, v136
	v_permlane32_swap_b32_e32 v135, v137
	global_store_dwordx4 v[130:131], v[134:137], off offset:128
	s_nop 1
	v_cvt_pk_bf16_f32 v134, v42, v43
	v_cvt_pk_bf16_f32 v135, v44, v45
	v_cvt_pk_bf16_f32 v136, v46, v47
	v_cvt_pk_bf16_f32 v137, v48, v49
	s_nop 0
	v_permlane32_swap_b32_e32 v134, v136
	v_permlane32_swap_b32_e32 v135, v137
	global_store_dwordx4 v[130:131], v[134:137], off offset:160
	s_nop 1
	v_cvt_pk_bf16_f32 v134, v2, v3
	v_cvt_pk_bf16_f32 v135, v4, v5
	v_cvt_pk_bf16_f32 v136, v6, v7
	v_cvt_pk_bf16_f32 v137, v8, v9
	s_nop 0
	v_permlane32_swap_b32_e32 v134, v136
	v_permlane32_swap_b32_e32 v135, v137
	global_store_dwordx4 v[130:131], v[134:137], off offset:192
	s_nop 1
	v_cvt_pk_bf16_f32 v134, v10, v11
	v_cvt_pk_bf16_f32 v135, v12, v13
	v_cvt_pk_bf16_f32 v136, v14, v15
	v_cvt_pk_bf16_f32 v137, v16, v17
	s_nop 0
	v_permlane32_swap_b32_e32 v134, v136
	v_permlane32_swap_b32_e32 v135, v137
	global_store_dwordx4 v[130:131], v[134:137], off offset:224

; template <bool SWAP>
; DI void gemm_mainloop(f32x16 (&acc)[4][2], const u16* __restrict__ A, int lda, int rlo, int rhi,
;                       const u16* __restrict__ B, int ldb, int K, char* lds, const u16* zero_line) {
;     ...
;   const int gch = (lc ^ ((lr >> 1) & 7)) * 8;
;   const u16* ap = A + (ptrdiff_t)lr * lda + gch;
;   const u16* bp = B + (ptrdiff_t)lr * ldb + gch;
;   const int nk = K >> 6;
;   typedef __attribute__((address_space(3))) unsigned lds_u32;
;   auto glds = [&](int kt, int st) {
;     char* as_ = lds + st * 65536 + tid * 16;
; #pragma unroll
;     for (int i = 0; i < 4; ++i) {
;       const int rr = lr + 64 * i;
;       const u16* srca = (rr >= rlo && rr < rhi) ? (ap + (ptrdiff_t)(64 * i) * lda + kt * 64) : (zero_line + lc * 8);
;       __builtin_amdgcn_global_load_lds((const unsigned*)srca, (lds_u32*)(as_ + i * 8192), 16, 0, 0);
;       __builtin_amdgcn_global_load_lds((const unsigned*)(bp + (ptrdiff_t)(64 * i) * ldb + kt * 64), (lds_u32*)(as_ + 32768 + i * 8192), 16, 0, 0);
;     }
;   };
;   const int sw = (r >> 1) & 7;
;   const int arow_off = (wm * 128 + r) * 128;
;   const int brow_off = 32768 + (wn * 64 + r) * 128;
;   __syncthreads();
;   glds(0, 0);
; template <int EPI>
; DI void phase_gemm(const Params& p, const GemmArgs& ga, char* lds) {
;     ...
;   for (int it = 0; it * (int)gridDim.x < total; ++it) {
;     const int lt = logical_index(it);
;     if (lt >= total) continue;
;     int mt, nt;
;     tile_mn(lt, Mt, ga.Nt, mt, nt);
;     int bb, tokbase, S, pos0, rlo = 0, rhi = 256;
;     if (EPI == EPI_UP) {
;       bb = 0; tokbase = 0; S = NTOK;
;       pos0 = 254 * mt - 1;
;       rlo = (mt == 0) ? 1 : 0;
;       rhi = NTOK - pos0; if (rhi > 256) rhi = 256;
;     } else {
;       seq_of_token(mt * 256, bb, tokbase, S);
;       pos0 = mt * 256 - tokbase;
;     }
;     const u16* A = ga.A + (ptrdiff_t)(tokbase + pos0) * ga.lda;
;     const u16* B = ga.Bt + (size_t)(nt * 256) * ga.K;
;     f32x16 acc[4][2];
;     bool swap;
;     if (EPI == EPI_M) swap = true;
;     else if (EPI == EPI_UP) swap = true;
;     else if (EPI == EPI_QKV1) swap = (nt < 8);
;     else swap = !(nt == 4 || nt == 5);
;     if (swap) gemm_mainloop<true>(acc, A, ga.lda, rlo, rhi, B, ga.K, ga.K, lds, (const u16*)(p.ws + OFF_ZERO));
;     else gemm_mainloop<false>(acc, A, ga.lda, rlo, rhi, B, ga.K, ga.K, lds, (const u16*)(p.ws + OFF_ZERO));
.LBB0_315:
	s_add_i32 s6, s6, s25
	s_cmpk_gt_i32 s6, 0x6bf
	s_cbranch_scc1 .LBB0_314
	s_mul_hi_i32 s7, s6, 0x38e38e39
	s_lshr_b32 s8, s7, 31
	s_ashr_i32 s29, s7, 4
	s_add_i32 s29, s29, s8
	s_mul_i32 s7, s29, 0xffffffb8
	s_add_i32 s6, s7, s6
	s_ashr_i32 s8, s6, 31
	s_lshr_b32 s8, s8, 29
	s_lshl_b32 s7, s29, 3
	s_add_i32 s8, s6, s8
	s_add_i32 s6, s6, s7
	s_and_b32 s30, s8, -8
	s_sub_i32 s28, s6, s30
	s_lshl_b32 s12, s28, 8
	s_ashr_i32 s13, s12, 31
	s_ashr_i32 s9, s8, 3
	s_lshl_b64 s[6:7], s[12:13], 11
	s_add_u32 s14, s90, s6
	s_addc_u32 s15, s91, s7
	s_lshl_b32 s16, s9, 8
	s_ashr_i32 s17, s16, 31
	s_lshl_b64 s[6:7], s[16:17], 11
	s_add_u32 s20, s70, s6
	s_addc_u32 s21, s71, s7
	s_and_b32 s6, s9, -2
	s_cmp_lg_u32 s6, 4
	s_cselect_b64 s[18:19], -1, 0
	s_cmp_eq_u32 s6, 4
	s_mov_b64 s[6:7], -1
	s_cbranch_scc1 .LBB0_322
	s_waitcnt vmcnt(5)
	v_mov_b32_e32 v10, v204
	s_nop 0
	v_ashrrev_i32_e32 v2, 3, v10
	v_lshrrev_b32_e32 v13, 1, v2
	v_xor_b32_e32 v0, v13, v10
	v_ashrrev_i32_e32 v3, 31, v2
	v_lshlrev_b64 v[4:5], 11, v[2:3]
	v_lshlrev_b32_e32 v0, 4, v0
	v_and_b32_e32 v12, 31, v10
	v_lshl_add_u64 v[6:7], s[14:15], 0, v[4:5]
	v_and_b32_e32 v0, 0x70, v0
	v_lshl_add_u64 v[8:9], s[20:21], 0, v[4:5]
	s_waitcnt vmcnt(4)
	v_lshrrev_b32_e32 v14, 1, v10
	v_lshl_add_u64 v[6:7], v[6:7], 0, v[0:1]
	v_lshl_add_u64 v[164:165], v[8:9], 0, v[0:1]
	v_and_or_b32 v0, v14, s51, v12
	v_lshlrev_b32_e32 v161, 7, v0
	v_lshlrev_b32_e32 v0, 7, v10
	v_lshlrev_b32_e32 v174, 4, v10
	v_and_b32_e32 v163, 0x6f80, v0
	v_and_b32_e32 v0, 0x70, v174
	v_add_u32_e32 v175, 0x8000, v174
	v_lshl_add_u64 v[166:167], s[80:81], 0, v[0:1]
	v_cmp_gt_u32_e32 vcc, s50, v2
	v_readfirstlane_b32 s6, v174
	s_mov_b32 m0, s6
	v_cndmask_b32_e32 v9, v167, v7, vcc
	v_cndmask_b32_e32 v8, v166, v6, vcc
	v_readfirstlane_b32 s6, v175
	v_add_u32_e32 v0, 64, v2
	s_barrier
	s_mov_b32 m0, s6
	s_mov_b64 s[10:11], 0x20000
	v_cmp_gt_u32_e64 s[6:7], s50, v0
	v_add_u32_e32 v0, 0x2000, v174
	v_lshl_add_u64 v[8:9], v[6:7], 0, s[10:11]
	v_readfirstlane_b32 s8, v0
	v_add_u32_e32 v176, 0xa000, v174
	v_cndmask_b32_e64 v9, v167, v9, s[6:7]
	v_cndmask_b32_e64 v8, v166, v8, s[6:7]
	s_mov_b32 m0, s8
	v_readfirstlane_b32 s8, v176
	v_lshl_add_u64 v[8:9], v[164:165], 0, s[10:11]
	s_mov_b32 m0, s8
	v_add_u32_e32 v3, 0x80, v2
	s_mov_b64 s[22:23], 0x40000
	v_add_u32_e32 v177, 0x4000, v174
	v_lshl_add_u64 v[8:9], v[6:7], 0, s[22:23]
	v_cmp_gt_u32_e64 s[8:9], s50, v3
	v_readfirstlane_b32 s10, v177
	v_add_u32_e32 v178, 0xc000, v174
	v_cndmask_b32_e64 v9, v167, v9, s[8:9]
	v_cndmask_b32_e64 v8, v166, v8, s[8:9]
	s_mov_b32 m0, s10
	v_readfirstlane_b32 s10, v178
	v_lshl_add_u64 v[8:9], v[164:165], 0, s[22:23]
	s_mov_b32 m0, s10
	s_mov_b64 s[22:23], 0x60000
	v_add_u32_e32 v8, 0xc0, v2
	v_add_u32_e32 v179, 0x6000, v174
	v_lshl_add_u64 v[2:3], v[6:7], 0, s[22:23]
	v_cmp_gt_u32_e64 s[10:11], s50, v8
	v_readfirstlane_b32 s17, v179
	v_add_u32_e32 v180, 0xe000, v174
	v_cndmask_b32_e64 v3, v167, v3, s[10:11]
	v_cndmask_b32_e64 v2, v166, v2, s[10:11]
	s_mov_b32 m0, s17
	v_readfirstlane_b32 s17, v180
	v_lshl_add_u64 v[2:3], v[164:165], 0, s[22:23]
	s_mov_b32 m0, s17
	v_bfe_u32 v11, v10, 5, 1
	s_sub_i32 s17, s26, s30
	s_lshl_b32 s22, s29, 6
	v_bfe_u32 v15, v10, 1, 3
	v_bitop3_b32 v2, v14, v11, 7 bitop3:0x6c
	s_sub_i32 s17, s17, s22
	v_lshlrev_b32_e32 v181, 4, v2
	v_bitop3_b32 v2, v11, v15, 2 bitop3:0x36
	s_lshl_b32 s22, s17, 8
	v_lshlrev_b32_e32 v182, 4, v2
	v_bitop3_b32 v2, v11, v15, 4 bitop3:0x36
	s_ashr_i32 s23, s22, 31
	v_lshlrev_b32_e32 v183, 4, v2
	v_bitop3_b32 v2, v11, v15, 6 bitop3:0x36
	s_lshl_b64 s[22:23], s[22:23], 11
	v_lshlrev_b32_e32 v186, 4, v2
	v_lshl_add_u64 v[2:3], v[4:5], 0, s[22:23]
	v_bitop3_b32 v4, v13, 7, v10 bitop3:0x48
	s_waitcnt vmcnt(0)
	v_lshl_or_b32 v2, v4, 4, v2
	v_lshl_add_u64 v[168:169], s[70:71], 0, v[2:3]
	v_mov_b32_e32 v130, 0
	v_mov_b32_e32 v2, 0
	s_mov_b32 s13, 1
	v_add_u32_e32 v187, 0x10000, v174
	v_add_u32_e32 v192, 0x18000, v174
	v_add_u32_e32 v193, 0x12000, v174
	v_add_u32_e32 v194, 0x1a000, v174
	v_add_u32_e32 v195, 0x14000, v174
	v_add_u32_e32 v196, 0x1c000, v174
	v_add_u32_e32 v197, 0x16000, v174
	v_add_u32_e32 v198, 0x1e000, v174
	v_add_u32_e32 v199, 0x10000, v161
	v_or_b32_e32 v200, 0x10000, v163
	s_mov_b64 s[22:23], 0
	v_mov_b32_e32 v3, v2
	v_mov_b32_e32 v4, v2
	v_mov_b32_e32 v5, v2
	v_mov_b32_e32 v6, v2
	v_mov_b32_e32 v7, v2
	v_mov_b32_e32 v8, v2
	v_mov_b32_e32 v9, v2
	v_mov_b32_e32 v10, v2
	v_mov_b32_e32 v11, v2
	v_mov_b32_e32 v12, v2
	v_mov_b32_e32 v13, v2
	v_mov_b32_e32 v14, v2
	v_mov_b32_e32 v15, v2
	v_mov_b32_e32 v16, v2
	v_mov_b32_e32 v17, v2
	v_mov_b32_e32 v34, v2
	v_mov_b32_e32 v35, v2
	v_mov_b32_e32 v36, v2
	v_mov_b32_e32 v37, v2
	v_mov_b32_e32 v38, v2
	v_mov_b32_e32 v39, v2
	v_mov_b32_e32 v40, v2
	v_mov_b32_e32 v41, v2
	v_mov_b32_e32 v42, v2
	v_mov_b32_e32 v43, v2
	v_mov_b32_e32 v44, v2
	v_mov_b32_e32 v45, v2
	v_mov_b32_e32 v46, v2
	v_mov_b32_e32 v47, v2
	v_mov_b32_e32 v48, v2
	v_mov_b32_e32 v49, v2
	s_waitcnt vmcnt(0)
; DI int opaque_tid() { int t = threadIdx.x; asm volatile("" : "+v"(t)); return t; }
; template <bool SWAP>
; DI void gemm_mainloop(f32x16 (&acc)[4][2], const u16* __restrict__ A, int lda, int rlo, int rhi,
;                       const u16* __restrict__ B, int ldb, int K, char* lds, const u16* zero_line) {
;   const int tid = opaque_tid(), lane = tid & 63, w = tid >> 6;
;   const int wm = w >> 2, wn = w & 3;
;   const int h = lane >> 5, r = lane & 31;
;   const int lr = tid >> 3, lc = tid & 7;
; #pragma unroll
;   for (int mi = 0; mi < 4; ++mi)
; #pragma unroll
;     for (int ni = 0; ni < 2; ++ni)
; #pragma unroll
;       for (int i = 0; i < 16; ++i) acc[mi][ni][i] = 0.f;
;   const int gch = (lc ^ ((lr >> 1) & 7)) * 8;
;   const u16* ap = A + (ptrdiff_t)lr * lda + gch;
;   const u16* bp = B + (ptrdiff_t)lr * ldb + gch;
;   const int nk = K >> 6;
;   typedef __attribute__((address_space(3))) unsigned lds_u32;
;   auto glds = [&](int kt, int st) {
;     char* as_ = lds + st * 65536 + tid * 16;
; #pragma unroll
;     for (int i = 0; i < 4; ++i) {
;       const int rr = lr + 64 * i;
;       const u16* srca = (rr >= rlo && rr < rhi) ? (ap + (ptrdiff_t)(64 * i) * lda + kt * 64) : (zero_line + lc * 8);
;       __builtin_amdgcn_global_load_lds((const unsigned*)srca, (lds_u32*)(as_ + i * 8192), 16, 0, 0);
;       __builtin_amdgcn_global_load_lds((const unsigned*)(bp + (ptrdiff_t)(64 * i) * ldb + kt * 64), (lds_u32*)(as_ + 32768 + i * 8192), 16, 0, 0);
;     }
;   };
;   const int sw = (r >> 1) & 7;
;   const int arow_off = (wm * 128 + r) * 128;
;   const int brow_off = 32768 + (wn * 64 + r) * 128;
;   __syncthreads();
;   glds(0, 0);
;   asm volatile("s_waitcnt vmcnt(0)" ::: "memory");
;   __syncthreads();
	v_mov_b32_e32 v18, v2
	v_mov_b32_e32 v19, v2
	v_mov_b32_e32 v20, v2
	v_mov_b32_e32 v21, v2
	v_mov_b32_e32 v22, v2
	v_mov_b32_e32 v23, v2
	v_mov_b32_e32 v24, v2
	v_mov_b32_e32 v25, v2
	v_mov_b32_e32 v26, v2
	v_mov_b32_e32 v27, v2
	v_mov_b32_e32 v28, v2
	v_mov_b32_e32 v29, v2
	v_mov_b32_e32 v30, v2
	v_mov_b32_e32 v31, v2
	v_mov_b32_e32 v32, v2
	v_mov_b32_e32 v33, v2
	v_mov_b32_e32 v66, v2
	v_mov_b32_e32 v67, v2
	v_mov_b32_e32 v68, v2
	v_mov_b32_e32 v69, v2
	v_mov_b32_e32 v70, v2
	v_mov_b32_e32 v71, v2
	v_mov_b32_e32 v72, v2
	v_mov_b32_e32 v73, v2
	v_mov_b32_e32 v74, v2
	v_mov_b32_e32 v75, v2
	v_mov_b32_e32 v76, v2
	v_mov_b32_e32 v77, v2
	v_mov_b32_e32 v78, v2
	v_mov_b32_e32 v79, v2
	v_mov_b32_e32 v80, v2
	v_mov_b32_e32 v81, v2
	v_mov_b32_e32 v50, v2
	v_mov_b32_e32 v51, v2
	v_mov_b32_e32 v52, v2
	v_mov_b32_e32 v53, v2
	v_mov_b32_e32 v54, v2
	v_mov_b32_e32 v55, v2
	v_mov_b32_e32 v56, v2
	v_mov_b32_e32 v57, v2
	v_mov_b32_e32 v58, v2
	v_mov_b32_e32 v59, v2
	v_mov_b32_e32 v60, v2
	v_mov_b32_e32 v61, v2
	v_mov_b32_e32 v62, v2
	v_mov_b32_e32 v63, v2
	v_mov_b32_e32 v64, v2
	v_mov_b32_e32 v65, v2
	v_mov_b32_e32 v98, v2
	v_mov_b32_e32 v99, v2
	v_mov_b32_e32 v100, v2
	v_mov_b32_e32 v101, v2
	v_mov_b32_e32 v102, v2
	v_mov_b32_e32 v103, v2
	v_mov_b32_e32 v104, v2
	v_mov_b32_e32 v105, v2
	v_mov_b32_e32 v106, v2
	v_mov_b32_e32 v107, v2
	v_mov_b32_e32 v108, v2
	v_mov_b32_e32 v109, v2
	v_mov_b32_e32 v110, v2
	v_mov_b32_e32 v111, v2
	v_mov_b32_e32 v112, v2
	v_mov_b32_e32 v113, v2
	v_mov_b32_e32 v82, v2
	v_mov_b32_e32 v83, v2
	v_mov_b32_e32 v84, v2
	v_mov_b32_e32 v85, v2
	v_mov_b32_e32 v86, v2
	v_mov_b32_e32 v87, v2
	v_mov_b32_e32 v88, v2
	v_mov_b32_e32 v89, v2
	v_mov_b32_e32 v90, v2
	v_mov_b32_e32 v91, v2
	v_mov_b32_e32 v92, v2
	v_mov_b32_e32 v93, v2
	v_mov_b32_e32 v94, v2
	v_mov_b32_e32 v95, v2
	v_mov_b32_e32 v96, v2
	v_mov_b32_e32 v97, v2
	v_mov_b32_e32 v114, v2
	v_mov_b32_e32 v115, v2
	v_mov_b32_e32 v116, v2
	v_mov_b32_e32 v117, v2
	v_mov_b32_e32 v118, v2
	v_mov_b32_e32 v119, v2
	v_mov_b32_e32 v120, v2
	v_mov_b32_e32 v121, v2
	v_mov_b32_e32 v122, v2
	v_mov_b32_e32 v123, v2
	v_mov_b32_e32 v124, v2
	v_mov_b32_e32 v125, v2
	v_mov_b32_e32 v126, v2
	v_mov_b32_e32 v127, v2
	v_mov_b32_e32 v128, v2
	v_mov_b32_e32 v129, v2
	v_mov_b32_e32 v131, v130
	v_mov_b32_e32 v132, v130
	v_mov_b32_e32 v133, v130
	v_mov_b32_e32 v134, v130
	v_mov_b32_e32 v135, v130
	v_mov_b32_e32 v136, v130
	v_mov_b32_e32 v137, v130
	v_mov_b32_e32 v138, v130
	v_mov_b32_e32 v139, v130
	v_mov_b32_e32 v140, v130
	v_mov_b32_e32 v141, v130
	v_mov_b32_e32 v146, v130
	v_mov_b32_e32 v147, v130
	v_mov_b32_e32 v148, v130
	v_mov_b32_e32 v149, v130
	v_mov_b32_e32 v142, v130
	v_mov_b32_e32 v143, v130
	v_mov_b32_e32 v144, v130
	v_mov_b32_e32 v145, v130
	v_mov_b32_e32 v150, v130
	v_mov_b32_e32 v151, v130
	v_mov_b32_e32 v152, v130
	v_mov_b32_e32 v153, v130
	s_waitcnt lgkmcnt(0)
	s_barrier
	s_ashr_i32 s7, s12, 31
	s_mov_b32 s6, s12
	s_lshl_b64 s[6:7], s[6:7], 11
	s_add_u32 s6, s90, s6
	s_addc_u32 s7, s91, s7
	s_ashr_i32 s9, s16, 31
	s_mov_b32 s8, s16
	s_lshl_b64 s[8:9], s[8:9], 11
	s_add_u32 s8, s70, s8
	s_addc_u32 s9, s71, s9
	v_and_b32_e32 v130, 63, v204
	v_lshrrev_b32_e32 v131, 6, v204
	v_lshrrev_b32_e32 v132, 3, v204
	v_lshrrev_b32_e32 v0, 4, v130
	v_lshl_add_u32 v0, v131, 2, v0
	v_xor_b32_e32 v0, v0, v130
	v_and_b32_e32 v0, 7, v0
	v_lshlrev_b32_e32 v133, 4, v0
	v_lshl_add_u32 v240, v132, 11, v133
	v_add_u32_e32 v241, 0x20000, v240
	v_add_u32_e32 v242, 0x40000, v240
	v_add_u32_e32 v243, 0x60000, v240
	v_and_b32_e32 v0, 31, v132
	v_lshrrev_b32_e32 v130, 5, v132
	v_lshl_add_u32 v0, v130, 6, v0
	v_lshl_add_u32 v244, v0, 11, v133
	v_add_u32_e32 v245, 0x10000, v244
	v_add_u32_e32 v246, 0x40000, v244
	v_add_u32_e32 v247, 0x50000, v244
	v_and_b32_e32 v132, 31, v204
	v_lshrrev_b32_e32 v0, 2, v131
	v_lshl_add_u32 v0, v0, 6, v132
	v_lshlrev_b32_e32 v166, 7, v0
	v_and_b32_e32 v0, 3, v131
	v_lshl_add_u32 v0, v0, 5, v132
	v_lshlrev_b32_e32 v186, 7, v0
	v_bfe_u32 v0, v204, 5, 1
	v_bfe_u32 v130, v132, 1, 3
	v_or_b32_e32 v133, 0, v0
	v_xor_b32_e32 v133, v133, v130
	v_lshlrev_b32_e32 v161, 4, v133
	v_or_b32_e32 v133, 2, v0
	v_xor_b32_e32 v133, v133, v130
	v_lshlrev_b32_e32 v163, 4, v133
	v_or_b32_e32 v133, 4, v0
	v_xor_b32_e32 v133, v133, v130
	v_lshlrev_b32_e32 v164, 4, v133
	v_or_b32_e32 v133, 6, v0
	v_xor_b32_e32 v133, v133, v130
	v_lshlrev_b32_e32 v165, 4, v133
	v_lshlrev_b32_e32 v131, 10, v131
	s_nop 0
	v_readfirstlane_b32 s100, v131
	v_mov_b32_e32 v146, 0
	v_mov_b32_e32 v147, 0
	v_mov_b32_e32 v148, 0
	v_mov_b32_e32 v149, 0
	v_lshlrev_b32_e32 v130, 4, v204
	v_add_u32_e32 v132, 0x10000, v130
	s_mov_b64 exec, -1
	s_mov_b32 s11, 0
	s_mov_b32 s10, 0x10000
	s_waitcnt lgkmcnt(0)
	s_add_u32 m0, s100, 0x8000
	s_nop 0
	global_load_lds_dwordx4 v244, s[8:9]
	v_add_u32_e32 v244, 0x80, v244
	s_add_u32 m0, s100, 0xa000
	s_nop 0
	global_load_lds_dwordx4 v246, s[8:9]
	v_add_u32_e32 v246, 0x80, v246
	s_add_u32 m0, s100, 0x0
	s_nop 0
	global_load_lds_dwordx4 v240, s[6:7]
	v_add_u32_e32 v240, 0x80, v240
	s_add_u32 m0, s100, 0x2000
	s_nop 0
	global_load_lds_dwordx4 v242, s[6:7]
	v_add_u32_e32 v242, 0x80, v242
	s_add_u32 m0, s100, 0xc000
	s_nop 0
	global_load_lds_dwordx4 v245, s[8:9]
	v_add_u32_e32 v245, 0x80, v245
	s_add_u32 m0, s100, 0xe000
	s_nop 0
	global_load_lds_dwordx4 v247, s[8:9]
	v_add_u32_e32 v247, 0x80, v247
	s_add_u32 m0, s100, 0x4000
	s_nop 0
	global_load_lds_dwordx4 v241, s[6:7]
	v_add_u32_e32 v241, 0x80, v241
	s_add_u32 m0, s100, 0x6000
	s_nop 0
	global_load_lds_dwordx4 v243, s[6:7]
	v_add_u32_e32 v243, 0x80, v243
	s_cmp_eq_u32 s101, 1
	s_cbranch_scc0 .Lg8_ia_p0
	s_barrier
; #define MFMA(a, b, c) __builtin_amdgcn_mfma_f32_32x32x16_bf16((a), (b), (c), 0, 0, 0)
; template <bool SWAP>
; DI void gemm_mainloop(f32x16 (&acc)[4][2], const u16* __restrict__ A, int lda, int rlo, int rhi,
;                       const u16* __restrict__ B, int ldb, int K, char* lds, const u16* zero_line) {
;     ...
;   auto ldfrag = [&](const char* st, int ks, int buf) {
;     const int co = ((2 * ks + h) ^ sw) << 4;
; #pragma unroll
;     for (int mi = 0; mi < 4; ++mi) fa[buf][mi] = *(const bf16x8*)(st + arow_off + mi * 4096 + co);
; #pragma unroll
;     for (int ni = 0; ni < 2; ++ni) fb[buf][ni] = *(const bf16x8*)(st + brow_off + ni * 4096 + co);
;   };
;   auto mma = [&](int buf) {
; #pragma unroll
;     for (int mi = 0; mi < 4; ++mi)
; #pragma unroll
;       for (int ni = 0; ni < 2; ++ni)
;         acc[mi][ni] = SWAP ? MFMA(fb[buf][ni], fa[buf][mi], acc[mi][ni]) : MFMA(fa[buf][mi], fb[buf][ni], acc[mi][ni]);
;   };
;   auto pat_rd = [&]() {
; #pragma unroll
;     for (int g = 0; g < 6; ++g) {
;       __builtin_amdgcn_sched_group_barrier(0x100, 1, 0);
;       __builtin_amdgcn_sched_group_barrier(0x008, 1, 0);
;     }
;     __builtin_amdgcn_sched_group_barrier(0x008, 2, 0);
;   };
; #pragma unroll 2
;   for (int kt = 0; kt < nk; ++kt) {
;     const char* st = lds + (kt & 1) * 65536;
;     ldfrag(st, 0, 0);
;     mma(1);
;     pat_rd();
;     if (kt + 1 < nk) glds(kt + 1, (kt + 1) & 1);
;     ldfrag(st, 1, 1);
;     mma(0);
;     pat_rd();
;     ldfrag(st, 2, 0);
;     mma(1);
;     pat_rd();
;     ldfrag(st, 3, 1);
;     mma(0);
;     pat_rd();
;     asm volatile("s_waitcnt vmcnt(0)" ::: "memory");
;     __syncthreads();
;   }
.Lg8_ia_p0:
	s_waitcnt vmcnt(4)
	s_barrier
	s_add_u32 m0, s100, 0x18000
	s_nop 0
	global_load_lds_dwordx4 v244, s[8:9]
	v_add_u32_e32 v244, 0x80, v244
	s_add_u32 m0, s100, 0x1a000
	s_nop 0
	global_load_lds_dwordx4 v246, s[8:9]
	v_add_u32_e32 v246, 0x80, v246
	s_add_u32 m0, s100, 0x10000
	s_nop 0
	global_load_lds_dwordx4 v240, s[6:7]
	v_add_u32_e32 v240, 0x80, v240
	s_add_u32 m0, s100, 0x12000
	s_nop 0
	global_load_lds_dwordx4 v242, s[6:7]
	v_add_u32_e32 v242, 0x80, v242
	s_add_u32 m0, s100, 0x1c000
	s_nop 0
	global_load_lds_dwordx4 v245, s[8:9]
	v_add_u32_e32 v245, 0x80, v245
	s_add_u32 m0, s100, 0x1e000
	s_nop 0
	global_load_lds_dwordx4 v247, s[8:9]
	v_add_u32_e32 v247, 0x80, v247
	s_waitcnt vmcnt(6)
	s_barrier
.Lg8_ia:
	v_add3_u32 v187, v186, v161, 0
	v_add3_u32 v248, v186, v163, 0
	ds_read_b128 v[176:179], v187 offset:32768
	ds_read_b128 v[180:183], v248 offset:32768
	v_add3_u32 v187, v186, v164, 0
	v_add3_u32 v248, v186, v165, 0
	ds_read_b128 v[192:195], v187 offset:32768
	ds_read_b128 v[196:199], v248 offset:32768
	v_add3_u32 v187, v166, v161, 0
	v_add3_u32 v248, v166, v163, 0
	ds_read_b128 v[130:133], v187
	ds_read_b128 v[134:137], v248
	ds_read_b128 v[146:149], v187 offset:4096
	ds_read_b128 v[150:153], v248 offset:4096
	v_add3_u32 v187, v166, v164, 0
	v_add3_u32 v248, v166, v165, 0
	ds_read_b128 v[138:141], v187
	ds_read_b128 v[142:145], v248
	ds_read_b128 v[168:171], v187 offset:4096
	ds_read_b128 v[172:175], v248 offset:4096
	s_add_u32 m0, s100, 0x14000
	s_nop 0
	global_load_lds_dwordx4 v241, s[6:7]
	v_add_u32_e32 v241, 0x80, v241
	s_add_u32 m0, s100, 0x16000
	s_nop 0
	global_load_lds_dwordx4 v243, s[6:7]
	v_add_u32_e32 v243, 0x80, v243
	s_waitcnt lgkmcnt(8)
	s_barrier
	s_waitcnt lgkmcnt(0)
	v_mfma_f32_32x32x16_bf16 v[114:129], v[176:179], v[130:133], v[114:129]
	v_mfma_f32_32x32x16_bf16 v[98:113], v[176:179], v[146:149], v[98:113]
	v_mfma_f32_32x32x16_bf16 v[114:129], v[180:183], v[134:137], v[114:129]
	v_mfma_f32_32x32x16_bf16 v[98:113], v[180:183], v[150:153], v[98:113]
	v_mfma_f32_32x32x16_bf16 v[114:129], v[192:195], v[138:141], v[114:129]
	v_mfma_f32_32x32x16_bf16 v[98:113], v[192:195], v[168:171], v[98:113]
	v_mfma_f32_32x32x16_bf16 v[114:129], v[196:199], v[142:145], v[114:129]
	v_mfma_f32_32x32x16_bf16 v[98:113], v[196:199], v[172:175], v[98:113]
	s_barrier
	v_add3_u32 v187, v186, v161, 0
	v_add3_u32 v248, v186, v163, 0
	ds_read_b128 v[200:203], v187 offset:49152
	ds_read_b128 v[228:231], v248 offset:49152
	v_add3_u32 v187, v186, v164, 0
	v_add3_u32 v248, v186, v165, 0
	ds_read_b128 v[232:235], v187 offset:49152
	ds_read_b128 v[236:239], v248 offset:49152
	s_add_u32 m0, s100, 0x8000
	s_nop 0
	global_load_lds_dwordx4 v244, s[8:9]
	v_add_u32_e32 v244, 0x80, v244
	s_add_u32 m0, s100, 0xa000
	s_nop 0
	global_load_lds_dwordx4 v246, s[8:9]
	v_add_u32_e32 v246, 0x80, v246
	s_barrier
	s_waitcnt lgkmcnt(0)
	v_mfma_f32_32x32x16_bf16 v[82:97], v[200:203], v[130:133], v[82:97]
	v_mfma_f32_32x32x16_bf16 v[50:65], v[200:203], v[146:149], v[50:65]
	v_mfma_f32_32x32x16_bf16 v[82:97], v[228:231], v[134:137], v[82:97]
	v_mfma_f32_32x32x16_bf16 v[50:65], v[228:231], v[150:153], v[50:65]
	v_mfma_f32_32x32x16_bf16 v[82:97], v[232:235], v[138:141], v[82:97]
	v_mfma_f32_32x32x16_bf16 v[50:65], v[232:235], v[168:171], v[50:65]
	v_mfma_f32_32x32x16_bf16 v[82:97], v[236:239], v[142:145], v[82:97]
	v_mfma_f32_32x32x16_bf16 v[50:65], v[236:239], v[172:175], v[50:65]
	s_barrier
	v_add3_u32 v187, v166, v161, 0
	v_add3_u32 v248, v166, v163, 0
	ds_read_b128 v[130:133], v187 offset:16384
	ds_read_b128 v[134:137], v248 offset:16384
	ds_read_b128 v[146:149], v187 offset:20480
	ds_read_b128 v[150:153], v248 offset:20480
	v_add3_u32 v187, v166, v164, 0
	v_add3_u32 v248, v166, v165, 0
	ds_read_b128 v[138:141], v187 offset:16384
	ds_read_b128 v[142:145], v248 offset:16384
	ds_read_b128 v[168:171], v187 offset:20480
	ds_read_b128 v[172:175], v248 offset:20480
	s_add_u32 m0, s100, 0x0
	s_nop 0
	global_load_lds_dwordx4 v240, s[6:7]
	v_add_u32_e32 v240, 0x80, v240
	s_add_u32 m0, s100, 0x2000
	s_nop 0
	global_load_lds_dwordx4 v242, s[6:7]
	v_add_u32_e32 v242, 0x80, v242
	s_barrier
	s_waitcnt lgkmcnt(0)
	v_mfma_f32_32x32x16_bf16 v[66:81], v[176:179], v[130:133], v[66:81]
	v_mfma_f32_32x32x16_bf16 v[34:49], v[176:179], v[146:149], v[34:49]
	v_mfma_f32_32x32x16_bf16 v[66:81], v[180:183], v[134:137], v[66:81]
	v_mfma_f32_32x32x16_bf16 v[34:49], v[180:183], v[150:153], v[34:49]
	v_mfma_f32_32x32x16_bf16 v[66:81], v[192:195], v[138:141], v[66:81]
	v_mfma_f32_32x32x16_bf16 v[34:49], v[192:195], v[168:171], v[34:49]
	v_mfma_f32_32x32x16_bf16 v[66:81], v[196:199], v[142:145], v[66:81]
	v_mfma_f32_32x32x16_bf16 v[34:49], v[196:199], v[172:175], v[34:49]
	s_barrier
	s_add_u32 m0, s100, 0xc000
	s_nop 0
	global_load_lds_dwordx4 v245, s[8:9]
	v_add_u32_e32 v245, 0x80, v245
	s_add_u32 m0, s100, 0xe000
	s_nop 0
	global_load_lds_dwordx4 v247, s[8:9]
	v_add_u32_e32 v247, 0x80, v247
	s_waitcnt vmcnt(6)
	s_barrier
	v_mfma_f32_32x32x16_bf16 v[18:33], v[200:203], v[130:133], v[18:33]
	v_mfma_f32_32x32x16_bf16 v[2:17], v[200:203], v[146:149], v[2:17]
	v_mfma_f32_32x32x16_bf16 v[18:33], v[228:231], v[134:137], v[18:33]
	v_mfma_f32_32x32x16_bf16 v[2:17], v[228:231], v[150:153], v[2:17]
	v_mfma_f32_32x32x16_bf16 v[18:33], v[232:235], v[138:141], v[18:33]
	v_mfma_f32_32x32x16_bf16 v[2:17], v[232:235], v[168:171], v[2:17]
	v_mfma_f32_32x32x16_bf16 v[18:33], v[236:239], v[142:145], v[18:33]
	v_mfma_f32_32x32x16_bf16 v[2:17], v[236:239], v[172:175], v[2:17]
	s_barrier
; #define MFMA(a, b, c) __builtin_amdgcn_mfma_f32_32x32x16_bf16((a), (b), (c), 0, 0, 0)
; template <bool SWAP>
; DI void gemm_mainloop(f32x16 (&acc)[4][2], const u16* __restrict__ A, int lda, int rlo, int rhi,
;                       const u16* __restrict__ B, int ldb, int K, char* lds, const u16* zero_line) {
;     ...
;   auto ldfrag = [&](const char* st, int ks, int buf) {
;     const int co = ((2 * ks + h) ^ sw) << 4;
; #pragma unroll
;     for (int mi = 0; mi < 4; ++mi) fa[buf][mi] = *(const bf16x8*)(st + arow_off + mi * 4096 + co);
; #pragma unroll
;     for (int ni = 0; ni < 2; ++ni) fb[buf][ni] = *(const bf16x8*)(st + brow_off + ni * 4096 + co);
;   };
;   auto mma = [&](int buf) {
; #pragma unroll
;     for (int mi = 0; mi < 4; ++mi)
; #pragma unroll
;       for (int ni = 0; ni < 2; ++ni)
;         acc[mi][ni] = SWAP ? MFMA(fb[buf][ni], fa[buf][mi], acc[mi][ni]) : MFMA(fa[buf][mi], fb[buf][ni], acc[mi][ni]);
;   };
;   auto pat_rd = [&]() {
; #pragma unroll
;     for (int g = 0; g < 6; ++g) {
;       __builtin_amdgcn_sched_group_barrier(0x100, 1, 0);
;       __builtin_amdgcn_sched_group_barrier(0x008, 1, 0);
;     }
;     __builtin_amdgcn_sched_group_barrier(0x008, 2, 0);
;   };
; #pragma unroll 2
;   for (int kt = 0; kt < nk; ++kt) {
;     const char* st = lds + (kt & 1) * 65536;
;     ldfrag(st, 0, 0);
;     mma(1);
;     pat_rd();
;     if (kt + 1 < nk) glds(kt + 1, (kt + 1) & 1);
;     ldfrag(st, 1, 1);
;     mma(0);
;     pat_rd();
;     ldfrag(st, 2, 0);
;     mma(1);
;     pat_rd();
;     ldfrag(st, 3, 1);
;     mma(0);
;     pat_rd();
;     asm volatile("s_waitcnt vmcnt(0)" ::: "memory");
;     __syncthreads();
;   }
	v_add3_u32 v187, v186, v161, s10
	v_add3_u32 v248, v186, v163, s10
	ds_read_b128 v[176:179], v187 offset:32768
	ds_read_b128 v[180:183], v248 offset:32768
	v_add3_u32 v187, v186, v164, s10
	v_add3_u32 v248, v186, v165, s10
	ds_read_b128 v[192:195], v187 offset:32768
	ds_read_b128 v[196:199], v248 offset:32768
	v_add3_u32 v187, v166, v161, s10
	v_add3_u32 v248, v166, v163, s10
	ds_read_b128 v[130:133], v187
	ds_read_b128 v[134:137], v248
	ds_read_b128 v[146:149], v187 offset:4096
	ds_read_b128 v[150:153], v248 offset:4096
	v_add3_u32 v187, v166, v164, s10
	v_add3_u32 v248, v166, v165, s10
	ds_read_b128 v[138:141], v187
	ds_read_b128 v[142:145], v248
	ds_read_b128 v[168:171], v187 offset:4096
	ds_read_b128 v[172:175], v248 offset:4096
	s_add_u32 m0, s100, 0x4000
	s_nop 0
	global_load_lds_dwordx4 v241, s[6:7]
	v_add_u32_e32 v241, 0x80, v241
	s_add_u32 m0, s100, 0x6000
	s_nop 0
	global_load_lds_dwordx4 v243, s[6:7]
	v_add_u32_e32 v243, 0x80, v243
	s_waitcnt lgkmcnt(8)
	s_barrier
	s_waitcnt lgkmcnt(0)
	v_mfma_f32_32x32x16_bf16 v[114:129], v[176:179], v[130:133], v[114:129]
	v_mfma_f32_32x32x16_bf16 v[98:113], v[176:179], v[146:149], v[98:113]
	v_mfma_f32_32x32x16_bf16 v[114:129], v[180:183], v[134:137], v[114:129]
	v_mfma_f32_32x32x16_bf16 v[98:113], v[180:183], v[150:153], v[98:113]
	v_mfma_f32_32x32x16_bf16 v[114:129], v[192:195], v[138:141], v[114:129]
	v_mfma_f32_32x32x16_bf16 v[98:113], v[192:195], v[168:171], v[98:113]
	v_mfma_f32_32x32x16_bf16 v[114:129], v[196:199], v[142:145], v[114:129]
	v_mfma_f32_32x32x16_bf16 v[98:113], v[196:199], v[172:175], v[98:113]
	s_barrier
	v_add3_u32 v187, v186, v161, s10
	v_add3_u32 v248, v186, v163, s10
	ds_read_b128 v[200:203], v187 offset:49152
	ds_read_b128 v[228:231], v248 offset:49152
	v_add3_u32 v187, v186, v164, s10
	v_add3_u32 v248, v186, v165, s10
	ds_read_b128 v[232:235], v187 offset:49152
	ds_read_b128 v[236:239], v248 offset:49152
	s_add_u32 m0, s100, 0x18000
	s_nop 0
	global_load_lds_dwordx4 v244, s[8:9]
	v_add_u32_e32 v244, 0x80, v244
	s_add_u32 m0, s100, 0x1a000
	s_nop 0
	global_load_lds_dwordx4 v246, s[8:9]
	v_add_u32_e32 v246, 0x80, v246
	s_barrier
	s_waitcnt lgkmcnt(0)
	v_mfma_f32_32x32x16_bf16 v[82:97], v[200:203], v[130:133], v[82:97]
	v_mfma_f32_32x32x16_bf16 v[50:65], v[200:203], v[146:149], v[50:65]
	v_mfma_f32_32x32x16_bf16 v[82:97], v[228:231], v[134:137], v[82:97]
	v_mfma_f32_32x32x16_bf16 v[50:65], v[228:231], v[150:153], v[50:65]
	v_mfma_f32_32x32x16_bf16 v[82:97], v[232:235], v[138:141], v[82:97]
	v_mfma_f32_32x32x16_bf16 v[50:65], v[232:235], v[168:171], v[50:65]
	v_mfma_f32_32x32x16_bf16 v[82:97], v[236:239], v[142:145], v[82:97]
	v_mfma_f32_32x32x16_bf16 v[50:65], v[236:239], v[172:175], v[50:65]
	s_barrier
	v_add3_u32 v187, v166, v161, s10
	v_add3_u32 v248, v166, v163, s10
	ds_read_b128 v[130:133], v187 offset:16384
	ds_read_b128 v[134:137], v248 offset:16384
	ds_read_b128 v[146:149], v187 offset:20480
	ds_read_b128 v[150:153], v248 offset:20480
	v_add3_u32 v187, v166, v164, s10
	v_add3_u32 v248, v166, v165, s10
	ds_read_b128 v[138:141], v187 offset:16384
	ds_read_b128 v[142:145], v248 offset:16384
	ds_read_b128 v[168:171], v187 offset:20480
	ds_read_b128 v[172:175], v248 offset:20480
	s_add_u32 m0, s100, 0x10000
	s_nop 0
	global_load_lds_dwordx4 v240, s[6:7]
	v_add_u32_e32 v240, 0x80, v240
	s_add_u32 m0, s100, 0x12000
	s_nop 0
	global_load_lds_dwordx4 v242, s[6:7]
	v_add_u32_e32 v242, 0x80, v242
	s_barrier
	s_waitcnt lgkmcnt(0)
	v_mfma_f32_32x32x16_bf16 v[66:81], v[176:179], v[130:133], v[66:81]
	v_mfma_f32_32x32x16_bf16 v[34:49], v[176:179], v[146:149], v[34:49]
	v_mfma_f32_32x32x16_bf16 v[66:81], v[180:183], v[134:137], v[66:81]
	v_mfma_f32_32x32x16_bf16 v[34:49], v[180:183], v[150:153], v[34:49]
	v_mfma_f32_32x32x16_bf16 v[66:81], v[192:195], v[138:141], v[66:81]
	v_mfma_f32_32x32x16_bf16 v[34:49], v[192:195], v[168:171], v[34:49]
	v_mfma_f32_32x32x16_bf16 v[66:81], v[196:199], v[142:145], v[66:81]
	v_mfma_f32_32x32x16_bf16 v[34:49], v[196:199], v[172:175], v[34:49]
	s_barrier
	s_add_u32 m0, s100, 0x1c000
	s_nop 0
	global_load_lds_dwordx4 v245, s[8:9]
	v_add_u32_e32 v245, 0x80, v245
	s_add_u32 m0, s100, 0x1e000
	s_nop 0
	global_load_lds_dwordx4 v247, s[8:9]
	v_add_u32_e32 v247, 0x80, v247
	s_waitcnt vmcnt(6)
	s_barrier
	v_mfma_f32_32x32x16_bf16 v[18:33], v[200:203], v[130:133], v[18:33]
	v_mfma_f32_32x32x16_bf16 v[2:17], v[200:203], v[146:149], v[2:17]
	v_mfma_f32_32x32x16_bf16 v[18:33], v[228:231], v[134:137], v[18:33]
	v_mfma_f32_32x32x16_bf16 v[2:17], v[228:231], v[150:153], v[2:17]
	v_mfma_f32_32x32x16_bf16 v[18:33], v[232:235], v[138:141], v[18:33]
	v_mfma_f32_32x32x16_bf16 v[2:17], v[232:235], v[168:171], v[2:17]
	v_mfma_f32_32x32x16_bf16 v[18:33], v[236:239], v[142:145], v[18:33]
	v_mfma_f32_32x32x16_bf16 v[2:17], v[236:239], v[172:175], v[2:17]
	s_barrier
	s_add_i32 s11, s11, 2
	s_cmp_lt_u32 s11, 14
	s_cbranch_scc1 .Lg8_ia
	v_add3_u32 v187, v186, v161, 0
	v_add3_u32 v248, v186, v163, 0
	ds_read_b128 v[176:179], v187 offset:32768
	ds_read_b128 v[180:183], v248 offset:32768
	v_add3_u32 v187, v186, v164, 0
	v_add3_u32 v248, v186, v165, 0
	ds_read_b128 v[192:195], v187 offset:32768
	ds_read_b128 v[196:199], v248 offset:32768
	v_add3_u32 v187, v166, v161, 0
	v_add3_u32 v248, v166, v163, 0
	ds_read_b128 v[130:133], v187
	ds_read_b128 v[134:137], v248
	ds_read_b128 v[146:149], v187 offset:4096
	ds_read_b128 v[150:153], v248 offset:4096
	v_add3_u32 v187, v166, v164, 0
	v_add3_u32 v248, v166, v165, 0
	ds_read_b128 v[138:141], v187
	ds_read_b128 v[142:145], v248
	ds_read_b128 v[168:171], v187 offset:4096
	ds_read_b128 v[172:175], v248 offset:4096
	s_add_u32 m0, s100, 0x14000
	s_nop 0
	global_load_lds_dwordx4 v241, s[6:7]
	v_add_u32_e32 v241, 0x80, v241
	s_add_u32 m0, s100, 0x16000
	s_nop 0
	global_load_lds_dwordx4 v243, s[6:7]
	v_add_u32_e32 v243, 0x80, v243
	s_barrier
; #define MFMA(a, b, c) __builtin_amdgcn_mfma_f32_32x32x16_bf16((a), (b), (c), 0, 0, 0)
; template <bool SWAP>
; DI void gemm_mainloop(f32x16 (&acc)[4][2], const u16* __restrict__ A, int lda, int rlo, int rhi,
;                       const u16* __restrict__ B, int ldb, int K, char* lds, const u16* zero_line) {
;     ...
;   auto ldfrag = [&](const char* st, int ks, int buf) {
;     const int co = ((2 * ks + h) ^ sw) << 4;
; #pragma unroll
;     for (int mi = 0; mi < 4; ++mi) fa[buf][mi] = *(const bf16x8*)(st + arow_off + mi * 4096 + co);
; #pragma unroll
;     for (int ni = 0; ni < 2; ++ni) fb[buf][ni] = *(const bf16x8*)(st + brow_off + ni * 4096 + co);
;   };
;   auto mma = [&](int buf) {
; #pragma unroll
;     for (int mi = 0; mi < 4; ++mi)
; #pragma unroll
;       for (int ni = 0; ni < 2; ++ni)
;         acc[mi][ni] = SWAP ? MFMA(fb[buf][ni], fa[buf][mi], acc[mi][ni]) : MFMA(fa[buf][mi], fb[buf][ni], acc[mi][ni]);
;   };
;   auto pat_rd = [&]() {
; #pragma unroll
;     for (int g = 0; g < 6; ++g) {
;       __builtin_amdgcn_sched_group_barrier(0x100, 1, 0);
;       __builtin_amdgcn_sched_group_barrier(0x008, 1, 0);
;     }
;     __builtin_amdgcn_sched_group_barrier(0x008, 2, 0);
;   };
; #pragma unroll 2
;   for (int kt = 0; kt < nk; ++kt) {
;     const char* st = lds + (kt & 1) * 65536;
;     ldfrag(st, 0, 0);
;     mma(1);
;     pat_rd();
;     if (kt + 1 < nk) glds(kt + 1, (kt + 1) & 1);
;     ldfrag(st, 1, 1);
;     mma(0);
;     pat_rd();
;     ldfrag(st, 2, 0);
;     mma(1);
;     pat_rd();
;     ldfrag(st, 3, 1);
;     mma(0);
;     pat_rd();
;     asm volatile("s_waitcnt vmcnt(0)" ::: "memory");
;     __syncthreads();
;   }
	s_waitcnt lgkmcnt(0)
	v_mfma_f32_32x32x16_bf16 v[114:129], v[176:179], v[130:133], v[114:129]
	v_mfma_f32_32x32x16_bf16 v[98:113], v[176:179], v[146:149], v[98:113]
	v_mfma_f32_32x32x16_bf16 v[114:129], v[180:183], v[134:137], v[114:129]
	v_mfma_f32_32x32x16_bf16 v[98:113], v[180:183], v[150:153], v[98:113]
	v_mfma_f32_32x32x16_bf16 v[114:129], v[192:195], v[138:141], v[114:129]
	v_mfma_f32_32x32x16_bf16 v[98:113], v[192:195], v[168:171], v[98:113]
	v_mfma_f32_32x32x16_bf16 v[114:129], v[196:199], v[142:145], v[114:129]
	v_mfma_f32_32x32x16_bf16 v[98:113], v[196:199], v[172:175], v[98:113]
	s_barrier
	v_add3_u32 v187, v186, v161, 0
	v_add3_u32 v248, v186, v163, 0
	ds_read_b128 v[200:203], v187 offset:49152
	ds_read_b128 v[228:231], v248 offset:49152
	v_add3_u32 v187, v186, v164, 0
	v_add3_u32 v248, v186, v165, 0
	ds_read_b128 v[232:235], v187 offset:49152
	ds_read_b128 v[236:239], v248 offset:49152
	s_barrier
	s_waitcnt lgkmcnt(0)
	v_mfma_f32_32x32x16_bf16 v[82:97], v[200:203], v[130:133], v[82:97]
	v_mfma_f32_32x32x16_bf16 v[50:65], v[200:203], v[146:149], v[50:65]
	v_mfma_f32_32x32x16_bf16 v[82:97], v[228:231], v[134:137], v[82:97]
	v_mfma_f32_32x32x16_bf16 v[50:65], v[228:231], v[150:153], v[50:65]
	v_mfma_f32_32x32x16_bf16 v[82:97], v[232:235], v[138:141], v[82:97]
	v_mfma_f32_32x32x16_bf16 v[50:65], v[232:235], v[168:171], v[50:65]
	v_mfma_f32_32x32x16_bf16 v[82:97], v[236:239], v[142:145], v[82:97]
	v_mfma_f32_32x32x16_bf16 v[50:65], v[236:239], v[172:175], v[50:65]
	s_barrier
	v_add3_u32 v187, v166, v161, 0
	v_add3_u32 v248, v166, v163, 0
	ds_read_b128 v[130:133], v187 offset:16384
	ds_read_b128 v[134:137], v248 offset:16384
	ds_read_b128 v[146:149], v187 offset:20480
	ds_read_b128 v[150:153], v248 offset:20480
	v_add3_u32 v187, v166, v164, 0
	v_add3_u32 v248, v166, v165, 0
	ds_read_b128 v[138:141], v187 offset:16384
	ds_read_b128 v[142:145], v248 offset:16384
	ds_read_b128 v[168:171], v187 offset:20480
	ds_read_b128 v[172:175], v248 offset:20480
	s_waitcnt vmcnt(4)
	s_barrier
	s_waitcnt lgkmcnt(0)
	v_mfma_f32_32x32x16_bf16 v[66:81], v[176:179], v[130:133], v[66:81]
	v_mfma_f32_32x32x16_bf16 v[34:49], v[176:179], v[146:149], v[34:49]
	v_mfma_f32_32x32x16_bf16 v[66:81], v[180:183], v[134:137], v[66:81]
	v_mfma_f32_32x32x16_bf16 v[34:49], v[180:183], v[150:153], v[34:49]
	v_mfma_f32_32x32x16_bf16 v[66:81], v[192:195], v[138:141], v[66:81]
	v_mfma_f32_32x32x16_bf16 v[34:49], v[192:195], v[168:171], v[34:49]
	v_mfma_f32_32x32x16_bf16 v[66:81], v[196:199], v[142:145], v[66:81]
	v_mfma_f32_32x32x16_bf16 v[34:49], v[196:199], v[172:175], v[34:49]
	v_mfma_f32_32x32x16_bf16 v[18:33], v[200:203], v[130:133], v[18:33]
	v_mfma_f32_32x32x16_bf16 v[2:17], v[200:203], v[146:149], v[2:17]
	v_mfma_f32_32x32x16_bf16 v[18:33], v[228:231], v[134:137], v[18:33]
	v_mfma_f32_32x32x16_bf16 v[2:17], v[228:231], v[150:153], v[2:17]
	v_mfma_f32_32x32x16_bf16 v[18:33], v[232:235], v[138:141], v[18:33]
	v_mfma_f32_32x32x16_bf16 v[2:17], v[232:235], v[168:171], v[2:17]
	v_mfma_f32_32x32x16_bf16 v[18:33], v[236:239], v[142:145], v[18:33]
	v_mfma_f32_32x32x16_bf16 v[2:17], v[236:239], v[172:175], v[2:17]
	s_barrier
	v_add3_u32 v187, v186, v161, s10
	v_add3_u32 v248, v186, v163, s10
	ds_read_b128 v[176:179], v187 offset:32768
	ds_read_b128 v[180:183], v248 offset:32768
	v_add3_u32 v187, v186, v164, s10
	v_add3_u32 v248, v186, v165, s10
	ds_read_b128 v[192:195], v187 offset:32768
	ds_read_b128 v[196:199], v248 offset:32768
	v_add3_u32 v187, v166, v161, s10
	v_add3_u32 v248, v166, v163, s10
	ds_read_b128 v[130:133], v187
	ds_read_b128 v[134:137], v248
	ds_read_b128 v[146:149], v187 offset:4096
	ds_read_b128 v[150:153], v248 offset:4096
	v_add3_u32 v187, v166, v164, s10
	v_add3_u32 v248, v166, v165, s10
	ds_read_b128 v[138:141], v187
	ds_read_b128 v[142:145], v248
	ds_read_b128 v[168:171], v187 offset:4096
	ds_read_b128 v[172:175], v248 offset:4096
	s_waitcnt vmcnt(2)
	s_barrier
	s_waitcnt lgkmcnt(0)
	v_mfma_f32_32x32x16_bf16 v[114:129], v[176:179], v[130:133], v[114:129]
	v_mfma_f32_32x32x16_bf16 v[98:113], v[176:179], v[146:149], v[98:113]
	v_mfma_f32_32x32x16_bf16 v[114:129], v[180:183], v[134:137], v[114:129]
	v_mfma_f32_32x32x16_bf16 v[98:113], v[180:183], v[150:153], v[98:113]
	v_mfma_f32_32x32x16_bf16 v[114:129], v[192:195], v[138:141], v[114:129]
	v_mfma_f32_32x32x16_bf16 v[98:113], v[192:195], v[168:171], v[98:113]
	v_mfma_f32_32x32x16_bf16 v[114:129], v[196:199], v[142:145], v[114:129]
	v_mfma_f32_32x32x16_bf16 v[98:113], v[196:199], v[172:175], v[98:113]
	s_barrier
	v_add3_u32 v187, v186, v161, s10
	v_add3_u32 v248, v186, v163, s10
	ds_read_b128 v[200:203], v187 offset:49152
	ds_read_b128 v[228:231], v248 offset:49152
	v_add3_u32 v187, v186, v164, s10
	v_add3_u32 v248, v186, v165, s10
	ds_read_b128 v[232:235], v187 offset:49152
	ds_read_b128 v[236:239], v248 offset:49152
	s_waitcnt vmcnt(0)
	s_barrier
	s_waitcnt lgkmcnt(0)
	v_mfma_f32_32x32x16_bf16 v[82:97], v[200:203], v[130:133], v[82:97]
	v_mfma_f32_32x32x16_bf16 v[50:65], v[200:203], v[146:149], v[50:65]
	v_mfma_f32_32x32x16_bf16 v[82:97], v[228:231], v[134:137], v[82:97]
	v_mfma_f32_32x32x16_bf16 v[50:65], v[228:231], v[150:153], v[50:65]
	v_mfma_f32_32x32x16_bf16 v[82:97], v[232:235], v[138:141], v[82:97]
	v_mfma_f32_32x32x16_bf16 v[50:65], v[232:235], v[168:171], v[50:65]
	v_mfma_f32_32x32x16_bf16 v[82:97], v[236:239], v[142:145], v[82:97]
	v_mfma_f32_32x32x16_bf16 v[50:65], v[236:239], v[172:175], v[50:65]
	s_barrier
; template <bool SWAP>
; DI void gemm_mainloop(f32x16 (&acc)[4][2], const u16* __restrict__ A, int lda, int rlo, int rhi,
;                       const u16* __restrict__ B, int ldb, int K, char* lds, const u16* zero_line) {
;     ...
;   const int gch = (lc ^ ((lr >> 1) & 7)) * 8;
;   const u16* ap = A + (ptrdiff_t)lr * lda + gch;
;   const u16* bp = B + (ptrdiff_t)lr * ldb + gch;
;   const int nk = K >> 6;
;   typedef __attribute__((address_space(3))) unsigned lds_u32;
;   auto glds = [&](int kt, int st) {
;     char* as_ = lds + st * 65536 + tid * 16;
; #pragma unroll
;     for (int i = 0; i < 4; ++i) {
;       const int rr = lr + 64 * i;
;       const u16* srca = (rr >= rlo && rr < rhi) ? (ap + (ptrdiff_t)(64 * i) * lda + kt * 64) : (zero_line + lc * 8);
;       __builtin_amdgcn_global_load_lds((const unsigned*)srca, (lds_u32*)(as_ + i * 8192), 16, 0, 0);
;       __builtin_amdgcn_global_load_lds((const unsigned*)(bp + (ptrdiff_t)(64 * i) * ldb + kt * 64), (lds_u32*)(as_ + 32768 + i * 8192), 16, 0, 0);
;     }
;   };
;     ...
;   auto ldfrag = [&](const char* st, int ks, int buf) {
;     const int co = ((2 * ks + h) ^ sw) << 4;
; #pragma unroll
;     for (int mi = 0; mi < 4; ++mi) fa[buf][mi] = *(const bf16x8*)(st + arow_off + mi * 4096 + co);
; #pragma unroll
;     for (int ni = 0; ni < 2; ++ni) fb[buf][ni] = *(const bf16x8*)(st + brow_off + ni * 4096 + co);
;   };
;   auto mma = [&](int buf) {
; #pragma unroll
;     for (int mi = 0; mi < 4; ++mi)
; #pragma unroll
;       for (int ni = 0; ni < 2; ++ni)
;         acc[mi][ni] = SWAP ? MFMA(fb[buf][ni], fa[buf][mi], acc[mi][ni]) : MFMA(fa[buf][mi], fb[buf][ni], acc[mi][ni]);
;   };
;   auto pat_rd = [&]() {
; #pragma unroll
;     for (int g = 0; g < 6; ++g) {
;       __builtin_amdgcn_sched_group_barrier(0x100, 1, 0);
;       __builtin_amdgcn_sched_group_barrier(0x008, 1, 0);
;     }
;     __builtin_amdgcn_sched_group_barrier(0x008, 2, 0);
;   };
; #pragma unroll 2
;   for (int kt = 0; kt < nk; ++kt) {
;     const char* st = lds + (kt & 1) * 65536;
;     ldfrag(st, 0, 0);
;     mma(1);
;     pat_rd();
;     if (kt + 1 < nk) glds(kt + 1, (kt + 1) & 1);
;     ldfrag(st, 1, 1);
;     mma(0);
;     pat_rd();
;     ldfrag(st, 2, 0);
;     mma(1);
;     pat_rd();
;     ldfrag(st, 3, 1);
;     mma(0);
;     pat_rd();
;     asm volatile("s_waitcnt vmcnt(0)" ::: "memory");
;     __syncthreads();
;   }
;   mma(1);
	v_add3_u32 v187, v166, v161, s10
	v_add3_u32 v248, v166, v163, s10
	ds_read_b128 v[130:133], v187 offset:16384
	ds_read_b128 v[134:137], v248 offset:16384
	ds_read_b128 v[146:149], v187 offset:20480
	ds_read_b128 v[150:153], v248 offset:20480
	v_add3_u32 v187, v166, v164, s10
	v_add3_u32 v248, v166, v165, s10
	ds_read_b128 v[138:141], v187 offset:16384
	ds_read_b128 v[142:145], v248 offset:16384
	ds_read_b128 v[168:171], v187 offset:20480
	ds_read_b128 v[172:175], v248 offset:20480
	s_barrier
	s_waitcnt lgkmcnt(0)
	v_mfma_f32_32x32x16_bf16 v[66:81], v[176:179], v[130:133], v[66:81]
	v_mfma_f32_32x32x16_bf16 v[34:49], v[176:179], v[146:149], v[34:49]
	v_mfma_f32_32x32x16_bf16 v[66:81], v[180:183], v[134:137], v[66:81]
	v_mfma_f32_32x32x16_bf16 v[34:49], v[180:183], v[150:153], v[34:49]
	v_mfma_f32_32x32x16_bf16 v[66:81], v[192:195], v[138:141], v[66:81]
	v_mfma_f32_32x32x16_bf16 v[34:49], v[192:195], v[168:171], v[34:49]
	v_mfma_f32_32x32x16_bf16 v[66:81], v[196:199], v[142:145], v[66:81]
	v_mfma_f32_32x32x16_bf16 v[34:49], v[196:199], v[172:175], v[34:49]
	v_mfma_f32_32x32x16_bf16 v[18:33], v[200:203], v[130:133], v[18:33]
	v_mfma_f32_32x32x16_bf16 v[2:17], v[200:203], v[146:149], v[2:17]
	v_mfma_f32_32x32x16_bf16 v[18:33], v[228:231], v[134:137], v[18:33]
	v_mfma_f32_32x32x16_bf16 v[2:17], v[228:231], v[150:153], v[2:17]
	v_mfma_f32_32x32x16_bf16 v[18:33], v[232:235], v[138:141], v[18:33]
	v_mfma_f32_32x32x16_bf16 v[2:17], v[232:235], v[168:171], v[2:17]
	v_mfma_f32_32x32x16_bf16 v[18:33], v[236:239], v[142:145], v[18:33]
	v_mfma_f32_32x32x16_bf16 v[2:17], v[236:239], v[172:175], v[2:17]
	s_barrier
	s_cmp_eq_u32 s101, 0
	s_cbranch_scc0 .Lg8_ia_p1
	s_barrier
.Lg8_ia_p1:
	s_nop 7
	s_nop 7
.LBB0_321:
	s_mov_b64 s[6:7], 0
.LBB0_322:
	s_and_b64 vcc, exec, s[6:7]
	s_cbranch_vccz .LBB0_328
	s_waitcnt vmcnt(5)
	s_nop 8
	v_mov_b32_e32 v10, v204
	s_nop 0
	v_ashrrev_i32_e32 v2, 3, v10
	v_lshrrev_b32_e32 v13, 1, v2
	v_xor_b32_e32 v0, v13, v10
	v_ashrrev_i32_e32 v3, 31, v2
	v_lshlrev_b64 v[4:5], 11, v[2:3]
	v_lshlrev_b32_e32 v0, 4, v0
	v_and_b32_e32 v12, 31, v10
	v_lshl_add_u64 v[6:7], s[14:15], 0, v[4:5]
	v_and_b32_e32 v0, 0x70, v0
	v_lshl_add_u64 v[8:9], s[20:21], 0, v[4:5]
	s_waitcnt vmcnt(4)
	v_lshrrev_b32_e32 v14, 1, v10
	v_lshl_add_u64 v[6:7], v[6:7], 0, v[0:1]
	v_lshl_add_u64 v[164:165], v[8:9], 0, v[0:1]
	v_and_or_b32 v0, v14, s51, v12
	v_lshlrev_b32_e32 v161, 7, v0
	v_lshlrev_b32_e32 v0, 7, v10
	v_lshlrev_b32_e32 v174, 4, v10
	v_and_b32_e32 v163, 0x6f80, v0
	v_and_b32_e32 v0, 0x70, v174
	v_add_u32_e32 v175, 0x8000, v174
	v_lshl_add_u64 v[166:167], s[80:81], 0, v[0:1]
	v_cmp_gt_u32_e32 vcc, s50, v2
	v_readfirstlane_b32 s6, v174
	s_mov_b32 m0, s6
	v_cndmask_b32_e32 v9, v167, v7, vcc
	v_cndmask_b32_e32 v8, v166, v6, vcc
	v_readfirstlane_b32 s6, v175
	v_add_u32_e32 v0, 64, v2
	s_barrier
	s_mov_b32 m0, s6
	s_mov_b64 s[10:11], 0x20000
	v_cmp_gt_u32_e64 s[6:7], s50, v0
	v_add_u32_e32 v0, 0x2000, v174
	v_lshl_add_u64 v[8:9], v[6:7], 0, s[10:11]
	v_readfirstlane_b32 s8, v0
	v_add_u32_e32 v176, 0xa000, v174
	v_cndmask_b32_e64 v9, v167, v9, s[6:7]
	v_cndmask_b32_e64 v8, v166, v8, s[6:7]
	s_mov_b32 m0, s8
	v_readfirstlane_b32 s8, v176
	v_lshl_add_u64 v[8:9], v[164:165], 0, s[10:11]
	s_mov_b32 m0, s8
	v_add_u32_e32 v3, 0x80, v2
	s_mov_b64 s[14:15], 0x40000
	v_add_u32_e32 v177, 0x4000, v174
	v_lshl_add_u64 v[8:9], v[6:7], 0, s[14:15]
	v_cmp_gt_u32_e64 s[8:9], s50, v3
	v_readfirstlane_b32 s10, v177
	v_add_u32_e32 v178, 0xc000, v174
	v_cndmask_b32_e64 v9, v167, v9, s[8:9]
	v_cndmask_b32_e64 v8, v166, v8, s[8:9]
	s_mov_b32 m0, s10
	v_readfirstlane_b32 s10, v178
	v_lshl_add_u64 v[8:9], v[164:165], 0, s[14:15]
	s_mov_b32 m0, s10
	s_mov_b64 s[20:21], 0x60000
	v_add_u32_e32 v8, 0xc0, v2
	v_add_u32_e32 v179, 0x6000, v174
	v_lshl_add_u64 v[2:3], v[6:7], 0, s[20:21]
	v_cmp_gt_u32_e64 s[10:11], s50, v8
	v_readfirstlane_b32 s14, v179
	v_add_u32_e32 v180, 0xe000, v174
	v_cndmask_b32_e64 v3, v167, v3, s[10:11]
	v_cndmask_b32_e64 v2, v166, v2, s[10:11]
	s_mov_b32 m0, s14
	v_readfirstlane_b32 s14, v180
	v_lshl_add_u64 v[2:3], v[164:165], 0, s[20:21]
	s_mov_b32 m0, s14
	v_bfe_u32 v11, v10, 5, 1
	s_sub_i32 s14, s26, s30
	s_lshl_b32 s15, s29, 6
	v_bfe_u32 v15, v10, 1, 3
	v_bitop3_b32 v2, v14, v11, 7 bitop3:0x6c
	s_sub_i32 s14, s14, s15
	v_lshlrev_b32_e32 v181, 4, v2
	v_bitop3_b32 v2, v11, v15, 2 bitop3:0x36
	s_lshl_b32 s14, s14, 8
	v_lshlrev_b32_e32 v182, 4, v2
	v_bitop3_b32 v2, v11, v15, 4 bitop3:0x36
	s_ashr_i32 s15, s14, 31
	v_lshlrev_b32_e32 v183, 4, v2
	v_bitop3_b32 v2, v11, v15, 6 bitop3:0x36
	s_lshl_b64 s[14:15], s[14:15], 11
	v_lshlrev_b32_e32 v186, 4, v2
	v_lshl_add_u64 v[2:3], v[4:5], 0, s[14:15]
	v_bitop3_b32 v4, v13, 7, v10 bitop3:0x48
	s_waitcnt vmcnt(0)
	v_lshl_or_b32 v2, v4, 4, v2
	v_lshl_add_u64 v[168:169], s[70:71], 0, v[2:3]
	v_mov_b32_e32 v130, 0
	v_mov_b32_e32 v2, 0
	s_mov_b32 s13, 1
	v_add_u32_e32 v187, 0x10000, v174
	v_add_u32_e32 v192, 0x18000, v174
	v_add_u32_e32 v193, 0x12000, v174
	v_add_u32_e32 v194, 0x1a000, v174
	v_add_u32_e32 v195, 0x14000, v174
	v_add_u32_e32 v196, 0x1c000, v174
	v_add_u32_e32 v197, 0x16000, v174
	v_add_u32_e32 v198, 0x1e000, v174
	v_add_u32_e32 v199, 0x10000, v161
	v_or_b32_e32 v200, 0x10000, v163
	s_mov_b64 s[14:15], 0
	v_mov_b32_e32 v3, v2
	v_mov_b32_e32 v4, v2
	v_mov_b32_e32 v5, v2
	v_mov_b32_e32 v6, v2
	v_mov_b32_e32 v7, v2
	v_mov_b32_e32 v8, v2
	v_mov_b32_e32 v9, v2
	v_mov_b32_e32 v10, v2
	v_mov_b32_e32 v11, v2
	v_mov_b32_e32 v12, v2
	v_mov_b32_e32 v13, v2
	v_mov_b32_e32 v14, v2
	v_mov_b32_e32 v15, v2
	v_mov_b32_e32 v16, v2
	v_mov_b32_e32 v17, v2
	v_mov_b32_e32 v34, v2
	v_mov_b32_e32 v35, v2
	v_mov_b32_e32 v36, v2
	v_mov_b32_e32 v37, v2
	v_mov_b32_e32 v38, v2
	v_mov_b32_e32 v39, v2
	v_mov_b32_e32 v40, v2
	v_mov_b32_e32 v41, v2
	v_mov_b32_e32 v42, v2
	v_mov_b32_e32 v43, v2
	v_mov_b32_e32 v44, v2
	v_mov_b32_e32 v45, v2
	v_mov_b32_e32 v46, v2
	v_mov_b32_e32 v47, v2
	v_mov_b32_e32 v48, v2
	v_mov_b32_e32 v49, v2
	s_waitcnt vmcnt(0)
; DI int opaque_tid() { int t = threadIdx.x; asm volatile("" : "+v"(t)); return t; }
; template <bool SWAP>
; DI void gemm_mainloop(f32x16 (&acc)[4][2], const u16* __restrict__ A, int lda, int rlo, int rhi,
;                       const u16* __restrict__ B, int ldb, int K, char* lds, const u16* zero_line) {
;   const int tid = opaque_tid(), lane = tid & 63, w = tid >> 6;
;   const int wm = w >> 2, wn = w & 3;
;   const int h = lane >> 5, r = lane & 31;
;   const int lr = tid >> 3, lc = tid & 7;
; #pragma unroll
;   for (int mi = 0; mi < 4; ++mi)
; #pragma unroll
;     for (int ni = 0; ni < 2; ++ni)
; #pragma unroll
;       for (int i = 0; i < 16; ++i) acc[mi][ni][i] = 0.f;
;   const int gch = (lc ^ ((lr >> 1) & 7)) * 8;
;   const u16* ap = A + (ptrdiff_t)lr * lda + gch;
;   const u16* bp = B + (ptrdiff_t)lr * ldb + gch;
;   const int nk = K >> 6;
;   typedef __attribute__((address_space(3))) unsigned lds_u32;
;   auto glds = [&](int kt, int st) {
;     char* as_ = lds + st * 65536 + tid * 16;
; #pragma unroll
;     for (int i = 0; i < 4; ++i) {
;       const int rr = lr + 64 * i;
;       const u16* srca = (rr >= rlo && rr < rhi) ? (ap + (ptrdiff_t)(64 * i) * lda + kt * 64) : (zero_line + lc * 8);
;       __builtin_amdgcn_global_load_lds((const unsigned*)srca, (lds_u32*)(as_ + i * 8192), 16, 0, 0);
;       __builtin_amdgcn_global_load_lds((const unsigned*)(bp + (ptrdiff_t)(64 * i) * ldb + kt * 64), (lds_u32*)(as_ + 32768 + i * 8192), 16, 0, 0);
;     }
;   };
;   const int sw = (r >> 1) & 7;
;   const int arow_off = (wm * 128 + r) * 128;
;   const int brow_off = 32768 + (wn * 64 + r) * 128;
;   __syncthreads();
;   glds(0, 0);
;   asm volatile("s_waitcnt vmcnt(0)" ::: "memory");
;   __syncthreads();
	v_mov_b32_e32 v18, v2
	v_mov_b32_e32 v19, v2
	v_mov_b32_e32 v20, v2
	v_mov_b32_e32 v21, v2
	v_mov_b32_e32 v22, v2
	v_mov_b32_e32 v23, v2
	v_mov_b32_e32 v24, v2
	v_mov_b32_e32 v25, v2
	v_mov_b32_e32 v26, v2
	v_mov_b32_e32 v27, v2
	v_mov_b32_e32 v28, v2
	v_mov_b32_e32 v29, v2
	v_mov_b32_e32 v30, v2
	v_mov_b32_e32 v31, v2
	v_mov_b32_e32 v32, v2
	v_mov_b32_e32 v33, v2
	v_mov_b32_e32 v66, v2
	v_mov_b32_e32 v67, v2
	v_mov_b32_e32 v68, v2
	v_mov_b32_e32 v69, v2
	v_mov_b32_e32 v70, v2
	v_mov_b32_e32 v71, v2
	v_mov_b32_e32 v72, v2
	v_mov_b32_e32 v73, v2
	v_mov_b32_e32 v74, v2
	v_mov_b32_e32 v75, v2
	v_mov_b32_e32 v76, v2
	v_mov_b32_e32 v77, v2
	v_mov_b32_e32 v78, v2
	v_mov_b32_e32 v79, v2
	v_mov_b32_e32 v80, v2
	v_mov_b32_e32 v81, v2
	v_mov_b32_e32 v50, v2
	v_mov_b32_e32 v51, v2
	v_mov_b32_e32 v52, v2
	v_mov_b32_e32 v53, v2
	v_mov_b32_e32 v54, v2
	v_mov_b32_e32 v55, v2
	v_mov_b32_e32 v56, v2
	v_mov_b32_e32 v57, v2
	v_mov_b32_e32 v58, v2
	v_mov_b32_e32 v59, v2
	v_mov_b32_e32 v60, v2
	v_mov_b32_e32 v61, v2
	v_mov_b32_e32 v62, v2
	v_mov_b32_e32 v63, v2
	v_mov_b32_e32 v64, v2
	v_mov_b32_e32 v65, v2
	v_mov_b32_e32 v98, v2
	v_mov_b32_e32 v99, v2
	v_mov_b32_e32 v100, v2
	v_mov_b32_e32 v101, v2
	v_mov_b32_e32 v102, v2
	v_mov_b32_e32 v103, v2
	v_mov_b32_e32 v104, v2
	v_mov_b32_e32 v105, v2
	v_mov_b32_e32 v106, v2
	v_mov_b32_e32 v107, v2
	v_mov_b32_e32 v108, v2
	v_mov_b32_e32 v109, v2
	v_mov_b32_e32 v110, v2
	v_mov_b32_e32 v111, v2
	v_mov_b32_e32 v112, v2
	v_mov_b32_e32 v113, v2
	v_mov_b32_e32 v82, v2
	v_mov_b32_e32 v83, v2
	v_mov_b32_e32 v84, v2
	v_mov_b32_e32 v85, v2
	v_mov_b32_e32 v86, v2
	v_mov_b32_e32 v87, v2
	v_mov_b32_e32 v88, v2
	v_mov_b32_e32 v89, v2
	v_mov_b32_e32 v90, v2
	v_mov_b32_e32 v91, v2
	v_mov_b32_e32 v92, v2
	v_mov_b32_e32 v93, v2
	v_mov_b32_e32 v94, v2
	v_mov_b32_e32 v95, v2
	v_mov_b32_e32 v96, v2
	v_mov_b32_e32 v97, v2
	v_mov_b32_e32 v114, v2
	v_mov_b32_e32 v115, v2
	v_mov_b32_e32 v116, v2
	v_mov_b32_e32 v117, v2
	v_mov_b32_e32 v118, v2
	v_mov_b32_e32 v119, v2
	v_mov_b32_e32 v120, v2
	v_mov_b32_e32 v121, v2
	v_mov_b32_e32 v122, v2
	v_mov_b32_e32 v123, v2
	v_mov_b32_e32 v124, v2
	v_mov_b32_e32 v125, v2
	v_mov_b32_e32 v126, v2
	v_mov_b32_e32 v127, v2
	v_mov_b32_e32 v128, v2
	v_mov_b32_e32 v129, v2
	v_mov_b32_e32 v131, v130
	v_mov_b32_e32 v132, v130
	v_mov_b32_e32 v133, v130
	v_mov_b32_e32 v134, v130
	v_mov_b32_e32 v135, v130
	v_mov_b32_e32 v136, v130
	v_mov_b32_e32 v137, v130
	v_mov_b32_e32 v138, v130
	v_mov_b32_e32 v139, v130
	v_mov_b32_e32 v140, v130
	v_mov_b32_e32 v141, v130
	v_mov_b32_e32 v146, v130
	v_mov_b32_e32 v147, v130
	v_mov_b32_e32 v148, v130
	v_mov_b32_e32 v149, v130
	v_mov_b32_e32 v142, v130
	v_mov_b32_e32 v143, v130
	v_mov_b32_e32 v144, v130
	v_mov_b32_e32 v145, v130
	v_mov_b32_e32 v150, v130
	v_mov_b32_e32 v151, v130
	v_mov_b32_e32 v152, v130
	v_mov_b32_e32 v153, v130
	s_waitcnt lgkmcnt(0)
	s_barrier
	s_ashr_i32 s7, s12, 31
	s_mov_b32 s6, s12
	s_lshl_b64 s[6:7], s[6:7], 11
	s_add_u32 s6, s90, s6
	s_addc_u32 s7, s91, s7
	s_ashr_i32 s9, s16, 31
	s_mov_b32 s8, s16
	s_lshl_b64 s[8:9], s[8:9], 11
	s_add_u32 s8, s70, s8
	s_addc_u32 s9, s71, s9
	v_and_b32_e32 v130, 63, v204
	v_lshrrev_b32_e32 v131, 6, v204
	v_lshrrev_b32_e32 v132, 3, v204
	v_lshrrev_b32_e32 v0, 4, v130
	v_lshl_add_u32 v0, v131, 2, v0
	v_xor_b32_e32 v0, v0, v130
	v_and_b32_e32 v0, 7, v0
	v_lshlrev_b32_e32 v133, 4, v0
	v_lshl_add_u32 v240, v132, 11, v133
	v_add_u32_e32 v241, 0x20000, v240
	v_add_u32_e32 v242, 0x40000, v240
	v_add_u32_e32 v243, 0x60000, v240
	v_and_b32_e32 v0, 31, v132
	v_lshrrev_b32_e32 v130, 5, v132
	v_lshl_add_u32 v0, v130, 6, v0
	v_lshl_add_u32 v244, v0, 11, v133
	v_add_u32_e32 v245, 0x10000, v244
	v_add_u32_e32 v246, 0x40000, v244
	v_add_u32_e32 v247, 0x50000, v244
	v_and_b32_e32 v132, 31, v204
	v_lshrrev_b32_e32 v0, 2, v131
	v_lshl_add_u32 v0, v0, 6, v132
	v_lshlrev_b32_e32 v166, 7, v0
	v_and_b32_e32 v0, 3, v131
	v_lshl_add_u32 v0, v0, 5, v132
	v_lshlrev_b32_e32 v186, 7, v0
	v_bfe_u32 v0, v204, 5, 1
	v_bfe_u32 v130, v132, 1, 3
	v_or_b32_e32 v133, 0, v0
	v_xor_b32_e32 v133, v133, v130
	v_lshlrev_b32_e32 v161, 4, v133
	v_or_b32_e32 v133, 2, v0
	v_xor_b32_e32 v133, v133, v130
	v_lshlrev_b32_e32 v163, 4, v133
	v_or_b32_e32 v133, 4, v0
	v_xor_b32_e32 v133, v133, v130
	v_lshlrev_b32_e32 v164, 4, v133
	v_or_b32_e32 v133, 6, v0
	v_xor_b32_e32 v133, v133, v130
	v_lshlrev_b32_e32 v165, 4, v133
	v_lshlrev_b32_e32 v131, 10, v131
	s_nop 0
	v_readfirstlane_b32 s100, v131
	v_mov_b32_e32 v146, 0
	v_mov_b32_e32 v147, 0
	v_mov_b32_e32 v148, 0
	v_mov_b32_e32 v149, 0
	v_lshlrev_b32_e32 v130, 4, v204
	v_add_u32_e32 v132, 0x10000, v130
	s_mov_b64 exec, -1
	s_mov_b32 s11, 0
	s_mov_b32 s10, 0x10000
	s_waitcnt lgkmcnt(0)
	s_add_u32 m0, s100, 0x8000
	s_nop 0
	global_load_lds_dwordx4 v244, s[8:9]
	v_add_u32_e32 v244, 0x80, v244
	s_add_u32 m0, s100, 0xa000
	s_nop 0
	global_load_lds_dwordx4 v246, s[8:9]
	v_add_u32_e32 v246, 0x80, v246
	s_add_u32 m0, s100, 0x0
	s_nop 0
	global_load_lds_dwordx4 v240, s[6:7]
	v_add_u32_e32 v240, 0x80, v240
	s_add_u32 m0, s100, 0x2000
	s_nop 0
	global_load_lds_dwordx4 v242, s[6:7]
	v_add_u32_e32 v242, 0x80, v242
	s_add_u32 m0, s100, 0xc000
	s_nop 0
	global_load_lds_dwordx4 v245, s[8:9]
	v_add_u32_e32 v245, 0x80, v245
	s_add_u32 m0, s100, 0xe000
	s_nop 0
	global_load_lds_dwordx4 v247, s[8:9]
	v_add_u32_e32 v247, 0x80, v247
	s_add_u32 m0, s100, 0x4000
	s_nop 0
	global_load_lds_dwordx4 v241, s[6:7]
	v_add_u32_e32 v241, 0x80, v241
	s_add_u32 m0, s100, 0x6000
	s_nop 0
	global_load_lds_dwordx4 v243, s[6:7]
	v_add_u32_e32 v243, 0x80, v243
	s_cmp_eq_u32 s101, 1
	s_cbranch_scc0 .Lg8_ib_p0
	s_barrier

; #define MFMA(a, b, c) __builtin_amdgcn_mfma_f32_32x32x16_bf16((a), (b), (c), 0, 0, 0)
; template <bool SWAP>
; DI void gemm_mainloop(f32x16 (&acc)[4][2], const u16* __restrict__ A, int lda, int rlo, int rhi,
;                       const u16* __restrict__ B, int ldb, int K, char* lds, const u16* zero_line) {
;     ...
;   auto ldfrag = [&](const char* st, int ks, int buf) {
;     const int co = ((2 * ks + h) ^ sw) << 4;
; #pragma unroll
;     for (int mi = 0; mi < 4; ++mi) fa[buf][mi] = *(const bf16x8*)(st + arow_off + mi * 4096 + co);
; #pragma unroll
;     for (int ni = 0; ni < 2; ++ni) fb[buf][ni] = *(const bf16x8*)(st + brow_off + ni * 4096 + co);
;   };
;   auto mma = [&](int buf) {
; #pragma unroll
;     for (int mi = 0; mi < 4; ++mi)
; #pragma unroll
;       for (int ni = 0; ni < 2; ++ni)
;         acc[mi][ni] = SWAP ? MFMA(fb[buf][ni], fa[buf][mi], acc[mi][ni]) : MFMA(fa[buf][mi], fb[buf][ni], acc[mi][ni]);
;   };
;   auto pat_rd = [&]() {
; #pragma unroll
;     for (int g = 0; g < 6; ++g) {
;       __builtin_amdgcn_sched_group_barrier(0x100, 1, 0);
;       __builtin_amdgcn_sched_group_barrier(0x008, 1, 0);
;     }
;     __builtin_amdgcn_sched_group_barrier(0x008, 2, 0);
;   };
; #pragma unroll 2
;   for (int kt = 0; kt < nk; ++kt) {
;     const char* st = lds + (kt & 1) * 65536;
;     ldfrag(st, 0, 0);
;     mma(1);
;     pat_rd();
;     if (kt + 1 < nk) glds(kt + 1, (kt + 1) & 1);
;     ldfrag(st, 1, 1);
;     mma(0);
;     pat_rd();
;     ldfrag(st, 2, 0);
;     mma(1);
;     pat_rd();
;     ldfrag(st, 3, 1);
;     mma(0);
;     pat_rd();
;     asm volatile("s_waitcnt vmcnt(0)" ::: "memory");
;     __syncthreads();
;   }
.Lg8_ib:
	v_add3_u32 v187, v186, v161, 0
	v_add3_u32 v248, v186, v163, 0
	ds_read_b128 v[176:179], v187 offset:32768
	ds_read_b128 v[180:183], v248 offset:32768
	v_add3_u32 v187, v186, v164, 0
	v_add3_u32 v248, v186, v165, 0
	ds_read_b128 v[192:195], v187 offset:32768
	ds_read_b128 v[196:199], v248 offset:32768
	v_add3_u32 v187, v166, v161, 0
	v_add3_u32 v248, v166, v163, 0
	ds_read_b128 v[130:133], v187
	ds_read_b128 v[134:137], v248
	ds_read_b128 v[146:149], v187 offset:4096
	ds_read_b128 v[150:153], v248 offset:4096
	v_add3_u32 v187, v166, v164, 0
	v_add3_u32 v248, v166, v165, 0
	ds_read_b128 v[138:141], v187
	ds_read_b128 v[142:145], v248
	ds_read_b128 v[168:171], v187 offset:4096
	ds_read_b128 v[172:175], v248 offset:4096
	s_add_u32 m0, s100, 0x14000
	s_nop 0
	global_load_lds_dwordx4 v241, s[6:7]
	v_add_u32_e32 v241, 0x80, v241
	s_add_u32 m0, s100, 0x16000
	s_nop 0
	global_load_lds_dwordx4 v243, s[6:7]
	v_add_u32_e32 v243, 0x80, v243
	s_waitcnt lgkmcnt(8)
	s_barrier
	s_waitcnt lgkmcnt(0)
	v_mfma_f32_32x32x16_bf16 v[114:129], v[130:133], v[176:179], v[114:129]
	v_mfma_f32_32x32x16_bf16 v[98:113], v[146:149], v[176:179], v[98:113]
	v_mfma_f32_32x32x16_bf16 v[114:129], v[134:137], v[180:183], v[114:129]
	v_mfma_f32_32x32x16_bf16 v[98:113], v[150:153], v[180:183], v[98:113]
	v_mfma_f32_32x32x16_bf16 v[114:129], v[138:141], v[192:195], v[114:129]
	v_mfma_f32_32x32x16_bf16 v[98:113], v[168:171], v[192:195], v[98:113]
	v_mfma_f32_32x32x16_bf16 v[114:129], v[142:145], v[196:199], v[114:129]
	v_mfma_f32_32x32x16_bf16 v[98:113], v[172:175], v[196:199], v[98:113]
	s_barrier
	v_add3_u32 v187, v186, v161, 0
	v_add3_u32 v248, v186, v163, 0
	ds_read_b128 v[200:203], v187 offset:49152
	ds_read_b128 v[228:231], v248 offset:49152
	v_add3_u32 v187, v186, v164, 0
	v_add3_u32 v248, v186, v165, 0
	ds_read_b128 v[232:235], v187 offset:49152
	ds_read_b128 v[236:239], v248 offset:49152
	s_add_u32 m0, s100, 0x8000
	s_nop 0
	global_load_lds_dwordx4 v244, s[8:9]
	v_add_u32_e32 v244, 0x80, v244
	s_add_u32 m0, s100, 0xa000
	s_nop 0
	global_load_lds_dwordx4 v246, s[8:9]
	v_add_u32_e32 v246, 0x80, v246
	s_barrier
	s_waitcnt lgkmcnt(0)
	v_mfma_f32_32x32x16_bf16 v[82:97], v[130:133], v[200:203], v[82:97]
	v_mfma_f32_32x32x16_bf16 v[50:65], v[146:149], v[200:203], v[50:65]
	v_mfma_f32_32x32x16_bf16 v[82:97], v[134:137], v[228:231], v[82:97]
	v_mfma_f32_32x32x16_bf16 v[50:65], v[150:153], v[228:231], v[50:65]
	v_mfma_f32_32x32x16_bf16 v[82:97], v[138:141], v[232:235], v[82:97]
	v_mfma_f32_32x32x16_bf16 v[50:65], v[168:171], v[232:235], v[50:65]
	v_mfma_f32_32x32x16_bf16 v[82:97], v[142:145], v[236:239], v[82:97]
	v_mfma_f32_32x32x16_bf16 v[50:65], v[172:175], v[236:239], v[50:65]
	s_barrier
	v_add3_u32 v187, v166, v161, 0
	v_add3_u32 v248, v166, v163, 0
	ds_read_b128 v[130:133], v187 offset:16384
	ds_read_b128 v[134:137], v248 offset:16384
	ds_read_b128 v[146:149], v187 offset:20480
	ds_read_b128 v[150:153], v248 offset:20480
	v_add3_u32 v187, v166, v164, 0
	v_add3_u32 v248, v166, v165, 0
	ds_read_b128 v[138:141], v187 offset:16384
	ds_read_b128 v[142:145], v248 offset:16384
	ds_read_b128 v[168:171], v187 offset:20480
	ds_read_b128 v[172:175], v248 offset:20480
	s_add_u32 m0, s100, 0x0
	s_nop 0
	global_load_lds_dwordx4 v240, s[6:7]
	v_add_u32_e32 v240, 0x80, v240
	s_add_u32 m0, s100, 0x2000
	s_nop 0
	global_load_lds_dwordx4 v242, s[6:7]
	v_add_u32_e32 v242, 0x80, v242
	s_barrier
	s_waitcnt lgkmcnt(0)
	v_mfma_f32_32x32x16_bf16 v[66:81], v[130:133], v[176:179], v[66:81]
	v_mfma_f32_32x32x16_bf16 v[34:49], v[146:149], v[176:179], v[34:49]
	v_mfma_f32_32x32x16_bf16 v[66:81], v[134:137], v[180:183], v[66:81]
	v_mfma_f32_32x32x16_bf16 v[34:49], v[150:153], v[180:183], v[34:49]
	v_mfma_f32_32x32x16_bf16 v[66:81], v[138:141], v[192:195], v[66:81]
	v_mfma_f32_32x32x16_bf16 v[34:49], v[168:171], v[192:195], v[34:49]
	v_mfma_f32_32x32x16_bf16 v[66:81], v[142:145], v[196:199], v[66:81]
	v_mfma_f32_32x32x16_bf16 v[34:49], v[172:175], v[196:199], v[34:49]
	s_barrier
	s_add_u32 m0, s100, 0xc000
	s_nop 0
	global_load_lds_dwordx4 v245, s[8:9]
	v_add_u32_e32 v245, 0x80, v245
	s_add_u32 m0, s100, 0xe000
	s_nop 0
	global_load_lds_dwordx4 v247, s[8:9]
	v_add_u32_e32 v247, 0x80, v247
	s_waitcnt vmcnt(6)
	s_barrier
	v_mfma_f32_32x32x16_bf16 v[18:33], v[130:133], v[200:203], v[18:33]
	v_mfma_f32_32x32x16_bf16 v[2:17], v[146:149], v[200:203], v[2:17]
	v_mfma_f32_32x32x16_bf16 v[18:33], v[134:137], v[228:231], v[18:33]
	v_mfma_f32_32x32x16_bf16 v[2:17], v[150:153], v[228:231], v[2:17]
	v_mfma_f32_32x32x16_bf16 v[18:33], v[138:141], v[232:235], v[18:33]
	v_mfma_f32_32x32x16_bf16 v[2:17], v[168:171], v[232:235], v[2:17]
	v_mfma_f32_32x32x16_bf16 v[18:33], v[142:145], v[236:239], v[18:33]
	v_mfma_f32_32x32x16_bf16 v[2:17], v[172:175], v[236:239], v[2:17]
	s_barrier
	v_add3_u32 v187, v186, v161, s10
	v_add3_u32 v248, v186, v163, s10
	ds_read_b128 v[176:179], v187 offset:32768
	ds_read_b128 v[180:183], v248 offset:32768
	v_add3_u32 v187, v186, v164, s10
	v_add3_u32 v248, v186, v165, s10
	ds_read_b128 v[192:195], v187 offset:32768
	ds_read_b128 v[196:199], v248 offset:32768
	v_add3_u32 v187, v166, v161, s10
	v_add3_u32 v248, v166, v163, s10
	ds_read_b128 v[130:133], v187
	ds_read_b128 v[134:137], v248
	ds_read_b128 v[146:149], v187 offset:4096
	ds_read_b128 v[150:153], v248 offset:4096
	v_add3_u32 v187, v166, v164, s10
	v_add3_u32 v248, v166, v165, s10
	ds_read_b128 v[138:141], v187
	ds_read_b128 v[142:145], v248
	ds_read_b128 v[168:171], v187 offset:4096
	ds_read_b128 v[172:175], v248 offset:4096
	s_add_u32 m0, s100, 0x4000
	s_nop 0
	global_load_lds_dwordx4 v241, s[6:7]
	v_add_u32_e32 v241, 0x80, v241
	s_add_u32 m0, s100, 0x6000
	s_nop 0
	global_load_lds_dwordx4 v243, s[6:7]
	v_add_u32_e32 v243, 0x80, v243
	s_waitcnt lgkmcnt(8)
	s_barrier
; template <bool SWAP>
; DI void gemm_mainloop(f32x16 (&acc)[4][2], const u16* __restrict__ A, int lda, int rlo, int rhi,
;                       const u16* __restrict__ B, int ldb, int K, char* lds, const u16* zero_line) {
;     ...
; #pragma unroll 2
;   for (int kt = 0; kt < nk; ++kt) {
;     const char* st = lds + (kt & 1) * 65536;
;     ldfrag(st, 0, 0);
;     mma(1);
;     pat_rd();
;     if (kt + 1 < nk) glds(kt + 1, (kt + 1) & 1);
;     ldfrag(st, 1, 1);
;     mma(0);
;     pat_rd();
;     ldfrag(st, 2, 0);
;     mma(1);
;     pat_rd();
;     ldfrag(st, 3, 1);
;     mma(0);
;     pat_rd();
;     asm volatile("s_waitcnt vmcnt(0)" ::: "memory");
;     __syncthreads();
;   }
	s_waitcnt lgkmcnt(0)
	v_mfma_f32_32x32x16_bf16 v[114:129], v[130:133], v[176:179], v[114:129]
	v_mfma_f32_32x32x16_bf16 v[98:113], v[146:149], v[176:179], v[98:113]
	v_mfma_f32_32x32x16_bf16 v[114:129], v[134:137], v[180:183], v[114:129]
	v_mfma_f32_32x32x16_bf16 v[98:113], v[150:153], v[180:183], v[98:113]
	v_mfma_f32_32x32x16_bf16 v[114:129], v[138:141], v[192:195], v[114:129]
	v_mfma_f32_32x32x16_bf16 v[98:113], v[168:171], v[192:195], v[98:113]
	v_mfma_f32_32x32x16_bf16 v[114:129], v[142:145], v[196:199], v[114:129]
	v_mfma_f32_32x32x16_bf16 v[98:113], v[172:175], v[196:199], v[98:113]
	s_barrier
	v_add3_u32 v187, v186, v161, s10
	v_add3_u32 v248, v186, v163, s10
	ds_read_b128 v[200:203], v187 offset:49152
	ds_read_b128 v[228:231], v248 offset:49152
	v_add3_u32 v187, v186, v164, s10
	v_add3_u32 v248, v186, v165, s10
	ds_read_b128 v[232:235], v187 offset:49152
	ds_read_b128 v[236:239], v248 offset:49152
	s_add_u32 m0, s100, 0x18000
	s_nop 0
	global_load_lds_dwordx4 v244, s[8:9]
	v_add_u32_e32 v244, 0x80, v244
	s_add_u32 m0, s100, 0x1a000
	s_nop 0
	global_load_lds_dwordx4 v246, s[8:9]
	v_add_u32_e32 v246, 0x80, v246
	s_barrier
	s_waitcnt lgkmcnt(0)
	v_mfma_f32_32x32x16_bf16 v[82:97], v[130:133], v[200:203], v[82:97]
	v_mfma_f32_32x32x16_bf16 v[50:65], v[146:149], v[200:203], v[50:65]
	v_mfma_f32_32x32x16_bf16 v[82:97], v[134:137], v[228:231], v[82:97]
	v_mfma_f32_32x32x16_bf16 v[50:65], v[150:153], v[228:231], v[50:65]
	v_mfma_f32_32x32x16_bf16 v[82:97], v[138:141], v[232:235], v[82:97]
	v_mfma_f32_32x32x16_bf16 v[50:65], v[168:171], v[232:235], v[50:65]
	v_mfma_f32_32x32x16_bf16 v[82:97], v[142:145], v[236:239], v[82:97]
	v_mfma_f32_32x32x16_bf16 v[50:65], v[172:175], v[236:239], v[50:65]
	s_barrier
	v_add3_u32 v187, v166, v161, s10
	v_add3_u32 v248, v166, v163, s10
	ds_read_b128 v[130:133], v187 offset:16384
	ds_read_b128 v[134:137], v248 offset:16384
	ds_read_b128 v[146:149], v187 offset:20480
	ds_read_b128 v[150:153], v248 offset:20480
	v_add3_u32 v187, v166, v164, s10
	v_add3_u32 v248, v166, v165, s10
	ds_read_b128 v[138:141], v187 offset:16384
	ds_read_b128 v[142:145], v248 offset:16384
	ds_read_b128 v[168:171], v187 offset:20480
	ds_read_b128 v[172:175], v248 offset:20480
	s_add_u32 m0, s100, 0x10000
	s_nop 0
	global_load_lds_dwordx4 v240, s[6:7]
	v_add_u32_e32 v240, 0x80, v240
	s_add_u32 m0, s100, 0x12000
	s_nop 0
	global_load_lds_dwordx4 v242, s[6:7]
	v_add_u32_e32 v242, 0x80, v242
	s_barrier
	s_waitcnt lgkmcnt(0)
	v_mfma_f32_32x32x16_bf16 v[66:81], v[130:133], v[176:179], v[66:81]
	v_mfma_f32_32x32x16_bf16 v[34:49], v[146:149], v[176:179], v[34:49]
	v_mfma_f32_32x32x16_bf16 v[66:81], v[134:137], v[180:183], v[66:81]
	v_mfma_f32_32x32x16_bf16 v[34:49], v[150:153], v[180:183], v[34:49]
	v_mfma_f32_32x32x16_bf16 v[66:81], v[138:141], v[192:195], v[66:81]
	v_mfma_f32_32x32x16_bf16 v[34:49], v[168:171], v[192:195], v[34:49]
	v_mfma_f32_32x32x16_bf16 v[66:81], v[142:145], v[196:199], v[66:81]
	v_mfma_f32_32x32x16_bf16 v[34:49], v[172:175], v[196:199], v[34:49]
	s_barrier
	s_add_u32 m0, s100, 0x1c000
	s_nop 0
	global_load_lds_dwordx4 v245, s[8:9]
	v_add_u32_e32 v245, 0x80, v245
	s_add_u32 m0, s100, 0x1e000
	s_nop 0
	global_load_lds_dwordx4 v247, s[8:9]
	v_add_u32_e32 v247, 0x80, v247
	s_waitcnt vmcnt(6)
	s_barrier
	v_mfma_f32_32x32x16_bf16 v[18:33], v[130:133], v[200:203], v[18:33]
	v_mfma_f32_32x32x16_bf16 v[2:17], v[146:149], v[200:203], v[2:17]
	v_mfma_f32_32x32x16_bf16 v[18:33], v[134:137], v[228:231], v[18:33]
	v_mfma_f32_32x32x16_bf16 v[2:17], v[150:153], v[228:231], v[2:17]
	v_mfma_f32_32x32x16_bf16 v[18:33], v[138:141], v[232:235], v[18:33]
	v_mfma_f32_32x32x16_bf16 v[2:17], v[168:171], v[232:235], v[2:17]
	v_mfma_f32_32x32x16_bf16 v[18:33], v[142:145], v[236:239], v[18:33]
	v_mfma_f32_32x32x16_bf16 v[2:17], v[172:175], v[236:239], v[2:17]
	s_barrier
	s_add_i32 s11, s11, 2
	s_cmp_lt_u32 s11, 14
	s_cbranch_scc1 .Lg8_ib
	v_add3_u32 v187, v186, v161, 0
	v_add3_u32 v248, v186, v163, 0
	ds_read_b128 v[176:179], v187 offset:32768
	ds_read_b128 v[180:183], v248 offset:32768
	v_add3_u32 v187, v186, v164, 0
	v_add3_u32 v248, v186, v165, 0
	ds_read_b128 v[192:195], v187 offset:32768
	ds_read_b128 v[196:199], v248 offset:32768
	v_add3_u32 v187, v166, v161, 0
	v_add3_u32 v248, v166, v163, 0
	ds_read_b128 v[130:133], v187
	ds_read_b128 v[134:137], v248
	ds_read_b128 v[146:149], v187 offset:4096
	ds_read_b128 v[150:153], v248 offset:4096
	v_add3_u32 v187, v166, v164, 0
	v_add3_u32 v248, v166, v165, 0
	ds_read_b128 v[138:141], v187
	ds_read_b128 v[142:145], v248
	ds_read_b128 v[168:171], v187 offset:4096
	ds_read_b128 v[172:175], v248 offset:4096
	s_add_u32 m0, s100, 0x14000
	s_nop 0
	global_load_lds_dwordx4 v241, s[6:7]
	v_add_u32_e32 v241, 0x80, v241
	s_add_u32 m0, s100, 0x16000
	s_nop 0
	global_load_lds_dwordx4 v243, s[6:7]
	v_add_u32_e32 v243, 0x80, v243
	s_barrier
	s_waitcnt lgkmcnt(0)
	v_mfma_f32_32x32x16_bf16 v[114:129], v[130:133], v[176:179], v[114:129]
	v_mfma_f32_32x32x16_bf16 v[98:113], v[146:149], v[176:179], v[98:113]
	v_mfma_f32_32x32x16_bf16 v[114:129], v[134:137], v[180:183], v[114:129]
	v_mfma_f32_32x32x16_bf16 v[98:113], v[150:153], v[180:183], v[98:113]
	v_mfma_f32_32x32x16_bf16 v[114:129], v[138:141], v[192:195], v[114:129]
	v_mfma_f32_32x32x16_bf16 v[98:113], v[168:171], v[192:195], v[98:113]
	v_mfma_f32_32x32x16_bf16 v[114:129], v[142:145], v[196:199], v[114:129]
	v_mfma_f32_32x32x16_bf16 v[98:113], v[172:175], v[196:199], v[98:113]
	s_barrier
	v_add3_u32 v187, v186, v161, 0
	v_add3_u32 v248, v186, v163, 0
	ds_read_b128 v[200:203], v187 offset:49152
	ds_read_b128 v[228:231], v248 offset:49152
	v_add3_u32 v187, v186, v164, 0
	v_add3_u32 v248, v186, v165, 0
	ds_read_b128 v[232:235], v187 offset:49152
	ds_read_b128 v[236:239], v248 offset:49152
	s_barrier
; template <bool SWAP>
; DI void gemm_mainloop(f32x16 (&acc)[4][2], const u16* __restrict__ A, int lda, int rlo, int rhi,
;                       const u16* __restrict__ B, int ldb, int K, char* lds, const u16* zero_line) {
;     ...
; #pragma unroll 2
;   for (int kt = 0; kt < nk; ++kt) {
;     const char* st = lds + (kt & 1) * 65536;
;     ldfrag(st, 0, 0);
;     mma(1);
;     pat_rd();
;     if (kt + 1 < nk) glds(kt + 1, (kt + 1) & 1);
;     ldfrag(st, 1, 1);
;     mma(0);
;     pat_rd();
;     ldfrag(st, 2, 0);
;     mma(1);
;     pat_rd();
;     ldfrag(st, 3, 1);
;     mma(0);
;     pat_rd();
;     asm volatile("s_waitcnt vmcnt(0)" ::: "memory");
;     __syncthreads();
;   }
;   mma(1);
	s_waitcnt lgkmcnt(0)
	v_mfma_f32_32x32x16_bf16 v[82:97], v[130:133], v[200:203], v[82:97]
	v_mfma_f32_32x32x16_bf16 v[50:65], v[146:149], v[200:203], v[50:65]
	v_mfma_f32_32x32x16_bf16 v[82:97], v[134:137], v[228:231], v[82:97]
	v_mfma_f32_32x32x16_bf16 v[50:65], v[150:153], v[228:231], v[50:65]
	v_mfma_f32_32x32x16_bf16 v[82:97], v[138:141], v[232:235], v[82:97]
	v_mfma_f32_32x32x16_bf16 v[50:65], v[168:171], v[232:235], v[50:65]
	v_mfma_f32_32x32x16_bf16 v[82:97], v[142:145], v[236:239], v[82:97]
	v_mfma_f32_32x32x16_bf16 v[50:65], v[172:175], v[236:239], v[50:65]
	s_barrier
	v_add3_u32 v187, v166, v161, 0
	v_add3_u32 v248, v166, v163, 0
	ds_read_b128 v[130:133], v187 offset:16384
	ds_read_b128 v[134:137], v248 offset:16384
	ds_read_b128 v[146:149], v187 offset:20480
	ds_read_b128 v[150:153], v248 offset:20480
	v_add3_u32 v187, v166, v164, 0
	v_add3_u32 v248, v166, v165, 0
	ds_read_b128 v[138:141], v187 offset:16384
	ds_read_b128 v[142:145], v248 offset:16384
	ds_read_b128 v[168:171], v187 offset:20480
	ds_read_b128 v[172:175], v248 offset:20480
	s_waitcnt vmcnt(4)
	s_barrier
	s_waitcnt lgkmcnt(0)
	v_mfma_f32_32x32x16_bf16 v[66:81], v[130:133], v[176:179], v[66:81]
	v_mfma_f32_32x32x16_bf16 v[34:49], v[146:149], v[176:179], v[34:49]
	v_mfma_f32_32x32x16_bf16 v[66:81], v[134:137], v[180:183], v[66:81]
	v_mfma_f32_32x32x16_bf16 v[34:49], v[150:153], v[180:183], v[34:49]
	v_mfma_f32_32x32x16_bf16 v[66:81], v[138:141], v[192:195], v[66:81]
	v_mfma_f32_32x32x16_bf16 v[34:49], v[168:171], v[192:195], v[34:49]
	v_mfma_f32_32x32x16_bf16 v[66:81], v[142:145], v[196:199], v[66:81]
	v_mfma_f32_32x32x16_bf16 v[34:49], v[172:175], v[196:199], v[34:49]
	v_mfma_f32_32x32x16_bf16 v[18:33], v[130:133], v[200:203], v[18:33]
	v_mfma_f32_32x32x16_bf16 v[2:17], v[146:149], v[200:203], v[2:17]
	v_mfma_f32_32x32x16_bf16 v[18:33], v[134:137], v[228:231], v[18:33]
	v_mfma_f32_32x32x16_bf16 v[2:17], v[150:153], v[228:231], v[2:17]
	v_mfma_f32_32x32x16_bf16 v[18:33], v[138:141], v[232:235], v[18:33]
	v_mfma_f32_32x32x16_bf16 v[2:17], v[168:171], v[232:235], v[2:17]
	v_mfma_f32_32x32x16_bf16 v[18:33], v[142:145], v[236:239], v[18:33]
	v_mfma_f32_32x32x16_bf16 v[2:17], v[172:175], v[236:239], v[2:17]
	s_barrier
	v_add3_u32 v187, v186, v161, s10
	v_add3_u32 v248, v186, v163, s10
	ds_read_b128 v[176:179], v187 offset:32768
	ds_read_b128 v[180:183], v248 offset:32768
	v_add3_u32 v187, v186, v164, s10
	v_add3_u32 v248, v186, v165, s10
	ds_read_b128 v[192:195], v187 offset:32768
	ds_read_b128 v[196:199], v248 offset:32768
	v_add3_u32 v187, v166, v161, s10
	v_add3_u32 v248, v166, v163, s10
	ds_read_b128 v[130:133], v187
	ds_read_b128 v[134:137], v248
	ds_read_b128 v[146:149], v187 offset:4096
	ds_read_b128 v[150:153], v248 offset:4096
	v_add3_u32 v187, v166, v164, s10
	v_add3_u32 v248, v166, v165, s10
	ds_read_b128 v[138:141], v187
	ds_read_b128 v[142:145], v248
	ds_read_b128 v[168:171], v187 offset:4096
	ds_read_b128 v[172:175], v248 offset:4096
	s_waitcnt vmcnt(2)
	s_barrier
	s_waitcnt lgkmcnt(0)
	v_mfma_f32_32x32x16_bf16 v[114:129], v[130:133], v[176:179], v[114:129]
	v_mfma_f32_32x32x16_bf16 v[98:113], v[146:149], v[176:179], v[98:113]
	v_mfma_f32_32x32x16_bf16 v[114:129], v[134:137], v[180:183], v[114:129]
	v_mfma_f32_32x32x16_bf16 v[98:113], v[150:153], v[180:183], v[98:113]
	v_mfma_f32_32x32x16_bf16 v[114:129], v[138:141], v[192:195], v[114:129]
	v_mfma_f32_32x32x16_bf16 v[98:113], v[168:171], v[192:195], v[98:113]
	v_mfma_f32_32x32x16_bf16 v[114:129], v[142:145], v[196:199], v[114:129]
	v_mfma_f32_32x32x16_bf16 v[98:113], v[172:175], v[196:199], v[98:113]
	s_barrier
	v_add3_u32 v187, v186, v161, s10
	v_add3_u32 v248, v186, v163, s10
	ds_read_b128 v[200:203], v187 offset:49152
	ds_read_b128 v[228:231], v248 offset:49152
	v_add3_u32 v187, v186, v164, s10
	v_add3_u32 v248, v186, v165, s10
	ds_read_b128 v[232:235], v187 offset:49152
	ds_read_b128 v[236:239], v248 offset:49152
	s_waitcnt vmcnt(0)
	s_barrier
	s_waitcnt lgkmcnt(0)
	v_mfma_f32_32x32x16_bf16 v[82:97], v[130:133], v[200:203], v[82:97]
	v_mfma_f32_32x32x16_bf16 v[50:65], v[146:149], v[200:203], v[50:65]
	v_mfma_f32_32x32x16_bf16 v[82:97], v[134:137], v[228:231], v[82:97]
	v_mfma_f32_32x32x16_bf16 v[50:65], v[150:153], v[228:231], v[50:65]
	v_mfma_f32_32x32x16_bf16 v[82:97], v[138:141], v[232:235], v[82:97]
	v_mfma_f32_32x32x16_bf16 v[50:65], v[168:171], v[232:235], v[50:65]
	v_mfma_f32_32x32x16_bf16 v[82:97], v[142:145], v[236:239], v[82:97]
	v_mfma_f32_32x32x16_bf16 v[50:65], v[172:175], v[236:239], v[50:65]
	s_barrier
	v_add3_u32 v187, v166, v161, s10
	v_add3_u32 v248, v166, v163, s10
	ds_read_b128 v[130:133], v187 offset:16384
	ds_read_b128 v[134:137], v248 offset:16384
	ds_read_b128 v[146:149], v187 offset:20480
	ds_read_b128 v[150:153], v248 offset:20480
	v_add3_u32 v187, v166, v164, s10
	v_add3_u32 v248, v166, v165, s10
	ds_read_b128 v[138:141], v187 offset:16384
	ds_read_b128 v[142:145], v248 offset:16384
	ds_read_b128 v[168:171], v187 offset:20480
	ds_read_b128 v[172:175], v248 offset:20480
	s_barrier
	s_waitcnt lgkmcnt(0)
	v_mfma_f32_32x32x16_bf16 v[66:81], v[130:133], v[176:179], v[66:81]
	v_mfma_f32_32x32x16_bf16 v[34:49], v[146:149], v[176:179], v[34:49]
	v_mfma_f32_32x32x16_bf16 v[66:81], v[134:137], v[180:183], v[66:81]
	v_mfma_f32_32x32x16_bf16 v[34:49], v[150:153], v[180:183], v[34:49]
	v_mfma_f32_32x32x16_bf16 v[66:81], v[138:141], v[192:195], v[66:81]
	v_mfma_f32_32x32x16_bf16 v[34:49], v[168:171], v[192:195], v[34:49]
	v_mfma_f32_32x32x16_bf16 v[66:81], v[142:145], v[196:199], v[66:81]
	v_mfma_f32_32x32x16_bf16 v[34:49], v[172:175], v[196:199], v[34:49]
	v_mfma_f32_32x32x16_bf16 v[18:33], v[130:133], v[200:203], v[18:33]
	v_mfma_f32_32x32x16_bf16 v[2:17], v[146:149], v[200:203], v[2:17]
	v_mfma_f32_32x32x16_bf16 v[18:33], v[134:137], v[228:231], v[18:33]
	v_mfma_f32_32x32x16_bf16 v[2:17], v[150:153], v[228:231], v[2:17]
	v_mfma_f32_32x32x16_bf16 v[18:33], v[138:141], v[232:235], v[18:33]
	v_mfma_f32_32x32x16_bf16 v[2:17], v[168:171], v[232:235], v[2:17]
	v_mfma_f32_32x32x16_bf16 v[18:33], v[142:145], v[236:239], v[18:33]
	v_mfma_f32_32x32x16_bf16 v[2:17], v[172:175], v[236:239], v[2:17]
	s_barrier
	s_cmp_eq_u32 s101, 0
	s_cbranch_scc0 .Lg8_ib_p1
	s_barrier

; DI u16 to_bf16(float a) { return (u16)(pk_bf16(a, 0.f) & 0xffffu); }
; template <int EPI>
; DI void phase_gemm(const Params& p, const GemmArgs& ga, char* lds) {
;     ...
;       seq_of_token(mt * 256, bb, tokbase, S);
;       pos0 = mt * 256 - tokbase;
;     }
;     ...
;       } else if (n0w >= 2176) {
; #pragma unroll
;         for (int ni = 0; ni < 2; ++ni)
; #pragma unroll
;           for (int i = 0; i < 16; ++i) {
;             const int vrow = 512 + (n0w - 2176) + ni * 32 + 8 * (i >> 2) + 4 * h + (i & 3);
;             u16* vb = VT + (size_t)640 * tokbase + (size_t)vrow * S + pos0 + wm * 128 + r;
; #pragma unroll
;             for (int mi = 0; mi < 4; ++mi) vb[mi * 32] = to_bf16(acc[mi][ni][i]);
;           }
;       } else {
;         const bool nrm = (n0w >= 1536);
;         int dcol;
;         const float* gq = p.gqa_qk_g;
;         float osc = 1.f;
;         if (n0w < 1024) { dcol = n0w; if (n0w < 512) osc = QK_SCALE_LOG2; }
;         else if (n0w < 2048) { dcol = 1024 + (n0w - 1536); osc = QK_SCALE_LOG2; }
;         else { dcol = 1536 + (n0w - 2048); gq += 64; }
.LBB0_327:
.LBB0_328:
	s_cmpk_lt_i32 s28, 0x80
	s_cselect_b64 s[10:11], -1, 0
	s_and_b64 s[6:7], s[10:11], exec
	s_movk_i32 s6, 0xc000
	s_cselect_b32 s6, s6, 0x7ffff800
	s_and_b32 s20, s6, s12
	s_sub_i32 s14, s12, s20
	v_or_b32_e32 v192, s16, v185
	s_mov_b64 s[6:7], -1
	s_and_b64 vcc, exec, s[18:19]
	s_cbranch_vccz .LBB0_386
	s_movk_i32 s6, 0x880
	v_cmp_gt_i32_e32 vcc, s6, v192
	s_and_saveexec_b64 s[6:7], vcc
	s_xor_b64 s[18:19], exec, s[6:7]
	s_cbranch_execz .LBB0_383
	v_readlane_b32 s36, v254, 21
	s_movk_i32 s6, 0x3ff
	v_readlane_b32 s42, v254, 27
	v_readlane_b32 s43, v254, 28
	v_cmp_lt_i32_e32 vcc, s6, v192
	v_readlane_b32 s37, v254, 22
	v_mov_b64_e32 v[130:131], s[42:43]
	v_readlane_b32 s38, v254, 23
	v_readlane_b32 s39, v254, 24
	v_readlane_b32 s40, v254, 25
	v_readlane_b32 s41, v254, 26
	v_readlane_b32 s44, v254, 29
	v_readlane_b32 s45, v254, 30
	v_readlane_b32 s46, v254, 31
	v_readlane_b32 s47, v254, 32
	v_readlane_b32 s48, v254, 33
	v_readlane_b32 s49, v254, 34
	v_readlane_b32 s50, v254, 35
	v_readlane_b32 s51, v254, 36
	s_and_saveexec_b64 s[6:7], vcc
	s_xor_b64 s[6:7], exec, s[6:7]
	s_cbranch_execz .LBB0_332
	s_cmpk_lt_u32 s16, 0x800
	s_cselect_b64 vcc, -1, 0
	s_and_b64 s[8:9], vcc, exec
	v_readlane_b32 s36, v254, 21
	s_cselect_b32 s8, 0, 0x100
	v_readlane_b32 s42, v254, 27
	v_readlane_b32 s43, v254, 28
	s_add_u32 s8, s42, s8
	s_addc_u32 s9, s43, 0
	v_add_u32_e32 v164, 0xfffffe00, v192
	v_cndmask_b32_e32 v146, 1.0, v219, vcc
	v_readlane_b32 s37, v254, 22
	v_readlane_b32 s38, v254, 23
	v_readlane_b32 s39, v254, 24
	v_readlane_b32 s40, v254, 25
	v_readlane_b32 s41, v254, 26
	v_readlane_b32 s44, v254, 29
	v_readlane_b32 s45, v254, 30
	v_readlane_b32 s46, v254, 31
	v_readlane_b32 s47, v254, 32
	v_readlane_b32 s48, v254, 33
	v_readlane_b32 s49, v254, 34
	v_readlane_b32 s50, v254, 35
	v_readlane_b32 s51, v254, 36
	v_mov_b64_e32 v[130:131], s[8:9]
